# all s_setprio flips removed from the 13 GEMM K-loops (on top of MoBA gating-LDS, own-block shared staging, packed-loop SGPR-base addressing)
# speedup vs baseline: 1.0088x; 1.0088x over previous
.LBB0_161:
	ds_read_b128 v[160:163], v155
	ds_read_b128 v[164:167], v155 offset:1024
	ds_read_b128 v[168:171], v155 offset:2048
	ds_read_b128 v[172:175], v155 offset:3072
	ds_read_b128 v[176:179], v156
	ds_read_b128 v[180:183], v156 offset:1024
	ds_read_b128 v[184:187], v156 offset:2048
	ds_read_b128 v[188:191], v156 offset:3072
	s_add_u32 s24, s22, 0xfffc0080
	s_addc_u32 s25, s23, -1
	s_cmp_eq_u32 s66, 12
	s_cselect_b32 s27, s13, s25
	s_cselect_b32 s26, s50, s24
	s_cselect_b32 s25, s11, s65
	s_cselect_b32 s24, s51, s64
	v_lshl_add_u64 v[146:147], s[22:23], 0, v[138:139]
	s_add_i32 m0, s19, 0xc000
	ds_read_b128 v[192:195], v157
	ds_read_b128 v[198:201], v157 offset:1024
	ds_read_b128 v[202:205], v157 offset:2048
	ds_read_b128 v[206:209], v157 offset:3072
	ds_read_b128 v[210:213], v157 offset:4096
	ds_read_b128 v[214:217], v157 offset:5120
	ds_read_b128 v[218:221], v157 offset:6144
	ds_read_b128 v[226:229], v157 offset:7168
	global_load_lds_dwordx4 v[146:147], off
	v_lshl_add_u64 v[146:147], s[22:23], 0, v[140:141]
	s_add_i32 m0, s19, 0xe000
	s_nop 0
	global_load_lds_dwordx4 v[146:147], off
	s_waitcnt vmcnt(8)
	s_waitcnt lgkmcnt(0)
	s_barrier
	s_waitcnt lgkmcnt(0)
	v_mfma_f32_16x16x32_bf16 v[124:127], v[160:163], v[192:195], v[124:127]
	v_mfma_f32_16x16x32_bf16 v[120:123], v[168:171], v[192:195], v[120:123]
	v_mfma_f32_16x16x32_bf16 v[108:111], v[160:163], v[202:205], v[108:111]
	v_mfma_f32_16x16x32_bf16 v[104:107], v[168:171], v[202:205], v[104:107]
	v_mfma_f32_16x16x32_bf16 v[92:95], v[160:163], v[210:213], v[92:95]
	v_mfma_f32_16x16x32_bf16 v[88:91], v[168:171], v[210:213], v[88:91]
	v_mfma_f32_16x16x32_bf16 v[76:79], v[160:163], v[218:221], v[76:79]
	v_mfma_f32_16x16x32_bf16 v[72:75], v[168:171], v[218:221], v[72:75]
	v_mfma_f32_16x16x32_bf16 v[124:127], v[164:167], v[198:201], v[124:127]
	v_mfma_f32_16x16x32_bf16 v[120:123], v[172:175], v[198:201], v[120:123]
	v_mfma_f32_16x16x32_bf16 v[108:111], v[164:167], v[206:209], v[108:111]
	v_mfma_f32_16x16x32_bf16 v[104:107], v[172:175], v[206:209], v[104:107]
	v_mfma_f32_16x16x32_bf16 v[92:95], v[164:167], v[214:217], v[92:95]
	v_mfma_f32_16x16x32_bf16 v[88:91], v[172:175], v[214:217], v[88:91]
	v_mfma_f32_16x16x32_bf16 v[76:79], v[164:167], v[226:229], v[76:79]
	v_mfma_f32_16x16x32_bf16 v[72:75], v[172:175], v[226:229], v[72:75]
	v_mfma_f32_16x16x32_bf16 v[116:119], v[176:179], v[192:195], v[116:119]
	v_mfma_f32_16x16x32_bf16 v[112:115], v[184:187], v[192:195], v[112:115]
	v_mfma_f32_16x16x32_bf16 v[100:103], v[176:179], v[202:205], v[100:103]
	v_mfma_f32_16x16x32_bf16 v[96:99], v[184:187], v[202:205], v[96:99]
	v_mfma_f32_16x16x32_bf16 v[84:87], v[176:179], v[210:213], v[84:87]
	v_mfma_f32_16x16x32_bf16 v[80:83], v[184:187], v[210:213], v[80:83]
	v_mfma_f32_16x16x32_bf16 v[68:71], v[176:179], v[218:221], v[68:71]
	v_mfma_f32_16x16x32_bf16 v[64:67], v[184:187], v[218:221], v[64:67]
	v_mfma_f32_16x16x32_bf16 v[116:119], v[180:183], v[198:201], v[116:119]
	v_mfma_f32_16x16x32_bf16 v[112:115], v[188:191], v[198:201], v[112:115]
	v_mfma_f32_16x16x32_bf16 v[100:103], v[180:183], v[206:209], v[100:103]
	v_mfma_f32_16x16x32_bf16 v[96:99], v[188:191], v[206:209], v[96:99]
	v_mfma_f32_16x16x32_bf16 v[84:87], v[180:183], v[214:217], v[84:87]
	v_mfma_f32_16x16x32_bf16 v[80:83], v[188:191], v[214:217], v[80:83]
	v_mfma_f32_16x16x32_bf16 v[68:71], v[180:183], v[226:229], v[68:71]
	v_mfma_f32_16x16x32_bf16 v[64:67], v[188:191], v[226:229], v[64:67]
	s_barrier
	s_add_i32 s62, s46, s28
	v_lshl_add_u64 v[146:147], s[24:25], 0, v[130:131]
	s_mov_b32 m0, s62
	ds_read_b128 v[192:195], v157 offset:16384
	ds_read_b128 v[198:201], v157 offset:17408
	ds_read_b128 v[202:205], v157 offset:18432
	ds_read_b128 v[206:209], v157 offset:19456
	ds_read_b128 v[210:213], v157 offset:20480
	ds_read_b128 v[214:217], v157 offset:21504
	ds_read_b128 v[218:221], v157 offset:22528
	ds_read_b128 v[226:229], v157 offset:23552
	global_load_lds_dwordx4 v[146:147], off
	s_add_i32 m0, s62, 0x2000
	s_add_u32 s70, s24, 0x40000
	v_lshl_add_u64 v[222:223], s[24:25], 0, v[134:135]
	s_addc_u32 s71, s25, 0
	s_add_i32 s62, s47, s28
	global_load_lds_dwordx4 v[222:223], off
	v_lshl_add_u64 v[230:231], s[70:71], 0, v[130:131]
	s_mov_b32 m0, s62
	v_lshl_add_u64 v[232:233], s[26:27], 0, v[132:133]
	global_load_lds_dwordx4 v[230:231], off
	v_lshl_add_u64 v[230:231], s[70:71], 0, v[134:135]
	s_add_i32 m0, s62, 0x2000
	s_nop 0
	global_load_lds_dwordx4 v[230:231], off
	v_lshl_add_u64 v[230:231], s[26:27], 0, v[128:129]
	s_mov_b32 m0, s19
	s_nop 0
	global_load_lds_dwordx4 v[230:231], off
	s_mov_b32 m0, s39
	s_nop 0
	global_load_lds_dwordx4 v[232:233], off
	s_waitcnt vmcnt(8)
	s_waitcnt lgkmcnt(0)
	s_barrier
	s_waitcnt lgkmcnt(0)
	v_mfma_f32_16x16x32_bf16 v[60:63], v[160:163], v[192:195], v[60:63]
	v_mfma_f32_16x16x32_bf16 v[56:59], v[168:171], v[192:195], v[56:59]
	v_mfma_f32_16x16x32_bf16 v[44:47], v[160:163], v[202:205], v[44:47]
	v_mfma_f32_16x16x32_bf16 v[40:43], v[168:171], v[202:205], v[40:43]
	v_mfma_f32_16x16x32_bf16 v[28:31], v[160:163], v[210:213], v[28:31]
	v_mfma_f32_16x16x32_bf16 v[24:27], v[168:171], v[210:213], v[24:27]
	v_mfma_f32_16x16x32_bf16 v[12:15], v[160:163], v[218:221], v[12:15]
	v_mfma_f32_16x16x32_bf16 v[8:11], v[168:171], v[218:221], v[8:11]
	v_mfma_f32_16x16x32_bf16 v[60:63], v[164:167], v[198:201], v[60:63]
	v_mfma_f32_16x16x32_bf16 v[56:59], v[172:175], v[198:201], v[56:59]
	v_mfma_f32_16x16x32_bf16 v[44:47], v[164:167], v[206:209], v[44:47]
	v_mfma_f32_16x16x32_bf16 v[40:43], v[172:175], v[206:209], v[40:43]
	v_mfma_f32_16x16x32_bf16 v[28:31], v[164:167], v[214:217], v[28:31]
	v_mfma_f32_16x16x32_bf16 v[24:27], v[172:175], v[214:217], v[24:27]
	v_mfma_f32_16x16x32_bf16 v[12:15], v[164:167], v[226:229], v[12:15]
	v_mfma_f32_16x16x32_bf16 v[8:11], v[172:175], v[226:229], v[8:11]
	v_mfma_f32_16x16x32_bf16 v[52:55], v[176:179], v[192:195], v[52:55]
	v_mfma_f32_16x16x32_bf16 v[48:51], v[184:187], v[192:195], v[48:51]
	v_mfma_f32_16x16x32_bf16 v[36:39], v[176:179], v[202:205], v[36:39]
	v_mfma_f32_16x16x32_bf16 v[32:35], v[184:187], v[202:205], v[32:35]
	v_mfma_f32_16x16x32_bf16 v[20:23], v[176:179], v[210:213], v[20:23]
	v_mfma_f32_16x16x32_bf16 v[16:19], v[184:187], v[210:213], v[16:19]
	v_mfma_f32_16x16x32_bf16 v[4:7], v[176:179], v[218:221], v[4:7]
	v_mfma_f32_16x16x32_bf16 v[0:3], v[184:187], v[218:221], v[0:3]
	v_mfma_f32_16x16x32_bf16 v[52:55], v[180:183], v[198:201], v[52:55]
	v_mfma_f32_16x16x32_bf16 v[48:51], v[188:191], v[198:201], v[48:51]
	v_mfma_f32_16x16x32_bf16 v[36:39], v[180:183], v[206:209], v[36:39]
	v_mfma_f32_16x16x32_bf16 v[32:35], v[188:191], v[206:209], v[32:35]
	v_mfma_f32_16x16x32_bf16 v[20:23], v[180:183], v[214:217], v[20:23]
	v_mfma_f32_16x16x32_bf16 v[16:19], v[188:191], v[214:217], v[16:19]
	v_mfma_f32_16x16x32_bf16 v[4:7], v[180:183], v[226:229], v[4:7]
	v_mfma_f32_16x16x32_bf16 v[0:3], v[188:191], v[226:229], v[0:3]
	s_barrier
	s_add_i32 s62, 0, 0x18000
	v_add_u32_e32 v148, s62, v150
	s_add_i32 s63, 0, 0x1c000
	ds_read_b128 v[160:163], v148
	ds_read_b128 v[164:167], v148 offset:1024
	ds_read_b128 v[168:171], v148 offset:2048
	ds_read_b128 v[172:175], v148 offset:3072
	v_add_u32_e32 v148, s63, v150
	ds_read_b128 v[176:179], v148
	ds_read_b128 v[180:183], v148 offset:1024
	ds_read_b128 v[184:187], v148 offset:2048
	ds_read_b128 v[188:191], v148 offset:3072
	s_add_u32 s26, s26, 0x40000
	s_addc_u32 s27, s27, 0
	s_mov_b32 m0, s40
	v_lshl_add_u64 v[234:235], s[26:27], 0, v[128:129]
	ds_read_b128 v[192:195], v157 offset:32768
	ds_read_b128 v[198:201], v157 offset:33792
	ds_read_b128 v[202:205], v157 offset:34816
	ds_read_b128 v[206:209], v157 offset:35840
	ds_read_b128 v[210:213], v157 offset:36864
	ds_read_b128 v[214:217], v157 offset:37888
	ds_read_b128 v[218:221], v157 offset:38912
	ds_read_b128 v[226:229], v157 offset:39936
	global_load_lds_dwordx4 v[234:235], off
	v_lshl_add_u64 v[234:235], s[26:27], 0, v[132:133]
	s_mov_b32 m0, s41
	s_nop 0
	global_load_lds_dwordx4 v[234:235], off
	s_waitcnt vmcnt(8)
	s_waitcnt lgkmcnt(0)
	s_barrier
	s_waitcnt lgkmcnt(0)
	v_mfma_f32_16x16x32_bf16 v[124:127], v[160:163], v[192:195], v[124:127]
	v_mfma_f32_16x16x32_bf16 v[120:123], v[168:171], v[192:195], v[120:123]
	v_mfma_f32_16x16x32_bf16 v[108:111], v[160:163], v[202:205], v[108:111]
	v_mfma_f32_16x16x32_bf16 v[104:107], v[168:171], v[202:205], v[104:107]
	v_mfma_f32_16x16x32_bf16 v[92:95], v[160:163], v[210:213], v[92:95]
	v_mfma_f32_16x16x32_bf16 v[88:91], v[168:171], v[210:213], v[88:91]
	v_mfma_f32_16x16x32_bf16 v[76:79], v[160:163], v[218:221], v[76:79]
	v_mfma_f32_16x16x32_bf16 v[72:75], v[168:171], v[218:221], v[72:75]
	v_mfma_f32_16x16x32_bf16 v[124:127], v[164:167], v[198:201], v[124:127]
	v_mfma_f32_16x16x32_bf16 v[120:123], v[172:175], v[198:201], v[120:123]
	v_mfma_f32_16x16x32_bf16 v[108:111], v[164:167], v[206:209], v[108:111]
	v_mfma_f32_16x16x32_bf16 v[104:107], v[172:175], v[206:209], v[104:107]
	v_mfma_f32_16x16x32_bf16 v[92:95], v[164:167], v[214:217], v[92:95]
	v_mfma_f32_16x16x32_bf16 v[88:91], v[172:175], v[214:217], v[88:91]
	v_mfma_f32_16x16x32_bf16 v[76:79], v[164:167], v[226:229], v[76:79]
	v_mfma_f32_16x16x32_bf16 v[72:75], v[172:175], v[226:229], v[72:75]
	v_mfma_f32_16x16x32_bf16 v[116:119], v[176:179], v[192:195], v[116:119]
	v_mfma_f32_16x16x32_bf16 v[112:115], v[184:187], v[192:195], v[112:115]
	v_mfma_f32_16x16x32_bf16 v[100:103], v[176:179], v[202:205], v[100:103]
	v_mfma_f32_16x16x32_bf16 v[96:99], v[184:187], v[202:205], v[96:99]
	v_mfma_f32_16x16x32_bf16 v[84:87], v[176:179], v[210:213], v[84:87]
	v_mfma_f32_16x16x32_bf16 v[80:83], v[184:187], v[210:213], v[80:83]
	v_mfma_f32_16x16x32_bf16 v[68:71], v[176:179], v[218:221], v[68:71]
	v_mfma_f32_16x16x32_bf16 v[64:67], v[184:187], v[218:221], v[64:67]
	v_mfma_f32_16x16x32_bf16 v[116:119], v[180:183], v[198:201], v[116:119]
	v_mfma_f32_16x16x32_bf16 v[112:115], v[188:191], v[198:201], v[112:115]
	v_mfma_f32_16x16x32_bf16 v[100:103], v[180:183], v[206:209], v[100:103]
	v_mfma_f32_16x16x32_bf16 v[96:99], v[188:191], v[206:209], v[96:99]
	v_mfma_f32_16x16x32_bf16 v[84:87], v[180:183], v[214:217], v[84:87]
	v_mfma_f32_16x16x32_bf16 v[80:83], v[188:191], v[214:217], v[80:83]
	v_mfma_f32_16x16x32_bf16 v[68:71], v[180:183], v[226:229], v[68:71]
	v_mfma_f32_16x16x32_bf16 v[64:67], v[188:191], v[226:229], v[64:67]
	s_barrier
	s_add_i32 s26, s62, s28
	v_lshl_add_u64 v[146:147], v[146:147], 0, s[6:7]
	s_mov_b32 m0, s26
	ds_read_b128 v[192:195], v157 offset:49152
	ds_read_b128 v[198:201], v157 offset:50176
	ds_read_b128 v[202:205], v157 offset:51200
	ds_read_b128 v[206:209], v157 offset:52224
	ds_read_b128 v[210:213], v157 offset:53248
	ds_read_b128 v[214:217], v157 offset:54272
	ds_read_b128 v[218:221], v157 offset:55296
	ds_read_b128 v[226:229], v157 offset:56320
	global_load_lds_dwordx4 v[146:147], off
	s_add_i32 m0, s26, 0x2000
	s_add_u32 s24, s24, 0x40080
	v_lshl_add_u64 v[146:147], v[222:223], 0, s[6:7]
	s_addc_u32 s25, s25, 0
	s_add_i32 s26, s63, s28
	global_load_lds_dwordx4 v[146:147], off
	v_lshl_add_u64 v[146:147], s[24:25], 0, v[130:131]
	s_mov_b32 m0, s26
	s_nop 0
	global_load_lds_dwordx4 v[146:147], off
	v_lshl_add_u64 v[146:147], s[24:25], 0, v[134:135]
	s_add_i32 m0, s26, 0x2000
	s_nop 0
	global_load_lds_dwordx4 v[146:147], off
	v_lshl_add_u64 v[146:147], v[230:231], 0, s[6:7]
	s_mov_b32 m0, s44
	s_nop 0
	global_load_lds_dwordx4 v[146:147], off
	v_lshl_add_u64 v[146:147], v[232:233], 0, s[6:7]
	s_mov_b32 m0, s45
	s_nop 0
	global_load_lds_dwordx4 v[146:147], off
	s_waitcnt vmcnt(8)
	s_waitcnt lgkmcnt(0)
	s_barrier
	s_waitcnt lgkmcnt(0)
	v_mfma_f32_16x16x32_bf16 v[60:63], v[160:163], v[192:195], v[60:63]
	v_mfma_f32_16x16x32_bf16 v[56:59], v[168:171], v[192:195], v[56:59]
	v_mfma_f32_16x16x32_bf16 v[44:47], v[160:163], v[202:205], v[44:47]
	v_mfma_f32_16x16x32_bf16 v[40:43], v[168:171], v[202:205], v[40:43]
	v_mfma_f32_16x16x32_bf16 v[28:31], v[160:163], v[210:213], v[28:31]
	v_mfma_f32_16x16x32_bf16 v[24:27], v[168:171], v[210:213], v[24:27]
	v_mfma_f32_16x16x32_bf16 v[12:15], v[160:163], v[218:221], v[12:15]
	v_mfma_f32_16x16x32_bf16 v[8:11], v[168:171], v[218:221], v[8:11]
	v_mfma_f32_16x16x32_bf16 v[60:63], v[164:167], v[198:201], v[60:63]
	v_mfma_f32_16x16x32_bf16 v[56:59], v[172:175], v[198:201], v[56:59]
	v_mfma_f32_16x16x32_bf16 v[44:47], v[164:167], v[206:209], v[44:47]
	v_mfma_f32_16x16x32_bf16 v[40:43], v[172:175], v[206:209], v[40:43]
	v_mfma_f32_16x16x32_bf16 v[28:31], v[164:167], v[214:217], v[28:31]
	v_mfma_f32_16x16x32_bf16 v[24:27], v[172:175], v[214:217], v[24:27]
	v_mfma_f32_16x16x32_bf16 v[12:15], v[164:167], v[226:229], v[12:15]
	v_mfma_f32_16x16x32_bf16 v[8:11], v[172:175], v[226:229], v[8:11]
	v_mfma_f32_16x16x32_bf16 v[52:55], v[176:179], v[192:195], v[52:55]
	v_mfma_f32_16x16x32_bf16 v[48:51], v[184:187], v[192:195], v[48:51]
	v_mfma_f32_16x16x32_bf16 v[36:39], v[176:179], v[202:205], v[36:39]
	v_mfma_f32_16x16x32_bf16 v[32:35], v[184:187], v[202:205], v[32:35]
	v_mfma_f32_16x16x32_bf16 v[20:23], v[176:179], v[210:213], v[20:23]
	v_mfma_f32_16x16x32_bf16 v[16:19], v[184:187], v[210:213], v[16:19]
	v_mfma_f32_16x16x32_bf16 v[4:7], v[176:179], v[218:221], v[4:7]
	v_mfma_f32_16x16x32_bf16 v[0:3], v[184:187], v[218:221], v[0:3]
	v_mfma_f32_16x16x32_bf16 v[52:55], v[180:183], v[198:201], v[52:55]
	v_mfma_f32_16x16x32_bf16 v[48:51], v[188:191], v[198:201], v[48:51]
	v_mfma_f32_16x16x32_bf16 v[36:39], v[180:183], v[206:209], v[36:39]
	v_mfma_f32_16x16x32_bf16 v[32:35], v[188:191], v[206:209], v[32:35]
	v_mfma_f32_16x16x32_bf16 v[20:23], v[180:183], v[214:217], v[20:23]
	v_mfma_f32_16x16x32_bf16 v[16:19], v[188:191], v[214:217], v[16:19]
	v_mfma_f32_16x16x32_bf16 v[4:7], v[180:183], v[226:229], v[4:7]
	v_mfma_f32_16x16x32_bf16 v[0:3], v[188:191], v[226:229], v[0:3]
	s_barrier
	s_add_i32 s66, s66, 2
	s_add_u32 s22, s22, 0x100
	s_addc_u32 s23, s23, 0
	s_add_u32 s64, s64, 0x100
	s_addc_u32 s65, s65, 0
	s_cmp_gt_u32 s66, 13
	s_cbranch_scc0 .LBB0_161
	s_and_b64 vcc, exec, s[8:9]
	s_cbranch_vccz .LBB0_164
	s_barrier

.LBB0_238:
	ds_read_b128 v[128:131], v189
	ds_read_b128 v[132:135], v189 offset:1024
	ds_read_b128 v[136:139], v189 offset:2048
	ds_read_b128 v[140:143], v189 offset:3072
	ds_read_b128 v[144:147], v190
	ds_read_b128 v[148:151], v190 offset:1024
	ds_read_b128 v[168:171], v190 offset:2048
	ds_read_b128 v[172:175], v190 offset:3072
	s_add_u32 s22, s18, 0xfff50080
	s_addc_u32 s23, s19, -1
	s_cmp_eq_u32 s66, 40
	s_cselect_b32 s25, s5, s23
	s_cselect_b32 s24, s4, s22
	s_cselect_b32 s23, s17, s65
	s_cselect_b32 s22, s16, s64
	v_lshl_add_u64 v[184:185], s[18:19], 0, v[160:161]
	s_add_i32 m0, s29, 0xc000
	ds_read_b128 v[176:179], v191
	ds_read_b128 v[180:183], v191 offset:1024
	ds_read_b128 v[198:201], v191 offset:2048
	ds_read_b128 v[202:205], v191 offset:3072
	ds_read_b128 v[206:209], v191 offset:4096
	ds_read_b128 v[210:213], v191 offset:5120
	ds_read_b128 v[214:217], v191 offset:6144
	ds_read_b128 v[218:221], v191 offset:7168
	global_load_lds_dwordx4 v[184:185], off
	v_lshl_add_u64 v[184:185], s[18:19], 0, v[162:163]
	s_add_i32 m0, s29, 0xe000
	s_nop 0
	global_load_lds_dwordx4 v[184:185], off
	s_waitcnt vmcnt(8)
	s_waitcnt lgkmcnt(0)
	s_barrier
	s_waitcnt lgkmcnt(0)
	v_mfma_f32_16x16x32_bf16 v[124:127], v[128:131], v[176:179], v[124:127]
	v_mfma_f32_16x16x32_bf16 v[120:123], v[136:139], v[176:179], v[120:123]
	v_mfma_f32_16x16x32_bf16 v[108:111], v[128:131], v[198:201], v[108:111]
	v_mfma_f32_16x16x32_bf16 v[104:107], v[136:139], v[198:201], v[104:107]
	v_mfma_f32_16x16x32_bf16 v[92:95], v[128:131], v[206:209], v[92:95]
	v_mfma_f32_16x16x32_bf16 v[88:91], v[136:139], v[206:209], v[88:91]
	v_mfma_f32_16x16x32_bf16 v[76:79], v[128:131], v[214:217], v[76:79]
	v_mfma_f32_16x16x32_bf16 v[72:75], v[136:139], v[214:217], v[72:75]
	v_mfma_f32_16x16x32_bf16 v[124:127], v[132:135], v[180:183], v[124:127]
	v_mfma_f32_16x16x32_bf16 v[120:123], v[140:143], v[180:183], v[120:123]
	v_mfma_f32_16x16x32_bf16 v[108:111], v[132:135], v[202:205], v[108:111]
	v_mfma_f32_16x16x32_bf16 v[104:107], v[140:143], v[202:205], v[104:107]
	v_mfma_f32_16x16x32_bf16 v[92:95], v[132:135], v[210:213], v[92:95]
	v_mfma_f32_16x16x32_bf16 v[88:91], v[140:143], v[210:213], v[88:91]
	v_mfma_f32_16x16x32_bf16 v[76:79], v[132:135], v[218:221], v[76:79]
	v_mfma_f32_16x16x32_bf16 v[72:75], v[140:143], v[218:221], v[72:75]
	v_mfma_f32_16x16x32_bf16 v[116:119], v[144:147], v[176:179], v[116:119]
	v_mfma_f32_16x16x32_bf16 v[112:115], v[168:171], v[176:179], v[112:115]
	v_mfma_f32_16x16x32_bf16 v[100:103], v[144:147], v[198:201], v[100:103]
	v_mfma_f32_16x16x32_bf16 v[96:99], v[168:171], v[198:201], v[96:99]
	v_mfma_f32_16x16x32_bf16 v[84:87], v[144:147], v[206:209], v[84:87]
	v_mfma_f32_16x16x32_bf16 v[80:83], v[168:171], v[206:209], v[80:83]
	v_mfma_f32_16x16x32_bf16 v[68:71], v[144:147], v[214:217], v[68:71]
	v_mfma_f32_16x16x32_bf16 v[64:67], v[168:171], v[214:217], v[64:67]
	v_mfma_f32_16x16x32_bf16 v[116:119], v[148:151], v[180:183], v[116:119]
	v_mfma_f32_16x16x32_bf16 v[112:115], v[172:175], v[180:183], v[112:115]
	v_mfma_f32_16x16x32_bf16 v[100:103], v[148:151], v[202:205], v[100:103]
	v_mfma_f32_16x16x32_bf16 v[96:99], v[172:175], v[202:205], v[96:99]
	v_mfma_f32_16x16x32_bf16 v[84:87], v[148:151], v[210:213], v[84:87]
	v_mfma_f32_16x16x32_bf16 v[80:83], v[172:175], v[210:213], v[80:83]
	v_mfma_f32_16x16x32_bf16 v[68:71], v[148:151], v[218:221], v[68:71]
	v_mfma_f32_16x16x32_bf16 v[64:67], v[172:175], v[218:221], v[64:67]
	s_barrier
	s_add_i32 s62, s46, s28
	v_lshl_add_u64 v[184:185], s[22:23], 0, v[154:155]
	s_mov_b32 m0, s62
	ds_read_b128 v[176:179], v191 offset:16384
	ds_read_b128 v[180:183], v191 offset:17408
	ds_read_b128 v[198:201], v191 offset:18432
	ds_read_b128 v[202:205], v191 offset:19456
	ds_read_b128 v[206:209], v191 offset:20480
	ds_read_b128 v[210:213], v191 offset:21504
	ds_read_b128 v[214:217], v191 offset:22528
	ds_read_b128 v[218:221], v191 offset:23552
	global_load_lds_dwordx4 v[184:185], off
	s_add_i32 m0, s62, 0x2000
	s_add_u32 s68, s22, 0xb0000
	v_lshl_add_u64 v[194:195], s[22:23], 0, v[158:159]
	s_addc_u32 s69, s23, 0
	s_add_i32 s62, s47, s28
	global_load_lds_dwordx4 v[194:195], off
	v_lshl_add_u64 v[222:223], s[68:69], 0, v[154:155]
	s_mov_b32 m0, s62
	v_lshl_add_u64 v[226:227], s[24:25], 0, v[156:157]
	global_load_lds_dwordx4 v[222:223], off
	v_lshl_add_u64 v[222:223], s[68:69], 0, v[158:159]
	s_add_i32 m0, s62, 0x2000
	s_nop 0
	global_load_lds_dwordx4 v[222:223], off
	v_lshl_add_u64 v[222:223], s[24:25], 0, v[152:153]
	s_mov_b32 m0, s29
	s_nop 0
	global_load_lds_dwordx4 v[222:223], off
	s_mov_b32 m0, s38
	s_nop 0
	global_load_lds_dwordx4 v[226:227], off
	s_waitcnt vmcnt(8)
	s_waitcnt lgkmcnt(0)
	s_barrier
	s_waitcnt lgkmcnt(0)
	v_mfma_f32_16x16x32_bf16 v[60:63], v[128:131], v[176:179], v[60:63]
	v_mfma_f32_16x16x32_bf16 v[56:59], v[136:139], v[176:179], v[56:59]
	v_mfma_f32_16x16x32_bf16 v[44:47], v[128:131], v[198:201], v[44:47]
	v_mfma_f32_16x16x32_bf16 v[40:43], v[136:139], v[198:201], v[40:43]
	v_mfma_f32_16x16x32_bf16 v[28:31], v[128:131], v[206:209], v[28:31]
	v_mfma_f32_16x16x32_bf16 v[24:27], v[136:139], v[206:209], v[24:27]
	v_mfma_f32_16x16x32_bf16 v[12:15], v[128:131], v[214:217], v[12:15]
	v_mfma_f32_16x16x32_bf16 v[8:11], v[136:139], v[214:217], v[8:11]
	v_mfma_f32_16x16x32_bf16 v[60:63], v[132:135], v[180:183], v[60:63]
	v_mfma_f32_16x16x32_bf16 v[56:59], v[140:143], v[180:183], v[56:59]
	v_mfma_f32_16x16x32_bf16 v[44:47], v[132:135], v[202:205], v[44:47]
	v_mfma_f32_16x16x32_bf16 v[40:43], v[140:143], v[202:205], v[40:43]
	v_mfma_f32_16x16x32_bf16 v[28:31], v[132:135], v[210:213], v[28:31]
	v_mfma_f32_16x16x32_bf16 v[24:27], v[140:143], v[210:213], v[24:27]
	v_mfma_f32_16x16x32_bf16 v[12:15], v[132:135], v[218:221], v[12:15]
	v_mfma_f32_16x16x32_bf16 v[8:11], v[140:143], v[218:221], v[8:11]
	v_mfma_f32_16x16x32_bf16 v[52:55], v[144:147], v[176:179], v[52:55]
	v_mfma_f32_16x16x32_bf16 v[48:51], v[168:171], v[176:179], v[48:51]
	v_mfma_f32_16x16x32_bf16 v[36:39], v[144:147], v[198:201], v[36:39]
	v_mfma_f32_16x16x32_bf16 v[32:35], v[168:171], v[198:201], v[32:35]
	v_mfma_f32_16x16x32_bf16 v[20:23], v[144:147], v[206:209], v[20:23]
	v_mfma_f32_16x16x32_bf16 v[16:19], v[168:171], v[206:209], v[16:19]
	v_mfma_f32_16x16x32_bf16 v[4:7], v[144:147], v[214:217], v[4:7]
	v_mfma_f32_16x16x32_bf16 v[0:3], v[168:171], v[214:217], v[0:3]
	v_mfma_f32_16x16x32_bf16 v[52:55], v[148:151], v[180:183], v[52:55]
	v_mfma_f32_16x16x32_bf16 v[48:51], v[172:175], v[180:183], v[48:51]
	v_mfma_f32_16x16x32_bf16 v[36:39], v[148:151], v[202:205], v[36:39]
	v_mfma_f32_16x16x32_bf16 v[32:35], v[172:175], v[202:205], v[32:35]
	v_mfma_f32_16x16x32_bf16 v[20:23], v[148:151], v[210:213], v[20:23]
	v_mfma_f32_16x16x32_bf16 v[16:19], v[172:175], v[210:213], v[16:19]
	v_mfma_f32_16x16x32_bf16 v[4:7], v[148:151], v[218:221], v[4:7]
	v_mfma_f32_16x16x32_bf16 v[0:3], v[172:175], v[218:221], v[0:3]
	s_barrier
	s_add_i32 s62, 0, 0x18000
	s_add_i32 s63, 0, 0x1c000
	v_add_u32_e32 v140, s62, v187
	v_add_u32_e32 v172, s63, v187
	ds_read_b128 v[128:131], v140
	ds_read_b128 v[132:135], v140 offset:1024
	ds_read_b128 v[136:139], v140 offset:2048
	ds_read_b128 v[140:143], v140 offset:3072
	ds_read_b128 v[144:147], v172
	ds_read_b128 v[148:151], v172 offset:1024
	ds_read_b128 v[168:171], v172 offset:2048
	ds_read_b128 v[172:175], v172 offset:3072
	s_add_u32 s24, s24, 0xb0000
	s_addc_u32 s25, s25, 0
	s_mov_b32 m0, s39
	v_lshl_add_u64 v[228:229], s[24:25], 0, v[152:153]
	ds_read_b128 v[176:179], v191 offset:32768
	ds_read_b128 v[180:183], v191 offset:33792
	ds_read_b128 v[198:201], v191 offset:34816
	ds_read_b128 v[202:205], v191 offset:35840
	ds_read_b128 v[206:209], v191 offset:36864
	ds_read_b128 v[210:213], v191 offset:37888
	ds_read_b128 v[214:217], v191 offset:38912
	ds_read_b128 v[218:221], v191 offset:39936
	global_load_lds_dwordx4 v[228:229], off
	v_lshl_add_u64 v[228:229], s[24:25], 0, v[156:157]
	s_mov_b32 m0, s40
	s_nop 0
	global_load_lds_dwordx4 v[228:229], off
	s_waitcnt vmcnt(8)
	s_waitcnt lgkmcnt(0)
	s_barrier
	s_waitcnt lgkmcnt(0)
	v_mfma_f32_16x16x32_bf16 v[124:127], v[128:131], v[176:179], v[124:127]
	v_mfma_f32_16x16x32_bf16 v[120:123], v[136:139], v[176:179], v[120:123]
	v_mfma_f32_16x16x32_bf16 v[108:111], v[128:131], v[198:201], v[108:111]
	v_mfma_f32_16x16x32_bf16 v[104:107], v[136:139], v[198:201], v[104:107]
	v_mfma_f32_16x16x32_bf16 v[92:95], v[128:131], v[206:209], v[92:95]
	v_mfma_f32_16x16x32_bf16 v[88:91], v[136:139], v[206:209], v[88:91]
	v_mfma_f32_16x16x32_bf16 v[76:79], v[128:131], v[214:217], v[76:79]
	v_mfma_f32_16x16x32_bf16 v[72:75], v[136:139], v[214:217], v[72:75]
	v_mfma_f32_16x16x32_bf16 v[124:127], v[132:135], v[180:183], v[124:127]
	v_mfma_f32_16x16x32_bf16 v[120:123], v[140:143], v[180:183], v[120:123]
	v_mfma_f32_16x16x32_bf16 v[108:111], v[132:135], v[202:205], v[108:111]
	v_mfma_f32_16x16x32_bf16 v[104:107], v[140:143], v[202:205], v[104:107]
	v_mfma_f32_16x16x32_bf16 v[92:95], v[132:135], v[210:213], v[92:95]
	v_mfma_f32_16x16x32_bf16 v[88:91], v[140:143], v[210:213], v[88:91]
	v_mfma_f32_16x16x32_bf16 v[76:79], v[132:135], v[218:221], v[76:79]
	v_mfma_f32_16x16x32_bf16 v[72:75], v[140:143], v[218:221], v[72:75]
	v_mfma_f32_16x16x32_bf16 v[116:119], v[144:147], v[176:179], v[116:119]
	v_mfma_f32_16x16x32_bf16 v[112:115], v[168:171], v[176:179], v[112:115]
	v_mfma_f32_16x16x32_bf16 v[100:103], v[144:147], v[198:201], v[100:103]
	v_mfma_f32_16x16x32_bf16 v[96:99], v[168:171], v[198:201], v[96:99]
	v_mfma_f32_16x16x32_bf16 v[84:87], v[144:147], v[206:209], v[84:87]
	v_mfma_f32_16x16x32_bf16 v[80:83], v[168:171], v[206:209], v[80:83]
	v_mfma_f32_16x16x32_bf16 v[68:71], v[144:147], v[214:217], v[68:71]
	v_mfma_f32_16x16x32_bf16 v[64:67], v[168:171], v[214:217], v[64:67]
	v_mfma_f32_16x16x32_bf16 v[116:119], v[148:151], v[180:183], v[116:119]
	v_mfma_f32_16x16x32_bf16 v[112:115], v[172:175], v[180:183], v[112:115]
	v_mfma_f32_16x16x32_bf16 v[100:103], v[148:151], v[202:205], v[100:103]
	v_mfma_f32_16x16x32_bf16 v[96:99], v[172:175], v[202:205], v[96:99]
	v_mfma_f32_16x16x32_bf16 v[84:87], v[148:151], v[210:213], v[84:87]
	v_mfma_f32_16x16x32_bf16 v[80:83], v[172:175], v[210:213], v[80:83]
	v_mfma_f32_16x16x32_bf16 v[68:71], v[148:151], v[218:221], v[68:71]
	v_mfma_f32_16x16x32_bf16 v[64:67], v[172:175], v[218:221], v[64:67]
	s_barrier
	s_add_i32 s24, s62, s28
	v_lshl_add_u64 v[184:185], v[184:185], 0, s[12:13]
	s_mov_b32 m0, s24
	ds_read_b128 v[176:179], v191 offset:49152
	ds_read_b128 v[180:183], v191 offset:50176
	ds_read_b128 v[198:201], v191 offset:51200
	ds_read_b128 v[202:205], v191 offset:52224
	ds_read_b128 v[206:209], v191 offset:53248
	ds_read_b128 v[210:213], v191 offset:54272
	ds_read_b128 v[214:217], v191 offset:55296
	ds_read_b128 v[218:221], v191 offset:56320
	global_load_lds_dwordx4 v[184:185], off
	s_add_i32 m0, s24, 0x2000
	s_add_u32 s22, s22, 0xb0080
	v_lshl_add_u64 v[184:185], v[194:195], 0, s[12:13]
	s_addc_u32 s23, s23, 0
	s_add_i32 s24, s63, s28
	global_load_lds_dwordx4 v[184:185], off
	v_lshl_add_u64 v[184:185], s[22:23], 0, v[154:155]
	s_mov_b32 m0, s24
	s_nop 0
	global_load_lds_dwordx4 v[184:185], off
	v_lshl_add_u64 v[184:185], s[22:23], 0, v[158:159]
	s_add_i32 m0, s24, 0x2000
	s_nop 0
	global_load_lds_dwordx4 v[184:185], off
	v_lshl_add_u64 v[184:185], v[222:223], 0, s[12:13]
	s_mov_b32 m0, s44
	s_nop 0
	global_load_lds_dwordx4 v[184:185], off
	v_lshl_add_u64 v[184:185], v[226:227], 0, s[12:13]
	s_mov_b32 m0, s45
	s_nop 0
	global_load_lds_dwordx4 v[184:185], off
	s_waitcnt vmcnt(8)
	s_waitcnt lgkmcnt(0)
	s_barrier
	s_waitcnt lgkmcnt(0)
	v_mfma_f32_16x16x32_bf16 v[60:63], v[128:131], v[176:179], v[60:63]
	v_mfma_f32_16x16x32_bf16 v[56:59], v[136:139], v[176:179], v[56:59]
	v_mfma_f32_16x16x32_bf16 v[44:47], v[128:131], v[198:201], v[44:47]
	v_mfma_f32_16x16x32_bf16 v[40:43], v[136:139], v[198:201], v[40:43]
	v_mfma_f32_16x16x32_bf16 v[28:31], v[128:131], v[206:209], v[28:31]
	v_mfma_f32_16x16x32_bf16 v[24:27], v[136:139], v[206:209], v[24:27]
	v_mfma_f32_16x16x32_bf16 v[12:15], v[128:131], v[214:217], v[12:15]
	v_mfma_f32_16x16x32_bf16 v[8:11], v[136:139], v[214:217], v[8:11]
	v_mfma_f32_16x16x32_bf16 v[60:63], v[132:135], v[180:183], v[60:63]
	v_mfma_f32_16x16x32_bf16 v[56:59], v[140:143], v[180:183], v[56:59]
	v_mfma_f32_16x16x32_bf16 v[44:47], v[132:135], v[202:205], v[44:47]
	v_mfma_f32_16x16x32_bf16 v[40:43], v[140:143], v[202:205], v[40:43]
	v_mfma_f32_16x16x32_bf16 v[28:31], v[132:135], v[210:213], v[28:31]
	v_mfma_f32_16x16x32_bf16 v[24:27], v[140:143], v[210:213], v[24:27]
	v_mfma_f32_16x16x32_bf16 v[12:15], v[132:135], v[218:221], v[12:15]
	v_mfma_f32_16x16x32_bf16 v[8:11], v[140:143], v[218:221], v[8:11]
	v_mfma_f32_16x16x32_bf16 v[52:55], v[144:147], v[176:179], v[52:55]
	v_mfma_f32_16x16x32_bf16 v[48:51], v[168:171], v[176:179], v[48:51]
	v_mfma_f32_16x16x32_bf16 v[36:39], v[144:147], v[198:201], v[36:39]
	v_mfma_f32_16x16x32_bf16 v[32:35], v[168:171], v[198:201], v[32:35]
	v_mfma_f32_16x16x32_bf16 v[20:23], v[144:147], v[206:209], v[20:23]
	v_mfma_f32_16x16x32_bf16 v[16:19], v[168:171], v[206:209], v[16:19]
	v_mfma_f32_16x16x32_bf16 v[4:7], v[144:147], v[214:217], v[4:7]
	v_mfma_f32_16x16x32_bf16 v[0:3], v[168:171], v[214:217], v[0:3]
	v_mfma_f32_16x16x32_bf16 v[52:55], v[148:151], v[180:183], v[52:55]
	v_mfma_f32_16x16x32_bf16 v[48:51], v[172:175], v[180:183], v[48:51]
	v_mfma_f32_16x16x32_bf16 v[36:39], v[148:151], v[202:205], v[36:39]
	v_mfma_f32_16x16x32_bf16 v[32:35], v[172:175], v[202:205], v[32:35]
	v_mfma_f32_16x16x32_bf16 v[20:23], v[148:151], v[210:213], v[20:23]
	v_mfma_f32_16x16x32_bf16 v[16:19], v[172:175], v[210:213], v[16:19]
	v_mfma_f32_16x16x32_bf16 v[4:7], v[148:151], v[218:221], v[4:7]
	v_mfma_f32_16x16x32_bf16 v[0:3], v[172:175], v[218:221], v[0:3]
	s_barrier
	s_add_i32 s66, s66, 2
	s_add_u32 s18, s18, 0x100
	s_addc_u32 s19, s19, 0
	s_add_u32 s64, s64, 0x100
	s_addc_u32 s65, s65, 0
	s_cmp_gt_u32 s66, 41
	s_cbranch_scc0 .LBB0_238
	s_and_b64 vcc, exec, s[14:15]
	s_cbranch_vccz .LBB0_241
	s_barrier

.LBB0_323:
	s_waitcnt vmcnt(0)
	ds_read_b128 v[36:39], v197
	ds_read_b128 v[40:43], v197 offset:1024
	ds_read_b128 v[44:47], v197 offset:2048
	ds_read_b128 v[48:51], v197 offset:3072
	ds_read_b128 v[80:83], v198
	ds_read_b128 v[84:87], v198 offset:1024
	ds_read_b128 v[88:91], v198 offset:2048
	ds_read_b128 v[92:95], v198 offset:3072
	s_add_u32 s28, s24, 0xfffc0080
	s_addc_u32 s29, s25, -1
	s_cmp_eq_u32 s70, 12
	s_cselect_b32 s39, s3, s29
	s_cselect_b32 s38, s17, s28
	s_cselect_b32 s29, s15, s69
	s_cselect_b32 s28, s27, s68
	v_lshl_add_u64 v[226:227], s[24:25], 0, v[172:173]
	s_add_i32 m0, s43, 0xc000
	ds_read_b128 v[180:183], v199
	ds_read_b128 v[184:187], v199 offset:1024
	ds_read_b128 v[188:191], v199 offset:2048
	ds_read_b128 v[204:207], v199 offset:3072
	ds_read_b128 v[208:211], v199 offset:4096
	ds_read_b128 v[212:215], v199 offset:5120
	ds_read_b128 v[216:219], v199 offset:6144
	ds_read_b128 v[220:223], v199 offset:7168
	global_load_lds_dwordx4 v[226:227], off
	v_lshl_add_u64 v[226:227], s[24:25], 0, v[174:175]
	s_add_i32 m0, s43, 0xe000
	s_nop 0
	global_load_lds_dwordx4 v[226:227], off
	s_waitcnt vmcnt(8)
	s_waitcnt lgkmcnt(0)
	s_barrier
	s_waitcnt lgkmcnt(0)
	v_mfma_f32_16x16x32_bf16 v[68:71], v[36:39], v[180:183], v[68:71]
	v_mfma_f32_16x16x32_bf16 v[64:67], v[44:47], v[180:183], v[64:67]
	v_mfma_f32_16x16x32_bf16 v[156:159], v[36:39], v[188:191], v[156:159]
	v_mfma_f32_16x16x32_bf16 v[152:155], v[44:47], v[188:191], v[152:155]
	v_mfma_f32_16x16x32_bf16 v[140:143], v[36:39], v[208:211], v[140:143]
	v_mfma_f32_16x16x32_bf16 v[136:139], v[44:47], v[208:211], v[136:139]
	v_mfma_f32_16x16x32_bf16 v[124:127], v[36:39], v[216:219], v[124:127]
	v_mfma_f32_16x16x32_bf16 v[120:123], v[44:47], v[216:219], v[120:123]
	v_mfma_f32_16x16x32_bf16 v[68:71], v[40:43], v[184:187], v[68:71]
	v_mfma_f32_16x16x32_bf16 v[64:67], v[48:51], v[184:187], v[64:67]
	v_mfma_f32_16x16x32_bf16 v[156:159], v[40:43], v[204:207], v[156:159]
	v_mfma_f32_16x16x32_bf16 v[152:155], v[48:51], v[204:207], v[152:155]
	v_mfma_f32_16x16x32_bf16 v[140:143], v[40:43], v[212:215], v[140:143]
	v_mfma_f32_16x16x32_bf16 v[136:139], v[48:51], v[212:215], v[136:139]
	v_mfma_f32_16x16x32_bf16 v[124:127], v[40:43], v[220:223], v[124:127]
	v_mfma_f32_16x16x32_bf16 v[120:123], v[48:51], v[220:223], v[120:123]
	v_mfma_f32_16x16x32_bf16 v[56:59], v[80:83], v[180:183], v[56:59]
	v_mfma_f32_16x16x32_bf16 v[52:55], v[88:91], v[180:183], v[52:55]
	v_mfma_f32_16x16x32_bf16 v[148:151], v[80:83], v[188:191], v[148:151]
	v_mfma_f32_16x16x32_bf16 v[144:147], v[88:91], v[188:191], v[144:147]
	v_mfma_f32_16x16x32_bf16 v[132:135], v[80:83], v[208:211], v[132:135]
	v_mfma_f32_16x16x32_bf16 v[128:131], v[88:91], v[208:211], v[128:131]
	v_mfma_f32_16x16x32_bf16 v[116:119], v[80:83], v[216:219], v[116:119]
	v_mfma_f32_16x16x32_bf16 v[112:115], v[88:91], v[216:219], v[112:115]
	v_mfma_f32_16x16x32_bf16 v[56:59], v[84:87], v[184:187], v[56:59]
	v_mfma_f32_16x16x32_bf16 v[52:55], v[92:95], v[184:187], v[52:55]
	v_mfma_f32_16x16x32_bf16 v[148:151], v[84:87], v[204:207], v[148:151]
	v_mfma_f32_16x16x32_bf16 v[144:147], v[92:95], v[204:207], v[144:147]
	v_mfma_f32_16x16x32_bf16 v[132:135], v[84:87], v[212:215], v[132:135]
	v_mfma_f32_16x16x32_bf16 v[128:131], v[92:95], v[212:215], v[128:131]
	v_mfma_f32_16x16x32_bf16 v[116:119], v[84:87], v[220:223], v[116:119]
	v_mfma_f32_16x16x32_bf16 v[112:115], v[92:95], v[220:223], v[112:115]
	s_barrier
	s_add_i32 s62, s66, s42
	v_lshl_add_u64 v[230:231], s[28:29], 0, v[162:163]
	s_mov_b32 m0, s62
	ds_read_b128 v[180:183], v199 offset:16384
	ds_read_b128 v[184:187], v199 offset:17408
	ds_read_b128 v[188:191], v199 offset:18432
	ds_read_b128 v[204:207], v199 offset:19456
	ds_read_b128 v[208:211], v199 offset:20480
	ds_read_b128 v[212:215], v199 offset:21504
	ds_read_b128 v[216:219], v199 offset:22528
	ds_read_b128 v[220:223], v199 offset:23552
	global_load_lds_dwordx4 v[230:231], off
	s_add_i32 m0, s62, 0x2000
	s_add_u32 s72, s28, 0x40000
	v_lshl_add_u64 v[232:233], s[28:29], 0, v[166:167]
	s_addc_u32 s73, s29, 0
	s_add_i32 s62, s67, s42
	global_load_lds_dwordx4 v[232:233], off
	v_lshl_add_u64 v[226:227], s[72:73], 0, v[162:163]
	s_mov_b32 m0, s62
	v_lshl_add_u64 v[234:235], s[38:39], 0, v[160:161]
	global_load_lds_dwordx4 v[226:227], off
	v_lshl_add_u64 v[226:227], s[72:73], 0, v[166:167]
	s_add_i32 m0, s62, 0x2000
	v_lshl_add_u64 v[236:237], s[38:39], 0, v[164:165]
	global_load_lds_dwordx4 v[226:227], off
	s_mov_b32 m0, s43
	s_nop 0
	global_load_lds_dwordx4 v[234:235], off
	s_mov_b32 m0, s44
	s_nop 0
	global_load_lds_dwordx4 v[236:237], off
	s_waitcnt vmcnt(8)
	s_waitcnt lgkmcnt(0)
	s_barrier
	s_waitcnt lgkmcnt(0)
	v_mfma_f32_16x16x32_bf16 v[108:111], v[36:39], v[180:183], v[108:111]
	v_mfma_f32_16x16x32_bf16 v[104:107], v[44:47], v[180:183], v[104:107]
	v_mfma_f32_16x16x32_bf16 v[76:79], v[36:39], v[188:191], v[76:79]
	v_mfma_f32_16x16x32_bf16 v[72:75], v[44:47], v[188:191], v[72:75]
	v_mfma_f32_16x16x32_bf16 v[28:31], v[36:39], v[208:211], v[28:31]
	v_mfma_f32_16x16x32_bf16 v[24:27], v[44:47], v[208:211], v[24:27]
	v_mfma_f32_16x16x32_bf16 v[12:15], v[36:39], v[216:219], v[12:15]
	v_mfma_f32_16x16x32_bf16 v[8:11], v[44:47], v[216:219], v[8:11]
	v_mfma_f32_16x16x32_bf16 v[108:111], v[40:43], v[184:187], v[108:111]
	v_mfma_f32_16x16x32_bf16 v[104:107], v[48:51], v[184:187], v[104:107]
	v_mfma_f32_16x16x32_bf16 v[76:79], v[40:43], v[204:207], v[76:79]
	v_mfma_f32_16x16x32_bf16 v[72:75], v[48:51], v[204:207], v[72:75]
	v_mfma_f32_16x16x32_bf16 v[28:31], v[40:43], v[212:215], v[28:31]
	v_mfma_f32_16x16x32_bf16 v[24:27], v[48:51], v[212:215], v[24:27]
	v_mfma_f32_16x16x32_bf16 v[12:15], v[40:43], v[220:223], v[12:15]
	v_mfma_f32_16x16x32_bf16 v[8:11], v[48:51], v[220:223], v[8:11]
	v_mfma_f32_16x16x32_bf16 v[32:35], v[88:91], v[188:191], v[32:35]
	v_mfma_f32_16x16x32_bf16 v[20:23], v[80:83], v[208:211], v[20:23]
	v_mfma_f32_16x16x32_bf16 v[16:19], v[88:91], v[208:211], v[16:19]
	v_mfma_f32_16x16x32_bf16 v[4:7], v[80:83], v[216:219], v[4:7]
	v_mfma_f32_16x16x32_bf16 v[0:3], v[88:91], v[216:219], v[0:3]
	v_mfma_f32_16x16x32_bf16 v[36:39], v[80:83], v[180:183], v[100:103]
	v_mfma_f32_16x16x32_bf16 v[40:43], v[88:91], v[180:183], v[96:99]
	v_mfma_f32_16x16x32_bf16 v[44:47], v[80:83], v[188:191], v[60:63]
	v_mfma_f32_16x16x32_bf16 v[32:35], v[92:95], v[204:207], v[32:35]
	v_mfma_f32_16x16x32_bf16 v[20:23], v[84:87], v[212:215], v[20:23]
	v_mfma_f32_16x16x32_bf16 v[16:19], v[92:95], v[212:215], v[16:19]
	v_mfma_f32_16x16x32_bf16 v[4:7], v[84:87], v[220:223], v[4:7]
	v_mfma_f32_16x16x32_bf16 v[0:3], v[92:95], v[220:223], v[0:3]
	v_mfma_f32_16x16x32_bf16 v[36:39], v[84:87], v[184:187], v[36:39]
	v_mfma_f32_16x16x32_bf16 v[40:43], v[92:95], v[184:187], v[40:43]
	v_mfma_f32_16x16x32_bf16 v[44:47], v[84:87], v[204:207], v[44:47]
	s_barrier
	s_add_i32 s62, 0, 0x18000
	s_add_i32 s63, 0, 0x1c000
	v_add_u32_e32 v84, s62, v194
	v_add_u32_e32 v96, s63, v194
	ds_read_b128 v[48:51], v84
	ds_read_b128 v[60:63], v84 offset:1024
	ds_read_b128 v[80:83], v84 offset:2048
	ds_read_b128 v[84:87], v84 offset:3072
	ds_read_b128 v[88:91], v96
	ds_read_b128 v[92:95], v96 offset:1024
	ds_read_b128 v[180:183], v96 offset:2048
	ds_read_b128 v[184:187], v96 offset:3072
	s_add_u32 s38, s38, 0x40000
	s_addc_u32 s39, s39, 0
	s_mov_b32 m0, s45
	v_lshl_add_u64 v[226:227], s[38:39], 0, v[160:161]
	ds_read_b128 v[96:99], v199 offset:32768
	ds_read_b128 v[100:103], v199 offset:33792
	ds_read_b128 v[188:191], v199 offset:34816
	ds_read_b128 v[204:207], v199 offset:35840
	ds_read_b128 v[208:211], v199 offset:36864
	ds_read_b128 v[212:215], v199 offset:37888
	ds_read_b128 v[216:219], v199 offset:38912
	ds_read_b128 v[220:223], v199 offset:39936
	global_load_lds_dwordx4 v[226:227], off
	v_lshl_add_u64 v[226:227], s[38:39], 0, v[164:165]
	s_mov_b32 m0, s46
	s_nop 0
	global_load_lds_dwordx4 v[226:227], off
	s_waitcnt vmcnt(8)
	s_waitcnt lgkmcnt(0)
	s_barrier
	s_waitcnt lgkmcnt(0)
	v_mfma_f32_16x16x32_bf16 v[68:71], v[48:51], v[96:99], v[68:71]
	v_mfma_f32_16x16x32_bf16 v[64:67], v[80:83], v[96:99], v[64:67]
	v_mfma_f32_16x16x32_bf16 v[156:159], v[48:51], v[188:191], v[156:159]
	v_mfma_f32_16x16x32_bf16 v[152:155], v[80:83], v[188:191], v[152:155]
	v_mfma_f32_16x16x32_bf16 v[140:143], v[48:51], v[208:211], v[140:143]
	v_mfma_f32_16x16x32_bf16 v[136:139], v[80:83], v[208:211], v[136:139]
	v_mfma_f32_16x16x32_bf16 v[124:127], v[48:51], v[216:219], v[124:127]
	v_mfma_f32_16x16x32_bf16 v[120:123], v[80:83], v[216:219], v[120:123]
	v_mfma_f32_16x16x32_bf16 v[68:71], v[60:63], v[100:103], v[68:71]
	v_mfma_f32_16x16x32_bf16 v[64:67], v[84:87], v[100:103], v[64:67]
	v_mfma_f32_16x16x32_bf16 v[156:159], v[60:63], v[204:207], v[156:159]
	v_mfma_f32_16x16x32_bf16 v[152:155], v[84:87], v[204:207], v[152:155]
	v_mfma_f32_16x16x32_bf16 v[140:143], v[60:63], v[212:215], v[140:143]
	v_mfma_f32_16x16x32_bf16 v[136:139], v[84:87], v[212:215], v[136:139]
	v_mfma_f32_16x16x32_bf16 v[124:127], v[60:63], v[220:223], v[124:127]
	v_mfma_f32_16x16x32_bf16 v[120:123], v[84:87], v[220:223], v[120:123]
	v_mfma_f32_16x16x32_bf16 v[56:59], v[88:91], v[96:99], v[56:59]
	v_mfma_f32_16x16x32_bf16 v[52:55], v[180:183], v[96:99], v[52:55]
	v_mfma_f32_16x16x32_bf16 v[96:99], v[88:91], v[188:191], v[148:151]
	v_mfma_f32_16x16x32_bf16 v[148:151], v[92:95], v[204:207], v[96:99]
	v_mfma_f32_16x16x32_bf16 v[96:99], v[180:183], v[188:191], v[144:147]
	v_mfma_f32_16x16x32_bf16 v[144:147], v[184:187], v[204:207], v[96:99]
	v_mfma_f32_16x16x32_bf16 v[96:99], v[88:91], v[208:211], v[132:135]
	v_mfma_f32_16x16x32_bf16 v[132:135], v[92:95], v[212:215], v[96:99]
	v_mfma_f32_16x16x32_bf16 v[96:99], v[180:183], v[208:211], v[128:131]
	v_mfma_f32_16x16x32_bf16 v[128:131], v[184:187], v[212:215], v[96:99]
	v_mfma_f32_16x16x32_bf16 v[96:99], v[88:91], v[216:219], v[116:119]
	v_mfma_f32_16x16x32_bf16 v[116:119], v[92:95], v[220:223], v[96:99]
	v_mfma_f32_16x16x32_bf16 v[96:99], v[180:183], v[216:219], v[112:115]
	v_mfma_f32_16x16x32_bf16 v[56:59], v[92:95], v[100:103], v[56:59]
	v_mfma_f32_16x16x32_bf16 v[52:55], v[184:187], v[100:103], v[52:55]
	v_mfma_f32_16x16x32_bf16 v[112:115], v[184:187], v[220:223], v[96:99]
	s_barrier
	s_add_i32 s38, s62, s42
	v_lshl_add_u64 v[100:101], v[230:231], 0, s[8:9]
	s_mov_b32 m0, s38
	ds_read_b128 v[96:99], v199 offset:49152
	ds_read_b128 v[188:191], v199 offset:50176
	ds_read_b128 v[204:207], v199 offset:51200
	ds_read_b128 v[208:211], v199 offset:52224
	ds_read_b128 v[212:215], v199 offset:53248
	ds_read_b128 v[216:219], v199 offset:54272
	ds_read_b128 v[220:223], v199 offset:55296
	ds_read_b128 v[226:229], v199 offset:56320
	global_load_lds_dwordx4 v[100:101], off
	s_add_i32 m0, s38, 0x2000
	s_add_u32 s28, s28, 0x40080
	v_lshl_add_u64 v[100:101], v[232:233], 0, s[8:9]
	s_addc_u32 s29, s29, 0
	s_add_i32 s38, s63, s42
	global_load_lds_dwordx4 v[100:101], off
	v_lshl_add_u64 v[100:101], s[28:29], 0, v[162:163]
	s_mov_b32 m0, s38
	s_nop 0
	global_load_lds_dwordx4 v[100:101], off
	v_lshl_add_u64 v[100:101], s[28:29], 0, v[166:167]
	s_add_i32 m0, s38, 0x2000
	s_nop 0
	global_load_lds_dwordx4 v[100:101], off
	v_lshl_add_u64 v[100:101], v[234:235], 0, s[8:9]
	s_mov_b32 m0, s51
	s_nop 0
	global_load_lds_dwordx4 v[100:101], off
	v_lshl_add_u64 v[100:101], v[236:237], 0, s[8:9]
	s_mov_b32 m0, s64
	s_nop 0
	global_load_lds_dwordx4 v[100:101], off
	s_waitcnt vmcnt(8)
	s_waitcnt lgkmcnt(0)
	s_barrier
	s_waitcnt lgkmcnt(0)
	v_mfma_f32_16x16x32_bf16 v[100:103], v[48:51], v[96:99], v[108:111]
	v_mfma_f32_16x16x32_bf16 v[108:111], v[60:63], v[188:191], v[100:103]
	v_mfma_f32_16x16x32_bf16 v[100:103], v[80:83], v[96:99], v[104:107]
	v_mfma_f32_16x16x32_bf16 v[76:79], v[48:51], v[204:207], v[76:79]
	v_mfma_f32_16x16x32_bf16 v[72:75], v[80:83], v[204:207], v[72:75]
	v_mfma_f32_16x16x32_bf16 v[28:31], v[48:51], v[212:215], v[28:31]
	v_mfma_f32_16x16x32_bf16 v[24:27], v[80:83], v[212:215], v[24:27]
	v_mfma_f32_16x16x32_bf16 v[12:15], v[48:51], v[220:223], v[12:15]
	v_mfma_f32_16x16x32_bf16 v[8:11], v[80:83], v[220:223], v[8:11]
	v_mfma_f32_16x16x32_bf16 v[104:107], v[84:87], v[188:191], v[100:103]
	v_mfma_f32_16x16x32_bf16 v[76:79], v[60:63], v[208:211], v[76:79]
	v_mfma_f32_16x16x32_bf16 v[72:75], v[84:87], v[208:211], v[72:75]
	v_mfma_f32_16x16x32_bf16 v[28:31], v[60:63], v[216:219], v[28:31]
	v_mfma_f32_16x16x32_bf16 v[24:27], v[84:87], v[216:219], v[24:27]
	v_mfma_f32_16x16x32_bf16 v[12:15], v[60:63], v[226:229], v[12:15]
	v_mfma_f32_16x16x32_bf16 v[8:11], v[84:87], v[226:229], v[8:11]
	v_mfma_f32_16x16x32_bf16 v[36:39], v[88:91], v[96:99], v[36:39]
	v_mfma_f32_16x16x32_bf16 v[100:103], v[92:95], v[188:191], v[36:39]
	v_mfma_f32_16x16x32_bf16 v[36:39], v[180:183], v[96:99], v[40:43]
	v_mfma_f32_16x16x32_bf16 v[96:99], v[184:187], v[188:191], v[36:39]
	v_mfma_f32_16x16x32_bf16 v[36:39], v[88:91], v[204:207], v[44:47]
	v_mfma_f32_16x16x32_bf16 v[32:35], v[180:183], v[204:207], v[32:35]
	v_mfma_f32_16x16x32_bf16 v[20:23], v[88:91], v[212:215], v[20:23]
	v_mfma_f32_16x16x32_bf16 v[16:19], v[180:183], v[212:215], v[16:19]
	v_mfma_f32_16x16x32_bf16 v[4:7], v[88:91], v[220:223], v[4:7]
	v_mfma_f32_16x16x32_bf16 v[0:3], v[180:183], v[220:223], v[0:3]
	v_mfma_f32_16x16x32_bf16 v[60:63], v[92:95], v[208:211], v[36:39]
	v_mfma_f32_16x16x32_bf16 v[32:35], v[184:187], v[208:211], v[32:35]
	v_mfma_f32_16x16x32_bf16 v[20:23], v[92:95], v[216:219], v[20:23]
	v_mfma_f32_16x16x32_bf16 v[16:19], v[184:187], v[216:219], v[16:19]
	v_mfma_f32_16x16x32_bf16 v[4:7], v[92:95], v[226:229], v[4:7]
	v_mfma_f32_16x16x32_bf16 v[0:3], v[184:187], v[226:229], v[0:3]
	s_barrier
	s_add_i32 s70, s70, 2
	s_add_u32 s24, s24, 0x100
	s_addc_u32 s25, s25, 0
	s_add_u32 s68, s68, 0x100
	s_addc_u32 s69, s69, 0
	s_cmp_gt_u32 s70, 13
	s_cbranch_scc0 .LBB0_323
	s_and_b64 vcc, exec, s[10:11]
	s_cbranch_vccz .LBB0_326
	s_barrier

.LBB0_796:
	ds_read_b128 v[128:131], v189
	ds_read_b128 v[132:135], v189 offset:1024
	ds_read_b128 v[136:139], v189 offset:2048
	ds_read_b128 v[140:143], v189 offset:3072
	ds_read_b128 v[144:147], v190
	ds_read_b128 v[148:151], v190 offset:1024
	ds_read_b128 v[168:171], v190 offset:2048
	ds_read_b128 v[172:175], v190 offset:3072
	s_add_u32 s28, s26, 0xfffc0080
	s_addc_u32 s29, s27, -1
	s_cmp_eq_u32 s76, 12
	s_cselect_b32 s45, s17, s29
	s_cselect_b32 s44, s25, s28
	s_cselect_b32 s29, s15, s75
	s_cselect_b32 s28, s73, s74
	v_lshl_add_u64 v[184:185], s[26:27], 0, v[160:161]
	s_add_i32 m0, s49, 0xc000
	ds_read_b128 v[176:179], v191
	ds_read_b128 v[180:183], v191 offset:1024
	ds_read_b128 v[198:201], v191 offset:2048
	ds_read_b128 v[202:205], v191 offset:3072
	ds_read_b128 v[206:209], v191 offset:4096
	ds_read_b128 v[210:213], v191 offset:5120
	ds_read_b128 v[214:217], v191 offset:6144
	ds_read_b128 v[218:221], v191 offset:7168
	global_load_lds_dwordx4 v[184:185], off
	v_lshl_add_u64 v[184:185], s[26:27], 0, v[162:163]
	s_add_i32 m0, s49, 0xe000
	s_nop 0
	global_load_lds_dwordx4 v[184:185], off
	s_waitcnt vmcnt(8)
	s_waitcnt lgkmcnt(0)
	s_barrier
	s_waitcnt lgkmcnt(0)
	v_mfma_f32_16x16x32_bf16 v[124:127], v[128:131], v[176:179], v[124:127]
	v_mfma_f32_16x16x32_bf16 v[120:123], v[136:139], v[176:179], v[120:123]
	v_mfma_f32_16x16x32_bf16 v[108:111], v[128:131], v[198:201], v[108:111]
	v_mfma_f32_16x16x32_bf16 v[104:107], v[136:139], v[198:201], v[104:107]
	v_mfma_f32_16x16x32_bf16 v[92:95], v[128:131], v[206:209], v[92:95]
	v_mfma_f32_16x16x32_bf16 v[88:91], v[136:139], v[206:209], v[88:91]
	v_mfma_f32_16x16x32_bf16 v[76:79], v[128:131], v[214:217], v[76:79]
	v_mfma_f32_16x16x32_bf16 v[72:75], v[136:139], v[214:217], v[72:75]
	v_mfma_f32_16x16x32_bf16 v[124:127], v[132:135], v[180:183], v[124:127]
	v_mfma_f32_16x16x32_bf16 v[120:123], v[140:143], v[180:183], v[120:123]
	v_mfma_f32_16x16x32_bf16 v[108:111], v[132:135], v[202:205], v[108:111]
	v_mfma_f32_16x16x32_bf16 v[104:107], v[140:143], v[202:205], v[104:107]
	v_mfma_f32_16x16x32_bf16 v[92:95], v[132:135], v[210:213], v[92:95]
	v_mfma_f32_16x16x32_bf16 v[88:91], v[140:143], v[210:213], v[88:91]
	v_mfma_f32_16x16x32_bf16 v[76:79], v[132:135], v[218:221], v[76:79]
	v_mfma_f32_16x16x32_bf16 v[72:75], v[140:143], v[218:221], v[72:75]
	v_mfma_f32_16x16x32_bf16 v[116:119], v[144:147], v[176:179], v[116:119]
	v_mfma_f32_16x16x32_bf16 v[112:115], v[168:171], v[176:179], v[112:115]
	v_mfma_f32_16x16x32_bf16 v[100:103], v[144:147], v[198:201], v[100:103]
	v_mfma_f32_16x16x32_bf16 v[96:99], v[168:171], v[198:201], v[96:99]
	v_mfma_f32_16x16x32_bf16 v[84:87], v[144:147], v[206:209], v[84:87]
	v_mfma_f32_16x16x32_bf16 v[80:83], v[168:171], v[206:209], v[80:83]
	v_mfma_f32_16x16x32_bf16 v[68:71], v[144:147], v[214:217], v[68:71]
	v_mfma_f32_16x16x32_bf16 v[64:67], v[168:171], v[214:217], v[64:67]
	v_mfma_f32_16x16x32_bf16 v[116:119], v[148:151], v[180:183], v[116:119]
	v_mfma_f32_16x16x32_bf16 v[112:115], v[172:175], v[180:183], v[112:115]
	v_mfma_f32_16x16x32_bf16 v[100:103], v[148:151], v[202:205], v[100:103]
	v_mfma_f32_16x16x32_bf16 v[96:99], v[172:175], v[202:205], v[96:99]
	v_mfma_f32_16x16x32_bf16 v[84:87], v[148:151], v[210:213], v[84:87]
	v_mfma_f32_16x16x32_bf16 v[80:83], v[172:175], v[210:213], v[80:83]
	v_mfma_f32_16x16x32_bf16 v[68:71], v[148:151], v[218:221], v[68:71]
	v_mfma_f32_16x16x32_bf16 v[64:67], v[172:175], v[218:221], v[64:67]
	s_barrier
	s_add_i32 s62, s70, s48
	v_lshl_add_u64 v[184:185], s[28:29], 0, v[154:155]
	s_mov_b32 m0, s62
	ds_read_b128 v[176:179], v191 offset:16384
	ds_read_b128 v[180:183], v191 offset:17408
	ds_read_b128 v[198:201], v191 offset:18432
	ds_read_b128 v[202:205], v191 offset:19456
	ds_read_b128 v[206:209], v191 offset:20480
	ds_read_b128 v[210:213], v191 offset:21504
	ds_read_b128 v[214:217], v191 offset:22528
	ds_read_b128 v[218:221], v191 offset:23552
	global_load_lds_dwordx4 v[184:185], off
	s_add_i32 m0, s62, 0x2000
	s_add_u32 s78, s28, 0x40000
	v_lshl_add_u64 v[194:195], s[28:29], 0, v[158:159]
	s_addc_u32 s79, s29, 0
	s_add_i32 s62, s71, s48
	global_load_lds_dwordx4 v[194:195], off
	v_lshl_add_u64 v[222:223], s[78:79], 0, v[154:155]
	s_mov_b32 m0, s62
	v_lshl_add_u64 v[226:227], s[44:45], 0, v[156:157]
	global_load_lds_dwordx4 v[222:223], off
	v_lshl_add_u64 v[222:223], s[78:79], 0, v[158:159]
	s_add_i32 m0, s62, 0x2000
	s_nop 0
	global_load_lds_dwordx4 v[222:223], off
	v_lshl_add_u64 v[222:223], s[44:45], 0, v[152:153]
	s_mov_b32 m0, s49
	s_nop 0
	global_load_lds_dwordx4 v[222:223], off
	s_mov_b32 m0, s50
	s_nop 0
	global_load_lds_dwordx4 v[226:227], off
	s_waitcnt vmcnt(8)
	s_waitcnt lgkmcnt(0)
	s_barrier
	s_waitcnt lgkmcnt(0)
	v_mfma_f32_16x16x32_bf16 v[60:63], v[128:131], v[176:179], v[60:63]
	v_mfma_f32_16x16x32_bf16 v[56:59], v[136:139], v[176:179], v[56:59]
	v_mfma_f32_16x16x32_bf16 v[44:47], v[128:131], v[198:201], v[44:47]
	v_mfma_f32_16x16x32_bf16 v[40:43], v[136:139], v[198:201], v[40:43]
	v_mfma_f32_16x16x32_bf16 v[28:31], v[128:131], v[206:209], v[28:31]
	v_mfma_f32_16x16x32_bf16 v[24:27], v[136:139], v[206:209], v[24:27]
	v_mfma_f32_16x16x32_bf16 v[12:15], v[128:131], v[214:217], v[12:15]
	v_mfma_f32_16x16x32_bf16 v[8:11], v[136:139], v[214:217], v[8:11]
	v_mfma_f32_16x16x32_bf16 v[60:63], v[132:135], v[180:183], v[60:63]
	v_mfma_f32_16x16x32_bf16 v[56:59], v[140:143], v[180:183], v[56:59]
	v_mfma_f32_16x16x32_bf16 v[44:47], v[132:135], v[202:205], v[44:47]
	v_mfma_f32_16x16x32_bf16 v[40:43], v[140:143], v[202:205], v[40:43]
	v_mfma_f32_16x16x32_bf16 v[28:31], v[132:135], v[210:213], v[28:31]
	v_mfma_f32_16x16x32_bf16 v[24:27], v[140:143], v[210:213], v[24:27]
	v_mfma_f32_16x16x32_bf16 v[12:15], v[132:135], v[218:221], v[12:15]
	v_mfma_f32_16x16x32_bf16 v[8:11], v[140:143], v[218:221], v[8:11]
	v_mfma_f32_16x16x32_bf16 v[52:55], v[144:147], v[176:179], v[52:55]
	v_mfma_f32_16x16x32_bf16 v[48:51], v[168:171], v[176:179], v[48:51]
	v_mfma_f32_16x16x32_bf16 v[36:39], v[144:147], v[198:201], v[36:39]
	v_mfma_f32_16x16x32_bf16 v[32:35], v[168:171], v[198:201], v[32:35]
	v_mfma_f32_16x16x32_bf16 v[20:23], v[144:147], v[206:209], v[20:23]
	v_mfma_f32_16x16x32_bf16 v[16:19], v[168:171], v[206:209], v[16:19]
	v_mfma_f32_16x16x32_bf16 v[4:7], v[144:147], v[214:217], v[4:7]
	v_mfma_f32_16x16x32_bf16 v[0:3], v[168:171], v[214:217], v[0:3]
	v_mfma_f32_16x16x32_bf16 v[52:55], v[148:151], v[180:183], v[52:55]
	v_mfma_f32_16x16x32_bf16 v[48:51], v[172:175], v[180:183], v[48:51]
	v_mfma_f32_16x16x32_bf16 v[36:39], v[148:151], v[202:205], v[36:39]
	v_mfma_f32_16x16x32_bf16 v[32:35], v[172:175], v[202:205], v[32:35]
	v_mfma_f32_16x16x32_bf16 v[20:23], v[148:151], v[210:213], v[20:23]
	v_mfma_f32_16x16x32_bf16 v[16:19], v[172:175], v[210:213], v[16:19]
	v_mfma_f32_16x16x32_bf16 v[4:7], v[148:151], v[218:221], v[4:7]
	v_mfma_f32_16x16x32_bf16 v[0:3], v[172:175], v[218:221], v[0:3]
	s_barrier
	s_add_i32 s62, 0, 0x18000
	s_add_i32 s63, 0, 0x1c000
	v_add_u32_e32 v140, s62, v187
	v_add_u32_e32 v172, s63, v187
	ds_read_b128 v[128:131], v140
	ds_read_b128 v[132:135], v140 offset:1024
	ds_read_b128 v[136:139], v140 offset:2048
	ds_read_b128 v[140:143], v140 offset:3072
	ds_read_b128 v[144:147], v172
	ds_read_b128 v[148:151], v172 offset:1024
	ds_read_b128 v[168:171], v172 offset:2048
	ds_read_b128 v[172:175], v172 offset:3072
	s_add_u32 s44, s44, 0x40000
	s_addc_u32 s45, s45, 0
	s_mov_b32 m0, s51
	v_lshl_add_u64 v[228:229], s[44:45], 0, v[152:153]
	ds_read_b128 v[176:179], v191 offset:32768
	ds_read_b128 v[180:183], v191 offset:33792
	ds_read_b128 v[198:201], v191 offset:34816
	ds_read_b128 v[202:205], v191 offset:35840
	ds_read_b128 v[206:209], v191 offset:36864
	ds_read_b128 v[210:213], v191 offset:37888
	ds_read_b128 v[214:217], v191 offset:38912
	ds_read_b128 v[218:221], v191 offset:39936
	global_load_lds_dwordx4 v[228:229], off
	v_lshl_add_u64 v[228:229], s[44:45], 0, v[156:157]
	s_mov_b32 m0, s64
	s_nop 0
	global_load_lds_dwordx4 v[228:229], off
	s_waitcnt vmcnt(8)
	s_waitcnt lgkmcnt(0)
	s_barrier
	s_waitcnt lgkmcnt(0)
	v_mfma_f32_16x16x32_bf16 v[124:127], v[128:131], v[176:179], v[124:127]
	v_mfma_f32_16x16x32_bf16 v[120:123], v[136:139], v[176:179], v[120:123]
	v_mfma_f32_16x16x32_bf16 v[108:111], v[128:131], v[198:201], v[108:111]
	v_mfma_f32_16x16x32_bf16 v[104:107], v[136:139], v[198:201], v[104:107]
	v_mfma_f32_16x16x32_bf16 v[92:95], v[128:131], v[206:209], v[92:95]
	v_mfma_f32_16x16x32_bf16 v[88:91], v[136:139], v[206:209], v[88:91]
	v_mfma_f32_16x16x32_bf16 v[76:79], v[128:131], v[214:217], v[76:79]
	v_mfma_f32_16x16x32_bf16 v[72:75], v[136:139], v[214:217], v[72:75]
	v_mfma_f32_16x16x32_bf16 v[124:127], v[132:135], v[180:183], v[124:127]
	v_mfma_f32_16x16x32_bf16 v[120:123], v[140:143], v[180:183], v[120:123]
	v_mfma_f32_16x16x32_bf16 v[108:111], v[132:135], v[202:205], v[108:111]
	v_mfma_f32_16x16x32_bf16 v[104:107], v[140:143], v[202:205], v[104:107]
	v_mfma_f32_16x16x32_bf16 v[92:95], v[132:135], v[210:213], v[92:95]
	v_mfma_f32_16x16x32_bf16 v[88:91], v[140:143], v[210:213], v[88:91]
	v_mfma_f32_16x16x32_bf16 v[76:79], v[132:135], v[218:221], v[76:79]
	v_mfma_f32_16x16x32_bf16 v[72:75], v[140:143], v[218:221], v[72:75]
	v_mfma_f32_16x16x32_bf16 v[116:119], v[144:147], v[176:179], v[116:119]
	v_mfma_f32_16x16x32_bf16 v[112:115], v[168:171], v[176:179], v[112:115]
	v_mfma_f32_16x16x32_bf16 v[100:103], v[144:147], v[198:201], v[100:103]
	v_mfma_f32_16x16x32_bf16 v[96:99], v[168:171], v[198:201], v[96:99]
	v_mfma_f32_16x16x32_bf16 v[84:87], v[144:147], v[206:209], v[84:87]
	v_mfma_f32_16x16x32_bf16 v[80:83], v[168:171], v[206:209], v[80:83]
	v_mfma_f32_16x16x32_bf16 v[68:71], v[144:147], v[214:217], v[68:71]
	v_mfma_f32_16x16x32_bf16 v[64:67], v[168:171], v[214:217], v[64:67]
	v_mfma_f32_16x16x32_bf16 v[116:119], v[148:151], v[180:183], v[116:119]
	v_mfma_f32_16x16x32_bf16 v[112:115], v[172:175], v[180:183], v[112:115]
	v_mfma_f32_16x16x32_bf16 v[100:103], v[148:151], v[202:205], v[100:103]
	v_mfma_f32_16x16x32_bf16 v[96:99], v[172:175], v[202:205], v[96:99]
	v_mfma_f32_16x16x32_bf16 v[84:87], v[148:151], v[210:213], v[84:87]
	v_mfma_f32_16x16x32_bf16 v[80:83], v[172:175], v[210:213], v[80:83]
	v_mfma_f32_16x16x32_bf16 v[68:71], v[148:151], v[218:221], v[68:71]
	v_mfma_f32_16x16x32_bf16 v[64:67], v[172:175], v[218:221], v[64:67]
	s_barrier
	s_add_i32 s44, s62, s48
	v_lshl_add_u64 v[184:185], v[184:185], 0, s[10:11]
	s_mov_b32 m0, s44
	ds_read_b128 v[176:179], v191 offset:49152
	ds_read_b128 v[180:183], v191 offset:50176
	ds_read_b128 v[198:201], v191 offset:51200
	ds_read_b128 v[202:205], v191 offset:52224
	ds_read_b128 v[206:209], v191 offset:53248
	ds_read_b128 v[210:213], v191 offset:54272
	ds_read_b128 v[214:217], v191 offset:55296
	ds_read_b128 v[218:221], v191 offset:56320
	global_load_lds_dwordx4 v[184:185], off
	s_add_i32 m0, s44, 0x2000
	s_add_u32 s28, s28, 0x40080
	v_lshl_add_u64 v[184:185], v[194:195], 0, s[10:11]
	s_addc_u32 s29, s29, 0
	s_add_i32 s44, s63, s48
	global_load_lds_dwordx4 v[184:185], off
	v_lshl_add_u64 v[184:185], s[28:29], 0, v[154:155]
	s_mov_b32 m0, s44
	s_nop 0
	global_load_lds_dwordx4 v[184:185], off
	v_lshl_add_u64 v[184:185], s[28:29], 0, v[158:159]
	s_add_i32 m0, s44, 0x2000
	s_nop 0
	global_load_lds_dwordx4 v[184:185], off
	v_lshl_add_u64 v[184:185], v[222:223], 0, s[10:11]
	s_mov_b32 m0, s66
	s_nop 0
	global_load_lds_dwordx4 v[184:185], off
	v_lshl_add_u64 v[184:185], v[226:227], 0, s[10:11]
	s_mov_b32 m0, s67
	s_nop 0
	global_load_lds_dwordx4 v[184:185], off
	s_waitcnt vmcnt(8)
	s_waitcnt lgkmcnt(0)
	s_barrier
	s_waitcnt lgkmcnt(0)
	v_mfma_f32_16x16x32_bf16 v[60:63], v[128:131], v[176:179], v[60:63]
	v_mfma_f32_16x16x32_bf16 v[56:59], v[136:139], v[176:179], v[56:59]
	v_mfma_f32_16x16x32_bf16 v[44:47], v[128:131], v[198:201], v[44:47]
	v_mfma_f32_16x16x32_bf16 v[40:43], v[136:139], v[198:201], v[40:43]
	v_mfma_f32_16x16x32_bf16 v[28:31], v[128:131], v[206:209], v[28:31]
	v_mfma_f32_16x16x32_bf16 v[24:27], v[136:139], v[206:209], v[24:27]
	v_mfma_f32_16x16x32_bf16 v[12:15], v[128:131], v[214:217], v[12:15]
	v_mfma_f32_16x16x32_bf16 v[8:11], v[136:139], v[214:217], v[8:11]
	v_mfma_f32_16x16x32_bf16 v[60:63], v[132:135], v[180:183], v[60:63]
	v_mfma_f32_16x16x32_bf16 v[56:59], v[140:143], v[180:183], v[56:59]
	v_mfma_f32_16x16x32_bf16 v[44:47], v[132:135], v[202:205], v[44:47]
	v_mfma_f32_16x16x32_bf16 v[40:43], v[140:143], v[202:205], v[40:43]
	v_mfma_f32_16x16x32_bf16 v[28:31], v[132:135], v[210:213], v[28:31]
	v_mfma_f32_16x16x32_bf16 v[24:27], v[140:143], v[210:213], v[24:27]
	v_mfma_f32_16x16x32_bf16 v[12:15], v[132:135], v[218:221], v[12:15]
	v_mfma_f32_16x16x32_bf16 v[8:11], v[140:143], v[218:221], v[8:11]
	v_mfma_f32_16x16x32_bf16 v[52:55], v[144:147], v[176:179], v[52:55]
	v_mfma_f32_16x16x32_bf16 v[48:51], v[168:171], v[176:179], v[48:51]
	v_mfma_f32_16x16x32_bf16 v[36:39], v[144:147], v[198:201], v[36:39]
	v_mfma_f32_16x16x32_bf16 v[32:35], v[168:171], v[198:201], v[32:35]
	v_mfma_f32_16x16x32_bf16 v[20:23], v[144:147], v[206:209], v[20:23]
	v_mfma_f32_16x16x32_bf16 v[16:19], v[168:171], v[206:209], v[16:19]
	v_mfma_f32_16x16x32_bf16 v[4:7], v[144:147], v[214:217], v[4:7]
	v_mfma_f32_16x16x32_bf16 v[0:3], v[168:171], v[214:217], v[0:3]
	v_mfma_f32_16x16x32_bf16 v[52:55], v[148:151], v[180:183], v[52:55]
	v_mfma_f32_16x16x32_bf16 v[48:51], v[172:175], v[180:183], v[48:51]
	v_mfma_f32_16x16x32_bf16 v[36:39], v[148:151], v[202:205], v[36:39]
	v_mfma_f32_16x16x32_bf16 v[32:35], v[172:175], v[202:205], v[32:35]
	v_mfma_f32_16x16x32_bf16 v[20:23], v[148:151], v[210:213], v[20:23]
	v_mfma_f32_16x16x32_bf16 v[16:19], v[172:175], v[210:213], v[16:19]
	v_mfma_f32_16x16x32_bf16 v[4:7], v[148:151], v[218:221], v[4:7]
	v_mfma_f32_16x16x32_bf16 v[0:3], v[172:175], v[218:221], v[0:3]
	s_barrier
	s_add_i32 s76, s76, 2
	s_add_u32 s26, s26, 0x100
	s_addc_u32 s27, s27, 0
	s_add_u32 s74, s74, 0x100
	s_addc_u32 s75, s75, 0
	s_cmp_gt_u32 s76, 13
	s_cbranch_scc0 .LBB0_796
	s_and_b64 vcc, exec, s[12:13]
	s_cbranch_vccz .LBB0_799
	s_barrier

.LBB0_879:
	ds_read_b128 v[160:163], v155
	ds_read_b128 v[164:167], v155 offset:1024
	ds_read_b128 v[168:171], v155 offset:2048
	ds_read_b128 v[172:175], v155 offset:3072
	ds_read_b128 v[176:179], v156
	ds_read_b128 v[180:183], v156 offset:1024
	ds_read_b128 v[184:187], v156 offset:2048
	ds_read_b128 v[188:191], v156 offset:3072
	s_add_u32 s24, s22, 0xfffc0080
	s_addc_u32 s25, s23, -1
	s_cmp_eq_u32 s74, 12
	s_cselect_b32 s27, s13, s25
	s_cselect_b32 s26, s70, s24
	s_cselect_b32 s25, s11, s73
	s_cselect_b32 s24, s71, s72
	v_lshl_add_u64 v[146:147], s[22:23], 0, v[138:139]
	s_add_i32 m0, s19, 0xc000
	ds_read_b128 v[192:195], v157
	ds_read_b128 v[198:201], v157 offset:1024
	ds_read_b128 v[202:205], v157 offset:2048
	ds_read_b128 v[206:209], v157 offset:3072
	ds_read_b128 v[210:213], v157 offset:4096
	ds_read_b128 v[214:217], v157 offset:5120
	ds_read_b128 v[218:221], v157 offset:6144
	ds_read_b128 v[226:229], v157 offset:7168
	global_load_lds_dwordx4 v[146:147], off
	v_lshl_add_u64 v[146:147], s[22:23], 0, v[140:141]
	s_add_i32 m0, s19, 0xe000
	s_nop 0
	global_load_lds_dwordx4 v[146:147], off
	s_waitcnt vmcnt(8)
	s_waitcnt lgkmcnt(0)
	s_barrier
	s_waitcnt lgkmcnt(0)
	v_mfma_f32_16x16x32_bf16 v[124:127], v[160:163], v[192:195], v[124:127]
	v_mfma_f32_16x16x32_bf16 v[120:123], v[168:171], v[192:195], v[120:123]
	v_mfma_f32_16x16x32_bf16 v[108:111], v[160:163], v[202:205], v[108:111]
	v_mfma_f32_16x16x32_bf16 v[104:107], v[168:171], v[202:205], v[104:107]
	v_mfma_f32_16x16x32_bf16 v[92:95], v[160:163], v[210:213], v[92:95]
	v_mfma_f32_16x16x32_bf16 v[88:91], v[168:171], v[210:213], v[88:91]
	v_mfma_f32_16x16x32_bf16 v[76:79], v[160:163], v[218:221], v[76:79]
	v_mfma_f32_16x16x32_bf16 v[72:75], v[168:171], v[218:221], v[72:75]
	v_mfma_f32_16x16x32_bf16 v[124:127], v[164:167], v[198:201], v[124:127]
	v_mfma_f32_16x16x32_bf16 v[120:123], v[172:175], v[198:201], v[120:123]
	v_mfma_f32_16x16x32_bf16 v[108:111], v[164:167], v[206:209], v[108:111]
	v_mfma_f32_16x16x32_bf16 v[104:107], v[172:175], v[206:209], v[104:107]
	v_mfma_f32_16x16x32_bf16 v[92:95], v[164:167], v[214:217], v[92:95]
	v_mfma_f32_16x16x32_bf16 v[88:91], v[172:175], v[214:217], v[88:91]
	v_mfma_f32_16x16x32_bf16 v[76:79], v[164:167], v[226:229], v[76:79]
	v_mfma_f32_16x16x32_bf16 v[72:75], v[172:175], v[226:229], v[72:75]
	v_mfma_f32_16x16x32_bf16 v[116:119], v[176:179], v[192:195], v[116:119]
	v_mfma_f32_16x16x32_bf16 v[112:115], v[184:187], v[192:195], v[112:115]
	v_mfma_f32_16x16x32_bf16 v[100:103], v[176:179], v[202:205], v[100:103]
	v_mfma_f32_16x16x32_bf16 v[96:99], v[184:187], v[202:205], v[96:99]
	v_mfma_f32_16x16x32_bf16 v[84:87], v[176:179], v[210:213], v[84:87]
	v_mfma_f32_16x16x32_bf16 v[80:83], v[184:187], v[210:213], v[80:83]
	v_mfma_f32_16x16x32_bf16 v[68:71], v[176:179], v[218:221], v[68:71]
	v_mfma_f32_16x16x32_bf16 v[64:67], v[184:187], v[218:221], v[64:67]
	v_mfma_f32_16x16x32_bf16 v[116:119], v[180:183], v[198:201], v[116:119]
	v_mfma_f32_16x16x32_bf16 v[112:115], v[188:191], v[198:201], v[112:115]
	v_mfma_f32_16x16x32_bf16 v[100:103], v[180:183], v[206:209], v[100:103]
	v_mfma_f32_16x16x32_bf16 v[96:99], v[188:191], v[206:209], v[96:99]
	v_mfma_f32_16x16x32_bf16 v[84:87], v[180:183], v[214:217], v[84:87]
	v_mfma_f32_16x16x32_bf16 v[80:83], v[188:191], v[214:217], v[80:83]
	v_mfma_f32_16x16x32_bf16 v[68:71], v[180:183], v[226:229], v[68:71]
	v_mfma_f32_16x16x32_bf16 v[64:67], v[188:191], v[226:229], v[64:67]
	s_barrier
	s_add_i32 s62, s66, s44
	v_lshl_add_u64 v[146:147], s[24:25], 0, v[132:133]
	s_mov_b32 m0, s62
	ds_read_b128 v[192:195], v157 offset:16384
	ds_read_b128 v[198:201], v157 offset:17408
	ds_read_b128 v[202:205], v157 offset:18432
	ds_read_b128 v[206:209], v157 offset:19456
	ds_read_b128 v[210:213], v157 offset:20480
	ds_read_b128 v[214:217], v157 offset:21504
	ds_read_b128 v[218:221], v157 offset:22528
	ds_read_b128 v[226:229], v157 offset:23552
	global_load_lds_dwordx4 v[146:147], off
	s_add_i32 m0, s62, 0x2000
	s_add_u32 s76, s24, 0x40000
	v_lshl_add_u64 v[222:223], s[24:25], 0, v[128:129]
	s_addc_u32 s77, s25, 0
	s_add_i32 s62, s67, s44
	global_load_lds_dwordx4 v[222:223], off
	v_lshl_add_u64 v[230:231], s[76:77], 0, v[132:133]
	s_mov_b32 m0, s62
	v_lshl_add_u64 v[232:233], s[26:27], 0, v[130:131]
	global_load_lds_dwordx4 v[230:231], off
	v_lshl_add_u64 v[230:231], s[76:77], 0, v[128:129]
	s_add_i32 m0, s62, 0x2000
	s_nop 0
	global_load_lds_dwordx4 v[230:231], off
	v_lshl_add_u64 v[230:231], s[26:27], 0, v[134:135]
	s_mov_b32 m0, s19
	s_nop 0
	global_load_lds_dwordx4 v[230:231], off
	s_mov_b32 m0, s47
	s_nop 0
	global_load_lds_dwordx4 v[232:233], off
	s_waitcnt vmcnt(8)
	s_waitcnt lgkmcnt(0)
	s_barrier
	s_waitcnt lgkmcnt(0)
	v_mfma_f32_16x16x32_bf16 v[60:63], v[160:163], v[192:195], v[60:63]
	v_mfma_f32_16x16x32_bf16 v[56:59], v[168:171], v[192:195], v[56:59]
	v_mfma_f32_16x16x32_bf16 v[44:47], v[160:163], v[202:205], v[44:47]
	v_mfma_f32_16x16x32_bf16 v[40:43], v[168:171], v[202:205], v[40:43]
	v_mfma_f32_16x16x32_bf16 v[28:31], v[160:163], v[210:213], v[28:31]
	v_mfma_f32_16x16x32_bf16 v[24:27], v[168:171], v[210:213], v[24:27]
	v_mfma_f32_16x16x32_bf16 v[12:15], v[160:163], v[218:221], v[12:15]
	v_mfma_f32_16x16x32_bf16 v[8:11], v[168:171], v[218:221], v[8:11]
	v_mfma_f32_16x16x32_bf16 v[60:63], v[164:167], v[198:201], v[60:63]
	v_mfma_f32_16x16x32_bf16 v[56:59], v[172:175], v[198:201], v[56:59]
	v_mfma_f32_16x16x32_bf16 v[44:47], v[164:167], v[206:209], v[44:47]
	v_mfma_f32_16x16x32_bf16 v[40:43], v[172:175], v[206:209], v[40:43]
	v_mfma_f32_16x16x32_bf16 v[28:31], v[164:167], v[214:217], v[28:31]
	v_mfma_f32_16x16x32_bf16 v[24:27], v[172:175], v[214:217], v[24:27]
	v_mfma_f32_16x16x32_bf16 v[12:15], v[164:167], v[226:229], v[12:15]
	v_mfma_f32_16x16x32_bf16 v[8:11], v[172:175], v[226:229], v[8:11]
	v_mfma_f32_16x16x32_bf16 v[52:55], v[176:179], v[192:195], v[52:55]
	v_mfma_f32_16x16x32_bf16 v[48:51], v[184:187], v[192:195], v[48:51]
	v_mfma_f32_16x16x32_bf16 v[36:39], v[176:179], v[202:205], v[36:39]
	v_mfma_f32_16x16x32_bf16 v[32:35], v[184:187], v[202:205], v[32:35]
	v_mfma_f32_16x16x32_bf16 v[20:23], v[176:179], v[210:213], v[20:23]
	v_mfma_f32_16x16x32_bf16 v[16:19], v[184:187], v[210:213], v[16:19]
	v_mfma_f32_16x16x32_bf16 v[4:7], v[176:179], v[218:221], v[4:7]
	v_mfma_f32_16x16x32_bf16 v[0:3], v[184:187], v[218:221], v[0:3]
	v_mfma_f32_16x16x32_bf16 v[52:55], v[180:183], v[198:201], v[52:55]
	v_mfma_f32_16x16x32_bf16 v[48:51], v[188:191], v[198:201], v[48:51]
	v_mfma_f32_16x16x32_bf16 v[36:39], v[180:183], v[206:209], v[36:39]
	v_mfma_f32_16x16x32_bf16 v[32:35], v[188:191], v[206:209], v[32:35]
	v_mfma_f32_16x16x32_bf16 v[20:23], v[180:183], v[214:217], v[20:23]
	v_mfma_f32_16x16x32_bf16 v[16:19], v[188:191], v[214:217], v[16:19]
	v_mfma_f32_16x16x32_bf16 v[4:7], v[180:183], v[226:229], v[4:7]
	v_mfma_f32_16x16x32_bf16 v[0:3], v[188:191], v[226:229], v[0:3]
	s_barrier
	s_add_i32 s62, 0, 0x18000
	v_add_u32_e32 v148, s62, v150
	s_add_i32 s63, 0, 0x1c000
	ds_read_b128 v[160:163], v148
	ds_read_b128 v[164:167], v148 offset:1024
	ds_read_b128 v[168:171], v148 offset:2048
	ds_read_b128 v[172:175], v148 offset:3072
	v_add_u32_e32 v148, s63, v150
	ds_read_b128 v[176:179], v148
	ds_read_b128 v[180:183], v148 offset:1024
	ds_read_b128 v[184:187], v148 offset:2048
	ds_read_b128 v[188:191], v148 offset:3072
	s_add_u32 s26, s26, 0x40000
	s_addc_u32 s27, s27, 0
	s_mov_b32 m0, s48
	v_lshl_add_u64 v[234:235], s[26:27], 0, v[134:135]
	ds_read_b128 v[192:195], v157 offset:32768
	ds_read_b128 v[198:201], v157 offset:33792
	ds_read_b128 v[202:205], v157 offset:34816
	ds_read_b128 v[206:209], v157 offset:35840
	ds_read_b128 v[210:213], v157 offset:36864
	ds_read_b128 v[214:217], v157 offset:37888
	ds_read_b128 v[218:221], v157 offset:38912
	ds_read_b128 v[226:229], v157 offset:39936
	global_load_lds_dwordx4 v[234:235], off
	v_lshl_add_u64 v[234:235], s[26:27], 0, v[130:131]
	s_mov_b32 m0, s49
	s_nop 0
	global_load_lds_dwordx4 v[234:235], off
	s_waitcnt vmcnt(8)
	s_waitcnt lgkmcnt(0)
	s_barrier
	s_waitcnt lgkmcnt(0)
	v_mfma_f32_16x16x32_bf16 v[124:127], v[160:163], v[192:195], v[124:127]
	v_mfma_f32_16x16x32_bf16 v[120:123], v[168:171], v[192:195], v[120:123]
	v_mfma_f32_16x16x32_bf16 v[108:111], v[160:163], v[202:205], v[108:111]
	v_mfma_f32_16x16x32_bf16 v[104:107], v[168:171], v[202:205], v[104:107]
	v_mfma_f32_16x16x32_bf16 v[92:95], v[160:163], v[210:213], v[92:95]
	v_mfma_f32_16x16x32_bf16 v[88:91], v[168:171], v[210:213], v[88:91]
	v_mfma_f32_16x16x32_bf16 v[76:79], v[160:163], v[218:221], v[76:79]
	v_mfma_f32_16x16x32_bf16 v[72:75], v[168:171], v[218:221], v[72:75]
	v_mfma_f32_16x16x32_bf16 v[124:127], v[164:167], v[198:201], v[124:127]
	v_mfma_f32_16x16x32_bf16 v[120:123], v[172:175], v[198:201], v[120:123]
	v_mfma_f32_16x16x32_bf16 v[108:111], v[164:167], v[206:209], v[108:111]
	v_mfma_f32_16x16x32_bf16 v[104:107], v[172:175], v[206:209], v[104:107]
	v_mfma_f32_16x16x32_bf16 v[92:95], v[164:167], v[214:217], v[92:95]
	v_mfma_f32_16x16x32_bf16 v[88:91], v[172:175], v[214:217], v[88:91]
	v_mfma_f32_16x16x32_bf16 v[76:79], v[164:167], v[226:229], v[76:79]
	v_mfma_f32_16x16x32_bf16 v[72:75], v[172:175], v[226:229], v[72:75]
	v_mfma_f32_16x16x32_bf16 v[116:119], v[176:179], v[192:195], v[116:119]
	v_mfma_f32_16x16x32_bf16 v[112:115], v[184:187], v[192:195], v[112:115]
	v_mfma_f32_16x16x32_bf16 v[100:103], v[176:179], v[202:205], v[100:103]
	v_mfma_f32_16x16x32_bf16 v[96:99], v[184:187], v[202:205], v[96:99]
	v_mfma_f32_16x16x32_bf16 v[84:87], v[176:179], v[210:213], v[84:87]
	v_mfma_f32_16x16x32_bf16 v[80:83], v[184:187], v[210:213], v[80:83]
	v_mfma_f32_16x16x32_bf16 v[68:71], v[176:179], v[218:221], v[68:71]
	v_mfma_f32_16x16x32_bf16 v[64:67], v[184:187], v[218:221], v[64:67]
	v_mfma_f32_16x16x32_bf16 v[116:119], v[180:183], v[198:201], v[116:119]
	v_mfma_f32_16x16x32_bf16 v[112:115], v[188:191], v[198:201], v[112:115]
	v_mfma_f32_16x16x32_bf16 v[100:103], v[180:183], v[206:209], v[100:103]
	v_mfma_f32_16x16x32_bf16 v[96:99], v[188:191], v[206:209], v[96:99]
	v_mfma_f32_16x16x32_bf16 v[84:87], v[180:183], v[214:217], v[84:87]
	v_mfma_f32_16x16x32_bf16 v[80:83], v[188:191], v[214:217], v[80:83]
	v_mfma_f32_16x16x32_bf16 v[68:71], v[180:183], v[226:229], v[68:71]
	v_mfma_f32_16x16x32_bf16 v[64:67], v[188:191], v[226:229], v[64:67]
	s_barrier
	s_add_i32 s26, s62, s44
	v_lshl_add_u64 v[146:147], v[146:147], 0, s[6:7]
	s_mov_b32 m0, s26
	ds_read_b128 v[192:195], v157 offset:49152
	ds_read_b128 v[198:201], v157 offset:50176
	ds_read_b128 v[202:205], v157 offset:51200
	ds_read_b128 v[206:209], v157 offset:52224
	ds_read_b128 v[210:213], v157 offset:53248
	ds_read_b128 v[214:217], v157 offset:54272
	ds_read_b128 v[218:221], v157 offset:55296
	ds_read_b128 v[226:229], v157 offset:56320
	global_load_lds_dwordx4 v[146:147], off
	s_add_i32 m0, s26, 0x2000
	s_add_u32 s24, s24, 0x40080
	v_lshl_add_u64 v[146:147], v[222:223], 0, s[6:7]
	s_addc_u32 s25, s25, 0
	s_add_i32 s26, s63, s44
	global_load_lds_dwordx4 v[146:147], off
	v_lshl_add_u64 v[146:147], s[24:25], 0, v[132:133]
	s_mov_b32 m0, s26
	s_nop 0
	global_load_lds_dwordx4 v[146:147], off
	v_lshl_add_u64 v[146:147], s[24:25], 0, v[128:129]
	s_add_i32 m0, s26, 0x2000
	s_nop 0
	global_load_lds_dwordx4 v[146:147], off
	v_lshl_add_u64 v[146:147], v[230:231], 0, s[6:7]
	s_mov_b32 m0, s51
	s_nop 0
	global_load_lds_dwordx4 v[146:147], off
	v_lshl_add_u64 v[146:147], v[232:233], 0, s[6:7]
	s_mov_b32 m0, s64
	s_nop 0
	global_load_lds_dwordx4 v[146:147], off
	s_waitcnt vmcnt(8)
	s_waitcnt lgkmcnt(0)
	s_barrier
	s_waitcnt lgkmcnt(0)
	v_mfma_f32_16x16x32_bf16 v[60:63], v[160:163], v[192:195], v[60:63]
	v_mfma_f32_16x16x32_bf16 v[56:59], v[168:171], v[192:195], v[56:59]
	v_mfma_f32_16x16x32_bf16 v[44:47], v[160:163], v[202:205], v[44:47]
	v_mfma_f32_16x16x32_bf16 v[40:43], v[168:171], v[202:205], v[40:43]
	v_mfma_f32_16x16x32_bf16 v[28:31], v[160:163], v[210:213], v[28:31]
	v_mfma_f32_16x16x32_bf16 v[24:27], v[168:171], v[210:213], v[24:27]
	v_mfma_f32_16x16x32_bf16 v[12:15], v[160:163], v[218:221], v[12:15]
	v_mfma_f32_16x16x32_bf16 v[8:11], v[168:171], v[218:221], v[8:11]
	v_mfma_f32_16x16x32_bf16 v[60:63], v[164:167], v[198:201], v[60:63]
	v_mfma_f32_16x16x32_bf16 v[56:59], v[172:175], v[198:201], v[56:59]
	v_mfma_f32_16x16x32_bf16 v[44:47], v[164:167], v[206:209], v[44:47]
	v_mfma_f32_16x16x32_bf16 v[40:43], v[172:175], v[206:209], v[40:43]
	v_mfma_f32_16x16x32_bf16 v[28:31], v[164:167], v[214:217], v[28:31]
	v_mfma_f32_16x16x32_bf16 v[24:27], v[172:175], v[214:217], v[24:27]
	v_mfma_f32_16x16x32_bf16 v[12:15], v[164:167], v[226:229], v[12:15]
	v_mfma_f32_16x16x32_bf16 v[8:11], v[172:175], v[226:229], v[8:11]
	v_mfma_f32_16x16x32_bf16 v[52:55], v[176:179], v[192:195], v[52:55]
	v_mfma_f32_16x16x32_bf16 v[48:51], v[184:187], v[192:195], v[48:51]
	v_mfma_f32_16x16x32_bf16 v[36:39], v[176:179], v[202:205], v[36:39]
	v_mfma_f32_16x16x32_bf16 v[32:35], v[184:187], v[202:205], v[32:35]
	v_mfma_f32_16x16x32_bf16 v[20:23], v[176:179], v[210:213], v[20:23]
	v_mfma_f32_16x16x32_bf16 v[16:19], v[184:187], v[210:213], v[16:19]
	v_mfma_f32_16x16x32_bf16 v[4:7], v[176:179], v[218:221], v[4:7]
	v_mfma_f32_16x16x32_bf16 v[0:3], v[184:187], v[218:221], v[0:3]
	v_mfma_f32_16x16x32_bf16 v[52:55], v[180:183], v[198:201], v[52:55]
	v_mfma_f32_16x16x32_bf16 v[48:51], v[188:191], v[198:201], v[48:51]
	v_mfma_f32_16x16x32_bf16 v[36:39], v[180:183], v[206:209], v[36:39]
	v_mfma_f32_16x16x32_bf16 v[32:35], v[188:191], v[206:209], v[32:35]
	v_mfma_f32_16x16x32_bf16 v[20:23], v[180:183], v[214:217], v[20:23]
	v_mfma_f32_16x16x32_bf16 v[16:19], v[188:191], v[214:217], v[16:19]
	v_mfma_f32_16x16x32_bf16 v[4:7], v[180:183], v[226:229], v[4:7]
	v_mfma_f32_16x16x32_bf16 v[0:3], v[188:191], v[226:229], v[0:3]
	s_barrier
	s_add_i32 s74, s74, 2
	s_add_u32 s22, s22, 0x100
	s_addc_u32 s23, s23, 0
	s_add_u32 s72, s72, 0x100
	s_addc_u32 s73, s73, 0
	s_cmp_gt_u32 s74, 13
	s_cbranch_scc0 .LBB0_879
	s_and_b64 vcc, exec, s[8:9]
	s_cbranch_vccz .LBB0_882
	s_barrier

.LBB0_960:
	ds_read_b128 v[128:131], v189
	ds_read_b128 v[132:135], v189 offset:1024
	ds_read_b128 v[136:139], v189 offset:2048
	ds_read_b128 v[140:143], v189 offset:3072
	ds_read_b128 v[144:147], v190
	ds_read_b128 v[148:151], v190 offset:1024
	ds_read_b128 v[168:171], v190 offset:2048
	ds_read_b128 v[172:175], v190 offset:3072
	s_add_u32 s22, s18, 0xfff50080
	s_addc_u32 s23, s19, -1
	s_cmp_eq_u32 s72, 40
	s_cselect_b32 s25, s5, s23
	s_cselect_b32 s24, s4, s22
	s_cselect_b32 s23, s17, s71
	s_cselect_b32 s22, s16, s70
	v_lshl_add_u64 v[184:185], s[18:19], 0, v[160:161]
	s_add_i32 m0, s29, 0xc000
	ds_read_b128 v[176:179], v191
	ds_read_b128 v[180:183], v191 offset:1024
	ds_read_b128 v[198:201], v191 offset:2048
	ds_read_b128 v[202:205], v191 offset:3072
	ds_read_b128 v[206:209], v191 offset:4096
	ds_read_b128 v[210:213], v191 offset:5120
	ds_read_b128 v[214:217], v191 offset:6144
	ds_read_b128 v[218:221], v191 offset:7168
	global_load_lds_dwordx4 v[184:185], off
	v_lshl_add_u64 v[184:185], s[18:19], 0, v[162:163]
	s_add_i32 m0, s29, 0xe000
	s_nop 0
	global_load_lds_dwordx4 v[184:185], off
	s_waitcnt vmcnt(8)
	s_waitcnt lgkmcnt(0)
	s_barrier
	s_waitcnt lgkmcnt(0)
	v_mfma_f32_16x16x32_bf16 v[124:127], v[128:131], v[176:179], v[124:127]
	v_mfma_f32_16x16x32_bf16 v[120:123], v[136:139], v[176:179], v[120:123]
	v_mfma_f32_16x16x32_bf16 v[108:111], v[128:131], v[198:201], v[108:111]
	v_mfma_f32_16x16x32_bf16 v[104:107], v[136:139], v[198:201], v[104:107]
	v_mfma_f32_16x16x32_bf16 v[92:95], v[128:131], v[206:209], v[92:95]
	v_mfma_f32_16x16x32_bf16 v[88:91], v[136:139], v[206:209], v[88:91]
	v_mfma_f32_16x16x32_bf16 v[76:79], v[128:131], v[214:217], v[76:79]
	v_mfma_f32_16x16x32_bf16 v[72:75], v[136:139], v[214:217], v[72:75]
	v_mfma_f32_16x16x32_bf16 v[124:127], v[132:135], v[180:183], v[124:127]
	v_mfma_f32_16x16x32_bf16 v[120:123], v[140:143], v[180:183], v[120:123]
	v_mfma_f32_16x16x32_bf16 v[108:111], v[132:135], v[202:205], v[108:111]
	v_mfma_f32_16x16x32_bf16 v[104:107], v[140:143], v[202:205], v[104:107]
	v_mfma_f32_16x16x32_bf16 v[92:95], v[132:135], v[210:213], v[92:95]
	v_mfma_f32_16x16x32_bf16 v[88:91], v[140:143], v[210:213], v[88:91]
	v_mfma_f32_16x16x32_bf16 v[76:79], v[132:135], v[218:221], v[76:79]
	v_mfma_f32_16x16x32_bf16 v[72:75], v[140:143], v[218:221], v[72:75]
	v_mfma_f32_16x16x32_bf16 v[116:119], v[144:147], v[176:179], v[116:119]
	v_mfma_f32_16x16x32_bf16 v[112:115], v[168:171], v[176:179], v[112:115]
	v_mfma_f32_16x16x32_bf16 v[100:103], v[144:147], v[198:201], v[100:103]
	v_mfma_f32_16x16x32_bf16 v[96:99], v[168:171], v[198:201], v[96:99]
	v_mfma_f32_16x16x32_bf16 v[84:87], v[144:147], v[206:209], v[84:87]
	v_mfma_f32_16x16x32_bf16 v[80:83], v[168:171], v[206:209], v[80:83]
	v_mfma_f32_16x16x32_bf16 v[68:71], v[144:147], v[214:217], v[68:71]
	v_mfma_f32_16x16x32_bf16 v[64:67], v[168:171], v[214:217], v[64:67]
	v_mfma_f32_16x16x32_bf16 v[116:119], v[148:151], v[180:183], v[116:119]
	v_mfma_f32_16x16x32_bf16 v[112:115], v[172:175], v[180:183], v[112:115]
	v_mfma_f32_16x16x32_bf16 v[100:103], v[148:151], v[202:205], v[100:103]
	v_mfma_f32_16x16x32_bf16 v[96:99], v[172:175], v[202:205], v[96:99]
	v_mfma_f32_16x16x32_bf16 v[84:87], v[148:151], v[210:213], v[84:87]
	v_mfma_f32_16x16x32_bf16 v[80:83], v[172:175], v[210:213], v[80:83]
	v_mfma_f32_16x16x32_bf16 v[68:71], v[148:151], v[218:221], v[68:71]
	v_mfma_f32_16x16x32_bf16 v[64:67], v[172:175], v[218:221], v[64:67]
	s_barrier
	s_add_i32 s62, s64, s28
	v_lshl_add_u64 v[184:185], s[22:23], 0, v[154:155]
	s_mov_b32 m0, s62
	ds_read_b128 v[176:179], v191 offset:16384
	ds_read_b128 v[180:183], v191 offset:17408
	ds_read_b128 v[198:201], v191 offset:18432
	ds_read_b128 v[202:205], v191 offset:19456
	ds_read_b128 v[206:209], v191 offset:20480
	ds_read_b128 v[210:213], v191 offset:21504
	ds_read_b128 v[214:217], v191 offset:22528
	ds_read_b128 v[218:221], v191 offset:23552
	global_load_lds_dwordx4 v[184:185], off
	s_add_i32 m0, s62, 0x2000
	s_add_u32 s74, s22, 0xb0000
	v_lshl_add_u64 v[194:195], s[22:23], 0, v[158:159]
	s_addc_u32 s75, s23, 0
	s_add_i32 s62, s65, s28
	global_load_lds_dwordx4 v[194:195], off
	v_lshl_add_u64 v[222:223], s[74:75], 0, v[154:155]
	s_mov_b32 m0, s62
	v_lshl_add_u64 v[226:227], s[24:25], 0, v[156:157]
	global_load_lds_dwordx4 v[222:223], off
	v_lshl_add_u64 v[222:223], s[74:75], 0, v[158:159]
	s_add_i32 m0, s62, 0x2000
	s_nop 0
	global_load_lds_dwordx4 v[222:223], off
	v_lshl_add_u64 v[222:223], s[24:25], 0, v[152:153]
	s_mov_b32 m0, s29
	s_nop 0
	global_load_lds_dwordx4 v[222:223], off
	s_mov_b32 m0, s44
	s_nop 0
	global_load_lds_dwordx4 v[226:227], off
	s_waitcnt vmcnt(8)
	s_waitcnt lgkmcnt(0)
	s_barrier
	s_waitcnt lgkmcnt(0)
	v_mfma_f32_16x16x32_bf16 v[60:63], v[128:131], v[176:179], v[60:63]
	v_mfma_f32_16x16x32_bf16 v[56:59], v[136:139], v[176:179], v[56:59]
	v_mfma_f32_16x16x32_bf16 v[44:47], v[128:131], v[198:201], v[44:47]
	v_mfma_f32_16x16x32_bf16 v[40:43], v[136:139], v[198:201], v[40:43]
	v_mfma_f32_16x16x32_bf16 v[28:31], v[128:131], v[206:209], v[28:31]
	v_mfma_f32_16x16x32_bf16 v[24:27], v[136:139], v[206:209], v[24:27]
	v_mfma_f32_16x16x32_bf16 v[12:15], v[128:131], v[214:217], v[12:15]
	v_mfma_f32_16x16x32_bf16 v[8:11], v[136:139], v[214:217], v[8:11]
	v_mfma_f32_16x16x32_bf16 v[60:63], v[132:135], v[180:183], v[60:63]
	v_mfma_f32_16x16x32_bf16 v[56:59], v[140:143], v[180:183], v[56:59]
	v_mfma_f32_16x16x32_bf16 v[44:47], v[132:135], v[202:205], v[44:47]
	v_mfma_f32_16x16x32_bf16 v[40:43], v[140:143], v[202:205], v[40:43]
	v_mfma_f32_16x16x32_bf16 v[28:31], v[132:135], v[210:213], v[28:31]
	v_mfma_f32_16x16x32_bf16 v[24:27], v[140:143], v[210:213], v[24:27]
	v_mfma_f32_16x16x32_bf16 v[12:15], v[132:135], v[218:221], v[12:15]
	v_mfma_f32_16x16x32_bf16 v[8:11], v[140:143], v[218:221], v[8:11]
	v_mfma_f32_16x16x32_bf16 v[52:55], v[144:147], v[176:179], v[52:55]
	v_mfma_f32_16x16x32_bf16 v[48:51], v[168:171], v[176:179], v[48:51]
	v_mfma_f32_16x16x32_bf16 v[36:39], v[144:147], v[198:201], v[36:39]
	v_mfma_f32_16x16x32_bf16 v[32:35], v[168:171], v[198:201], v[32:35]
	v_mfma_f32_16x16x32_bf16 v[20:23], v[144:147], v[206:209], v[20:23]
	v_mfma_f32_16x16x32_bf16 v[16:19], v[168:171], v[206:209], v[16:19]
	v_mfma_f32_16x16x32_bf16 v[4:7], v[144:147], v[214:217], v[4:7]
	v_mfma_f32_16x16x32_bf16 v[0:3], v[168:171], v[214:217], v[0:3]
	v_mfma_f32_16x16x32_bf16 v[52:55], v[148:151], v[180:183], v[52:55]
	v_mfma_f32_16x16x32_bf16 v[48:51], v[172:175], v[180:183], v[48:51]
	v_mfma_f32_16x16x32_bf16 v[36:39], v[148:151], v[202:205], v[36:39]
	v_mfma_f32_16x16x32_bf16 v[32:35], v[172:175], v[202:205], v[32:35]
	v_mfma_f32_16x16x32_bf16 v[20:23], v[148:151], v[210:213], v[20:23]
	v_mfma_f32_16x16x32_bf16 v[16:19], v[172:175], v[210:213], v[16:19]
	v_mfma_f32_16x16x32_bf16 v[4:7], v[148:151], v[218:221], v[4:7]
	v_mfma_f32_16x16x32_bf16 v[0:3], v[172:175], v[218:221], v[0:3]
	s_barrier
	s_add_i32 s62, 0, 0x18000
	s_add_i32 s63, 0, 0x1c000
	v_add_u32_e32 v140, s62, v187
	v_add_u32_e32 v172, s63, v187
	ds_read_b128 v[128:131], v140
	ds_read_b128 v[132:135], v140 offset:1024
	ds_read_b128 v[136:139], v140 offset:2048
	ds_read_b128 v[140:143], v140 offset:3072
	ds_read_b128 v[144:147], v172
	ds_read_b128 v[148:151], v172 offset:1024
	ds_read_b128 v[168:171], v172 offset:2048
	ds_read_b128 v[172:175], v172 offset:3072
	s_add_u32 s24, s24, 0xb0000
	s_addc_u32 s25, s25, 0
	s_mov_b32 m0, s45
	v_lshl_add_u64 v[228:229], s[24:25], 0, v[152:153]
	ds_read_b128 v[176:179], v191 offset:32768
	ds_read_b128 v[180:183], v191 offset:33792
	ds_read_b128 v[198:201], v191 offset:34816
	ds_read_b128 v[202:205], v191 offset:35840
	ds_read_b128 v[206:209], v191 offset:36864
	ds_read_b128 v[210:213], v191 offset:37888
	ds_read_b128 v[214:217], v191 offset:38912
	ds_read_b128 v[218:221], v191 offset:39936
	global_load_lds_dwordx4 v[228:229], off
	v_lshl_add_u64 v[228:229], s[24:25], 0, v[156:157]
	s_mov_b32 m0, s46
	s_nop 0
	global_load_lds_dwordx4 v[228:229], off
	s_waitcnt vmcnt(8)
	s_waitcnt lgkmcnt(0)
	s_barrier
	s_waitcnt lgkmcnt(0)
	v_mfma_f32_16x16x32_bf16 v[124:127], v[128:131], v[176:179], v[124:127]
	v_mfma_f32_16x16x32_bf16 v[120:123], v[136:139], v[176:179], v[120:123]
	v_mfma_f32_16x16x32_bf16 v[108:111], v[128:131], v[198:201], v[108:111]
	v_mfma_f32_16x16x32_bf16 v[104:107], v[136:139], v[198:201], v[104:107]
	v_mfma_f32_16x16x32_bf16 v[92:95], v[128:131], v[206:209], v[92:95]
	v_mfma_f32_16x16x32_bf16 v[88:91], v[136:139], v[206:209], v[88:91]
	v_mfma_f32_16x16x32_bf16 v[76:79], v[128:131], v[214:217], v[76:79]
	v_mfma_f32_16x16x32_bf16 v[72:75], v[136:139], v[214:217], v[72:75]
	v_mfma_f32_16x16x32_bf16 v[124:127], v[132:135], v[180:183], v[124:127]
	v_mfma_f32_16x16x32_bf16 v[120:123], v[140:143], v[180:183], v[120:123]
	v_mfma_f32_16x16x32_bf16 v[108:111], v[132:135], v[202:205], v[108:111]
	v_mfma_f32_16x16x32_bf16 v[104:107], v[140:143], v[202:205], v[104:107]
	v_mfma_f32_16x16x32_bf16 v[92:95], v[132:135], v[210:213], v[92:95]
	v_mfma_f32_16x16x32_bf16 v[88:91], v[140:143], v[210:213], v[88:91]
	v_mfma_f32_16x16x32_bf16 v[76:79], v[132:135], v[218:221], v[76:79]
	v_mfma_f32_16x16x32_bf16 v[72:75], v[140:143], v[218:221], v[72:75]
	v_mfma_f32_16x16x32_bf16 v[116:119], v[144:147], v[176:179], v[116:119]
	v_mfma_f32_16x16x32_bf16 v[112:115], v[168:171], v[176:179], v[112:115]
	v_mfma_f32_16x16x32_bf16 v[100:103], v[144:147], v[198:201], v[100:103]
	v_mfma_f32_16x16x32_bf16 v[96:99], v[168:171], v[198:201], v[96:99]
	v_mfma_f32_16x16x32_bf16 v[84:87], v[144:147], v[206:209], v[84:87]
	v_mfma_f32_16x16x32_bf16 v[80:83], v[168:171], v[206:209], v[80:83]
	v_mfma_f32_16x16x32_bf16 v[68:71], v[144:147], v[214:217], v[68:71]
	v_mfma_f32_16x16x32_bf16 v[64:67], v[168:171], v[214:217], v[64:67]
	v_mfma_f32_16x16x32_bf16 v[116:119], v[148:151], v[180:183], v[116:119]
	v_mfma_f32_16x16x32_bf16 v[112:115], v[172:175], v[180:183], v[112:115]
	v_mfma_f32_16x16x32_bf16 v[100:103], v[148:151], v[202:205], v[100:103]
	v_mfma_f32_16x16x32_bf16 v[96:99], v[172:175], v[202:205], v[96:99]
	v_mfma_f32_16x16x32_bf16 v[84:87], v[148:151], v[210:213], v[84:87]
	v_mfma_f32_16x16x32_bf16 v[80:83], v[172:175], v[210:213], v[80:83]
	v_mfma_f32_16x16x32_bf16 v[68:71], v[148:151], v[218:221], v[68:71]
	v_mfma_f32_16x16x32_bf16 v[64:67], v[172:175], v[218:221], v[64:67]
	s_barrier
	s_add_i32 s24, s62, s28
	v_lshl_add_u64 v[184:185], v[184:185], 0, s[12:13]
	s_mov_b32 m0, s24
	ds_read_b128 v[176:179], v191 offset:49152
	ds_read_b128 v[180:183], v191 offset:50176
	ds_read_b128 v[198:201], v191 offset:51200
	ds_read_b128 v[202:205], v191 offset:52224
	ds_read_b128 v[206:209], v191 offset:53248
	ds_read_b128 v[210:213], v191 offset:54272
	ds_read_b128 v[214:217], v191 offset:55296
	ds_read_b128 v[218:221], v191 offset:56320
	global_load_lds_dwordx4 v[184:185], off
	s_add_i32 m0, s24, 0x2000
	s_add_u32 s22, s22, 0xb0080
	v_lshl_add_u64 v[184:185], v[194:195], 0, s[12:13]
	s_addc_u32 s23, s23, 0
	s_add_i32 s24, s63, s28
	global_load_lds_dwordx4 v[184:185], off
	v_lshl_add_u64 v[184:185], s[22:23], 0, v[154:155]
	s_mov_b32 m0, s24
	s_nop 0
	global_load_lds_dwordx4 v[184:185], off
	v_lshl_add_u64 v[184:185], s[22:23], 0, v[158:159]
	s_add_i32 m0, s24, 0x2000
	s_nop 0
	global_load_lds_dwordx4 v[184:185], off
	v_lshl_add_u64 v[184:185], v[222:223], 0, s[12:13]
	s_mov_b32 m0, s48
	s_nop 0
	global_load_lds_dwordx4 v[184:185], off
	v_lshl_add_u64 v[184:185], v[226:227], 0, s[12:13]
	s_mov_b32 m0, s49
	s_nop 0
	global_load_lds_dwordx4 v[184:185], off
	s_waitcnt vmcnt(8)
	s_waitcnt lgkmcnt(0)
	s_barrier
	s_waitcnt lgkmcnt(0)
	v_mfma_f32_16x16x32_bf16 v[60:63], v[128:131], v[176:179], v[60:63]
	v_mfma_f32_16x16x32_bf16 v[56:59], v[136:139], v[176:179], v[56:59]
	v_mfma_f32_16x16x32_bf16 v[44:47], v[128:131], v[198:201], v[44:47]
	v_mfma_f32_16x16x32_bf16 v[40:43], v[136:139], v[198:201], v[40:43]
	v_mfma_f32_16x16x32_bf16 v[28:31], v[128:131], v[206:209], v[28:31]
	v_mfma_f32_16x16x32_bf16 v[24:27], v[136:139], v[206:209], v[24:27]
	v_mfma_f32_16x16x32_bf16 v[12:15], v[128:131], v[214:217], v[12:15]
	v_mfma_f32_16x16x32_bf16 v[8:11], v[136:139], v[214:217], v[8:11]
	v_mfma_f32_16x16x32_bf16 v[60:63], v[132:135], v[180:183], v[60:63]
	v_mfma_f32_16x16x32_bf16 v[56:59], v[140:143], v[180:183], v[56:59]
	v_mfma_f32_16x16x32_bf16 v[44:47], v[132:135], v[202:205], v[44:47]
	v_mfma_f32_16x16x32_bf16 v[40:43], v[140:143], v[202:205], v[40:43]
	v_mfma_f32_16x16x32_bf16 v[28:31], v[132:135], v[210:213], v[28:31]
	v_mfma_f32_16x16x32_bf16 v[24:27], v[140:143], v[210:213], v[24:27]
	v_mfma_f32_16x16x32_bf16 v[12:15], v[132:135], v[218:221], v[12:15]
	v_mfma_f32_16x16x32_bf16 v[8:11], v[140:143], v[218:221], v[8:11]
	v_mfma_f32_16x16x32_bf16 v[52:55], v[144:147], v[176:179], v[52:55]
	v_mfma_f32_16x16x32_bf16 v[48:51], v[168:171], v[176:179], v[48:51]
	v_mfma_f32_16x16x32_bf16 v[36:39], v[144:147], v[198:201], v[36:39]
	v_mfma_f32_16x16x32_bf16 v[32:35], v[168:171], v[198:201], v[32:35]
	v_mfma_f32_16x16x32_bf16 v[20:23], v[144:147], v[206:209], v[20:23]
	v_mfma_f32_16x16x32_bf16 v[16:19], v[168:171], v[206:209], v[16:19]
	v_mfma_f32_16x16x32_bf16 v[4:7], v[144:147], v[214:217], v[4:7]
	v_mfma_f32_16x16x32_bf16 v[0:3], v[168:171], v[214:217], v[0:3]
	v_mfma_f32_16x16x32_bf16 v[52:55], v[148:151], v[180:183], v[52:55]
	v_mfma_f32_16x16x32_bf16 v[48:51], v[172:175], v[180:183], v[48:51]
	v_mfma_f32_16x16x32_bf16 v[36:39], v[148:151], v[202:205], v[36:39]
	v_mfma_f32_16x16x32_bf16 v[32:35], v[172:175], v[202:205], v[32:35]
	v_mfma_f32_16x16x32_bf16 v[20:23], v[148:151], v[210:213], v[20:23]
	v_mfma_f32_16x16x32_bf16 v[16:19], v[172:175], v[210:213], v[16:19]
	v_mfma_f32_16x16x32_bf16 v[4:7], v[148:151], v[218:221], v[4:7]
	v_mfma_f32_16x16x32_bf16 v[0:3], v[172:175], v[218:221], v[0:3]
	s_barrier
	s_add_i32 s72, s72, 2
	s_add_u32 s18, s18, 0x100
	s_addc_u32 s19, s19, 0
	s_add_u32 s70, s70, 0x100
	s_addc_u32 s71, s71, 0
	s_cmp_gt_u32 s72, 41
	s_cbranch_scc0 .LBB0_960
	s_and_b64 vcc, exec, s[14:15]
	s_cbranch_vccz .LBB0_963
	s_barrier

.LBB0_1053:
	ds_read_b128 v[32:35], v222
	s_waitcnt vmcnt(0)
	ds_read_b128 v[36:39], v222 offset:1024
	ds_read_b128 v[40:43], v222 offset:2048
	ds_read_b128 v[44:47], v222 offset:3072
	ds_read_b128 v[80:83], v223
	ds_read_b128 v[84:87], v223 offset:1024
	ds_read_b128 v[88:91], v223 offset:2048
	ds_read_b128 v[92:95], v223 offset:3072
	s_add_u32 s46, s4, 0xfffc0080
	s_addc_u32 s47, s5, -1
	s_cmp_eq_u32 s84, 12
	s_cselect_b32 s49, s25, s47
	s_cselect_b32 s48, s45, s46
	s_cselect_b32 s47, s23, s65
	s_cselect_b32 s46, s51, s64
	v_lshl_add_u64 v[194:195], s[4:5], 0, v[174:175]
	s_add_i32 m0, s70, 0xc000
	ds_read_b128 v[182:185], v225
	ds_read_b128 v[186:189], v225 offset:1024
	ds_read_b128 v[190:193], v225 offset:2048
	ds_read_b128 v[198:201], v225 offset:3072
	ds_read_b128 v[202:205], v225 offset:4096
	ds_read_b128 v[206:209], v225 offset:5120
	ds_read_b128 v[210:213], v225 offset:6144
	ds_read_b128 v[228:231], v225 offset:7168
	global_load_lds_dwordx4 v[194:195], off
	v_lshl_add_u64 v[194:195], s[4:5], 0, v[176:177]
	s_add_i32 m0, s70, 0xe000
	s_nop 0
	global_load_lds_dwordx4 v[194:195], off
	s_waitcnt vmcnt(8)
	s_waitcnt lgkmcnt(0)
	s_barrier
	s_waitcnt lgkmcnt(0)
	v_mfma_f32_16x16x32_bf16 v[68:71], v[32:35], v[182:185], v[68:71]
	v_mfma_f32_16x16x32_bf16 v[60:63], v[40:43], v[182:185], v[60:63]
	v_mfma_f32_16x16x32_bf16 v[156:159], v[32:35], v[190:193], v[156:159]
	v_mfma_f32_16x16x32_bf16 v[152:155], v[40:43], v[190:193], v[152:155]
	v_mfma_f32_16x16x32_bf16 v[140:143], v[32:35], v[202:205], v[140:143]
	v_mfma_f32_16x16x32_bf16 v[136:139], v[40:43], v[202:205], v[136:139]
	v_mfma_f32_16x16x32_bf16 v[124:127], v[32:35], v[210:213], v[124:127]
	v_mfma_f32_16x16x32_bf16 v[120:123], v[40:43], v[210:213], v[120:123]
	v_mfma_f32_16x16x32_bf16 v[68:71], v[36:39], v[186:189], v[68:71]
	v_mfma_f32_16x16x32_bf16 v[60:63], v[44:47], v[186:189], v[60:63]
	v_mfma_f32_16x16x32_bf16 v[156:159], v[36:39], v[198:201], v[156:159]
	v_mfma_f32_16x16x32_bf16 v[152:155], v[44:47], v[198:201], v[152:155]
	v_mfma_f32_16x16x32_bf16 v[140:143], v[36:39], v[206:209], v[140:143]
	v_mfma_f32_16x16x32_bf16 v[136:139], v[44:47], v[206:209], v[136:139]
	v_mfma_f32_16x16x32_bf16 v[124:127], v[36:39], v[228:231], v[124:127]
	v_mfma_f32_16x16x32_bf16 v[120:123], v[44:47], v[228:231], v[120:123]
	v_mfma_f32_16x16x32_bf16 v[56:59], v[80:83], v[182:185], v[56:59]
	v_mfma_f32_16x16x32_bf16 v[48:51], v[88:91], v[182:185], v[48:51]
	v_mfma_f32_16x16x32_bf16 v[148:151], v[80:83], v[190:193], v[148:151]
	v_mfma_f32_16x16x32_bf16 v[144:147], v[88:91], v[190:193], v[144:147]
	v_mfma_f32_16x16x32_bf16 v[132:135], v[80:83], v[202:205], v[132:135]
	v_mfma_f32_16x16x32_bf16 v[128:131], v[88:91], v[202:205], v[128:131]
	v_mfma_f32_16x16x32_bf16 v[116:119], v[80:83], v[210:213], v[116:119]
	v_mfma_f32_16x16x32_bf16 v[112:115], v[88:91], v[210:213], v[112:115]
	v_mfma_f32_16x16x32_bf16 v[56:59], v[84:87], v[186:189], v[56:59]
	v_mfma_f32_16x16x32_bf16 v[48:51], v[92:95], v[186:189], v[48:51]
	v_mfma_f32_16x16x32_bf16 v[148:151], v[84:87], v[198:201], v[148:151]
	v_mfma_f32_16x16x32_bf16 v[144:147], v[92:95], v[198:201], v[144:147]
	v_mfma_f32_16x16x32_bf16 v[132:135], v[84:87], v[206:209], v[132:135]
	v_mfma_f32_16x16x32_bf16 v[128:131], v[92:95], v[206:209], v[128:131]
	v_mfma_f32_16x16x32_bf16 v[116:119], v[84:87], v[228:231], v[116:119]
	v_mfma_f32_16x16x32_bf16 v[112:115], v[92:95], v[228:231], v[112:115]
	s_barrier
	s_add_i32 s62, s82, s69
	v_lshl_add_u64 v[194:195], s[46:47], 0, v[162:163]
	s_mov_b32 m0, s62
	ds_read_b128 v[182:185], v225 offset:16384
	ds_read_b128 v[186:189], v225 offset:17408
	ds_read_b128 v[190:193], v225 offset:18432
	ds_read_b128 v[198:201], v225 offset:19456
	ds_read_b128 v[202:205], v225 offset:20480
	ds_read_b128 v[206:209], v225 offset:21504
	ds_read_b128 v[210:213], v225 offset:22528
	ds_read_b128 v[228:231], v225 offset:23552
	global_load_lds_dwordx4 v[194:195], off
	s_add_i32 m0, s62, 0x2000
	s_add_u32 s86, s46, 0x40000
	v_lshl_add_u64 v[236:237], s[46:47], 0, v[166:167]
	s_addc_u32 s87, s47, 0
	s_add_i32 s62, s83, s69
	global_load_lds_dwordx4 v[236:237], off
	v_lshl_add_u64 v[232:233], s[86:87], 0, v[162:163]
	s_mov_b32 m0, s62
	v_lshl_add_u64 v[238:239], s[48:49], 0, v[160:161]
	global_load_lds_dwordx4 v[232:233], off
	v_lshl_add_u64 v[232:233], s[86:87], 0, v[166:167]
	s_add_i32 m0, s62, 0x2000
	v_lshl_add_u64 v[240:241], s[48:49], 0, v[164:165]
	global_load_lds_dwordx4 v[232:233], off
	s_mov_b32 m0, s70
	s_nop 0
	global_load_lds_dwordx4 v[238:239], off
	s_mov_b32 m0, s71
	s_nop 0
	global_load_lds_dwordx4 v[240:241], off
	s_waitcnt vmcnt(8)
	s_waitcnt lgkmcnt(0)
	s_barrier
	s_waitcnt lgkmcnt(0)
	v_mfma_f32_16x16x32_bf16 v[108:111], v[32:35], v[182:185], v[108:111]
	v_mfma_f32_16x16x32_bf16 v[104:107], v[40:43], v[182:185], v[104:107]
	v_mfma_f32_16x16x32_bf16 v[76:79], v[32:35], v[190:193], v[76:79]
	v_mfma_f32_16x16x32_bf16 v[72:75], v[40:43], v[190:193], v[72:75]
	v_mfma_f32_16x16x32_bf16 v[28:31], v[32:35], v[202:205], v[28:31]
	v_mfma_f32_16x16x32_bf16 v[24:27], v[40:43], v[202:205], v[24:27]
	v_mfma_f32_16x16x32_bf16 v[12:15], v[32:35], v[210:213], v[12:15]
	v_mfma_f32_16x16x32_bf16 v[8:11], v[40:43], v[210:213], v[8:11]
	v_mfma_f32_16x16x32_bf16 v[108:111], v[36:39], v[186:189], v[108:111]
	v_mfma_f32_16x16x32_bf16 v[104:107], v[44:47], v[186:189], v[104:107]
	v_mfma_f32_16x16x32_bf16 v[76:79], v[36:39], v[198:201], v[76:79]
	v_mfma_f32_16x16x32_bf16 v[72:75], v[44:47], v[198:201], v[72:75]
	v_mfma_f32_16x16x32_bf16 v[28:31], v[36:39], v[206:209], v[28:31]
	v_mfma_f32_16x16x32_bf16 v[24:27], v[44:47], v[206:209], v[24:27]
	v_mfma_f32_16x16x32_bf16 v[12:15], v[36:39], v[228:231], v[12:15]
	v_mfma_f32_16x16x32_bf16 v[8:11], v[44:47], v[228:231], v[8:11]
	v_mfma_f32_16x16x32_bf16 v[20:23], v[80:83], v[202:205], v[20:23]
	v_mfma_f32_16x16x32_bf16 v[16:19], v[88:91], v[202:205], v[16:19]
	v_mfma_f32_16x16x32_bf16 v[4:7], v[80:83], v[210:213], v[4:7]
	v_mfma_f32_16x16x32_bf16 v[0:3], v[88:91], v[210:213], v[0:3]
	v_mfma_f32_16x16x32_bf16 v[32:35], v[80:83], v[182:185], v[100:103]
	v_mfma_f32_16x16x32_bf16 v[36:39], v[88:91], v[182:185], v[96:99]
	v_mfma_f32_16x16x32_bf16 v[40:43], v[80:83], v[190:193], v[64:67]
	v_mfma_f32_16x16x32_bf16 v[44:47], v[88:91], v[190:193], v[52:55]
	v_mfma_f32_16x16x32_bf16 v[20:23], v[84:87], v[206:209], v[20:23]
	v_mfma_f32_16x16x32_bf16 v[16:19], v[92:95], v[206:209], v[16:19]
	v_mfma_f32_16x16x32_bf16 v[4:7], v[84:87], v[228:231], v[4:7]
	v_mfma_f32_16x16x32_bf16 v[0:3], v[92:95], v[228:231], v[0:3]
	v_mfma_f32_16x16x32_bf16 v[32:35], v[84:87], v[186:189], v[32:35]
	v_mfma_f32_16x16x32_bf16 v[36:39], v[92:95], v[186:189], v[36:39]
	v_mfma_f32_16x16x32_bf16 v[40:43], v[84:87], v[198:201], v[40:43]
	v_mfma_f32_16x16x32_bf16 v[44:47], v[92:95], v[198:201], v[44:47]
	s_barrier
	s_add_i32 s62, 0, 0x18000
	s_add_i32 s63, 0, 0x1c000
	v_add_u32_e32 v84, s62, v221
	v_add_u32_e32 v96, s63, v221
	ds_read_b128 v[52:55], v84
	ds_read_b128 v[64:67], v84 offset:1024
	ds_read_b128 v[80:83], v84 offset:2048
	ds_read_b128 v[84:87], v84 offset:3072
	ds_read_b128 v[88:91], v96
	ds_read_b128 v[92:95], v96 offset:1024
	ds_read_b128 v[182:185], v96 offset:2048
	ds_read_b128 v[186:189], v96 offset:3072
	s_add_u32 s48, s48, 0x40000
	s_addc_u32 s49, s49, 0
	s_mov_b32 m0, s72
	v_lshl_add_u64 v[232:233], s[48:49], 0, v[160:161]
	ds_read_b128 v[96:99], v225 offset:32768
	ds_read_b128 v[100:103], v225 offset:33792
	ds_read_b128 v[190:193], v225 offset:34816
	ds_read_b128 v[198:201], v225 offset:35840
	ds_read_b128 v[202:205], v225 offset:36864
	ds_read_b128 v[206:209], v225 offset:37888
	ds_read_b128 v[210:213], v225 offset:38912
	ds_read_b128 v[228:231], v225 offset:39936
	global_load_lds_dwordx4 v[232:233], off
	v_lshl_add_u64 v[232:233], s[48:49], 0, v[164:165]
	s_mov_b32 m0, s73
	s_nop 0
	global_load_lds_dwordx4 v[232:233], off
	s_waitcnt vmcnt(8)
	s_waitcnt lgkmcnt(0)
	s_barrier
	s_waitcnt lgkmcnt(0)
	v_mfma_f32_16x16x32_bf16 v[68:71], v[52:55], v[96:99], v[68:71]
	v_mfma_f32_16x16x32_bf16 v[60:63], v[80:83], v[96:99], v[60:63]
	v_mfma_f32_16x16x32_bf16 v[156:159], v[52:55], v[190:193], v[156:159]
	v_mfma_f32_16x16x32_bf16 v[152:155], v[80:83], v[190:193], v[152:155]
	v_mfma_f32_16x16x32_bf16 v[140:143], v[52:55], v[202:205], v[140:143]
	v_mfma_f32_16x16x32_bf16 v[136:139], v[80:83], v[202:205], v[136:139]
	v_mfma_f32_16x16x32_bf16 v[124:127], v[52:55], v[210:213], v[124:127]
	v_mfma_f32_16x16x32_bf16 v[120:123], v[80:83], v[210:213], v[120:123]
	v_mfma_f32_16x16x32_bf16 v[68:71], v[64:67], v[100:103], v[68:71]
	v_mfma_f32_16x16x32_bf16 v[60:63], v[84:87], v[100:103], v[60:63]
	v_mfma_f32_16x16x32_bf16 v[156:159], v[64:67], v[198:201], v[156:159]
	v_mfma_f32_16x16x32_bf16 v[152:155], v[84:87], v[198:201], v[152:155]
	v_mfma_f32_16x16x32_bf16 v[140:143], v[64:67], v[206:209], v[140:143]
	v_mfma_f32_16x16x32_bf16 v[136:139], v[84:87], v[206:209], v[136:139]
	v_mfma_f32_16x16x32_bf16 v[124:127], v[64:67], v[228:231], v[124:127]
	v_mfma_f32_16x16x32_bf16 v[120:123], v[84:87], v[228:231], v[120:123]
	v_mfma_f32_16x16x32_bf16 v[56:59], v[88:91], v[96:99], v[56:59]
	v_mfma_f32_16x16x32_bf16 v[48:51], v[182:185], v[96:99], v[48:51]
	v_mfma_f32_16x16x32_bf16 v[96:99], v[88:91], v[190:193], v[148:151]
	v_mfma_f32_16x16x32_bf16 v[148:151], v[92:95], v[198:201], v[96:99]
	v_mfma_f32_16x16x32_bf16 v[96:99], v[182:185], v[190:193], v[144:147]
	v_mfma_f32_16x16x32_bf16 v[144:147], v[186:189], v[198:201], v[96:99]
	v_mfma_f32_16x16x32_bf16 v[96:99], v[88:91], v[202:205], v[132:135]
	v_mfma_f32_16x16x32_bf16 v[132:135], v[92:95], v[206:209], v[96:99]
	v_mfma_f32_16x16x32_bf16 v[96:99], v[182:185], v[202:205], v[128:131]
	v_mfma_f32_16x16x32_bf16 v[128:131], v[186:189], v[206:209], v[96:99]
	v_mfma_f32_16x16x32_bf16 v[96:99], v[88:91], v[210:213], v[116:119]
	v_mfma_f32_16x16x32_bf16 v[116:119], v[92:95], v[228:231], v[96:99]
	v_mfma_f32_16x16x32_bf16 v[96:99], v[182:185], v[210:213], v[112:115]
	v_mfma_f32_16x16x32_bf16 v[56:59], v[92:95], v[100:103], v[56:59]
	v_mfma_f32_16x16x32_bf16 v[48:51], v[186:189], v[100:103], v[48:51]
	v_mfma_f32_16x16x32_bf16 v[112:115], v[186:189], v[228:231], v[96:99]
	s_barrier
	s_add_i32 s48, s62, s69
	v_lshl_add_u64 v[100:101], v[194:195], 0, s[12:13]
	s_mov_b32 m0, s48
	ds_read_b128 v[96:99], v225 offset:49152
	ds_read_b128 v[190:193], v225 offset:50176
	ds_read_b128 v[198:201], v225 offset:51200
	ds_read_b128 v[202:205], v225 offset:52224
	ds_read_b128 v[206:209], v225 offset:53248
	ds_read_b128 v[210:213], v225 offset:54272
	ds_read_b128 v[228:231], v225 offset:55296
	ds_read_b128 v[232:235], v225 offset:56320
	global_load_lds_dwordx4 v[100:101], off
	s_add_i32 m0, s48, 0x2000
	s_add_u32 s46, s46, 0x40080
	v_lshl_add_u64 v[100:101], v[236:237], 0, s[12:13]
	s_addc_u32 s47, s47, 0
	s_add_i32 s48, s63, s69
	global_load_lds_dwordx4 v[100:101], off
	v_lshl_add_u64 v[100:101], s[46:47], 0, v[162:163]
	s_mov_b32 m0, s48
	s_nop 0
	global_load_lds_dwordx4 v[100:101], off
	v_lshl_add_u64 v[100:101], s[46:47], 0, v[166:167]
	s_add_i32 m0, s48, 0x2000
	s_nop 0
	global_load_lds_dwordx4 v[100:101], off
	v_lshl_add_u64 v[100:101], v[238:239], 0, s[12:13]
	s_mov_b32 m0, s76
	s_nop 0
	global_load_lds_dwordx4 v[100:101], off
	v_lshl_add_u64 v[100:101], v[240:241], 0, s[12:13]
	s_mov_b32 m0, s77
	s_nop 0
	global_load_lds_dwordx4 v[100:101], off
	s_waitcnt vmcnt(8)
	s_waitcnt lgkmcnt(0)
	s_barrier
	s_waitcnt lgkmcnt(0)
	v_mfma_f32_16x16x32_bf16 v[100:103], v[52:55], v[96:99], v[108:111]
	v_mfma_f32_16x16x32_bf16 v[108:111], v[64:67], v[190:193], v[100:103]
	v_mfma_f32_16x16x32_bf16 v[100:103], v[80:83], v[96:99], v[104:107]
	v_mfma_f32_16x16x32_bf16 v[76:79], v[52:55], v[198:201], v[76:79]
	v_mfma_f32_16x16x32_bf16 v[72:75], v[80:83], v[198:201], v[72:75]
	v_mfma_f32_16x16x32_bf16 v[28:31], v[52:55], v[206:209], v[28:31]
	v_mfma_f32_16x16x32_bf16 v[24:27], v[80:83], v[206:209], v[24:27]
	v_mfma_f32_16x16x32_bf16 v[12:15], v[52:55], v[228:231], v[12:15]
	v_mfma_f32_16x16x32_bf16 v[8:11], v[80:83], v[228:231], v[8:11]
	v_mfma_f32_16x16x32_bf16 v[104:107], v[84:87], v[190:193], v[100:103]
	v_mfma_f32_16x16x32_bf16 v[76:79], v[64:67], v[202:205], v[76:79]
	v_mfma_f32_16x16x32_bf16 v[72:75], v[84:87], v[202:205], v[72:75]
	v_mfma_f32_16x16x32_bf16 v[28:31], v[64:67], v[210:213], v[28:31]
	v_mfma_f32_16x16x32_bf16 v[24:27], v[84:87], v[210:213], v[24:27]
	v_mfma_f32_16x16x32_bf16 v[12:15], v[64:67], v[232:235], v[12:15]
	v_mfma_f32_16x16x32_bf16 v[8:11], v[84:87], v[232:235], v[8:11]
	v_mfma_f32_16x16x32_bf16 v[32:35], v[88:91], v[96:99], v[32:35]
	v_mfma_f32_16x16x32_bf16 v[100:103], v[92:95], v[190:193], v[32:35]
	v_mfma_f32_16x16x32_bf16 v[32:35], v[182:185], v[96:99], v[36:39]
	v_mfma_f32_16x16x32_bf16 v[96:99], v[186:189], v[190:193], v[32:35]
	v_mfma_f32_16x16x32_bf16 v[32:35], v[88:91], v[198:201], v[40:43]
	v_mfma_f32_16x16x32_bf16 v[64:67], v[92:95], v[202:205], v[32:35]
	v_mfma_f32_16x16x32_bf16 v[32:35], v[182:185], v[198:201], v[44:47]
	v_mfma_f32_16x16x32_bf16 v[20:23], v[88:91], v[206:209], v[20:23]
	v_mfma_f32_16x16x32_bf16 v[16:19], v[182:185], v[206:209], v[16:19]
	v_mfma_f32_16x16x32_bf16 v[4:7], v[88:91], v[228:231], v[4:7]
	v_mfma_f32_16x16x32_bf16 v[0:3], v[182:185], v[228:231], v[0:3]
	v_mfma_f32_16x16x32_bf16 v[52:55], v[186:189], v[202:205], v[32:35]
	v_mfma_f32_16x16x32_bf16 v[20:23], v[92:95], v[210:213], v[20:23]
	v_mfma_f32_16x16x32_bf16 v[16:19], v[186:189], v[210:213], v[16:19]
	v_mfma_f32_16x16x32_bf16 v[4:7], v[92:95], v[232:235], v[4:7]
	v_mfma_f32_16x16x32_bf16 v[0:3], v[186:189], v[232:235], v[0:3]
	s_barrier
	s_add_i32 s84, s84, 2
	s_add_u32 s4, s4, 0x100
	s_addc_u32 s5, s5, 0
	s_add_u32 s64, s64, 0x100
	s_addc_u32 s65, s65, 0
	s_cmp_gt_u32 s84, 13
	s_cbranch_scc0 .LBB0_1053
	s_and_b64 vcc, exec, s[14:15]
	s_cbranch_vccz .LBB0_1056
	s_barrier

.LBB0_1357:
	ds_read_b128 v[152:155], v147
	ds_read_b128 v[156:159], v147 offset:1024
	ds_read_b128 v[168:171], v147 offset:2048
	ds_read_b128 v[172:175], v147 offset:3072
	ds_read_b128 v[176:179], v148
	ds_read_b128 v[180:183], v148 offset:1024
	ds_read_b128 v[184:187], v148 offset:2048
	ds_read_b128 v[188:191], v148 offset:3072
	s_add_u32 s26, s24, 0xfffc0080
	s_addc_u32 s27, s25, -1
	s_cmp_eq_u32 s76, 12
	s_cselect_b32 s29, s15, s27
	s_cselect_b32 s28, s72, s26
	s_cselect_b32 s27, s13, s75
	s_cselect_b32 s26, s73, s74
	v_lshl_add_u64 v[138:139], s[24:25], 0, v[130:131]
	s_add_i32 m0, s23, 0xc000
	ds_read_b128 v[192:195], v149
	ds_read_b128 v[198:201], v149 offset:1024
	ds_read_b128 v[202:205], v149 offset:2048
	ds_read_b128 v[206:209], v149 offset:3072
	ds_read_b128 v[210:213], v149 offset:4096
	ds_read_b128 v[214:217], v149 offset:5120
	ds_read_b128 v[218:221], v149 offset:6144
	ds_read_b128 v[226:229], v149 offset:7168
	global_load_lds_dwordx4 v[138:139], off
	v_lshl_add_u64 v[138:139], s[24:25], 0, v[132:133]
	s_add_i32 m0, s23, 0xe000
	s_nop 0
	global_load_lds_dwordx4 v[138:139], off
	s_waitcnt vmcnt(8)
	s_waitcnt lgkmcnt(0)
	s_barrier
	s_waitcnt lgkmcnt(0)
	v_mfma_f32_16x16x32_bf16 v[124:127], v[152:155], v[192:195], v[124:127]
	v_mfma_f32_16x16x32_bf16 v[120:123], v[168:171], v[192:195], v[120:123]
	v_mfma_f32_16x16x32_bf16 v[108:111], v[152:155], v[202:205], v[108:111]
	v_mfma_f32_16x16x32_bf16 v[104:107], v[168:171], v[202:205], v[104:107]
	v_mfma_f32_16x16x32_bf16 v[92:95], v[152:155], v[210:213], v[92:95]
	v_mfma_f32_16x16x32_bf16 v[88:91], v[168:171], v[210:213], v[88:91]
	v_mfma_f32_16x16x32_bf16 v[76:79], v[152:155], v[218:221], v[76:79]
	v_mfma_f32_16x16x32_bf16 v[72:75], v[168:171], v[218:221], v[72:75]
	v_mfma_f32_16x16x32_bf16 v[124:127], v[156:159], v[198:201], v[124:127]
	v_mfma_f32_16x16x32_bf16 v[120:123], v[172:175], v[198:201], v[120:123]
	v_mfma_f32_16x16x32_bf16 v[108:111], v[156:159], v[206:209], v[108:111]
	v_mfma_f32_16x16x32_bf16 v[104:107], v[172:175], v[206:209], v[104:107]
	v_mfma_f32_16x16x32_bf16 v[92:95], v[156:159], v[214:217], v[92:95]
	v_mfma_f32_16x16x32_bf16 v[88:91], v[172:175], v[214:217], v[88:91]
	v_mfma_f32_16x16x32_bf16 v[76:79], v[156:159], v[226:229], v[76:79]
	v_mfma_f32_16x16x32_bf16 v[72:75], v[172:175], v[226:229], v[72:75]
	v_mfma_f32_16x16x32_bf16 v[116:119], v[176:179], v[192:195], v[116:119]
	v_mfma_f32_16x16x32_bf16 v[112:115], v[184:187], v[192:195], v[112:115]
	v_mfma_f32_16x16x32_bf16 v[100:103], v[176:179], v[202:205], v[100:103]
	v_mfma_f32_16x16x32_bf16 v[96:99], v[184:187], v[202:205], v[96:99]
	v_mfma_f32_16x16x32_bf16 v[84:87], v[176:179], v[210:213], v[84:87]
	v_mfma_f32_16x16x32_bf16 v[80:83], v[184:187], v[210:213], v[80:83]
	v_mfma_f32_16x16x32_bf16 v[68:71], v[176:179], v[218:221], v[68:71]
	v_mfma_f32_16x16x32_bf16 v[64:67], v[184:187], v[218:221], v[64:67]
	v_mfma_f32_16x16x32_bf16 v[116:119], v[180:183], v[198:201], v[116:119]
	v_mfma_f32_16x16x32_bf16 v[112:115], v[188:191], v[198:201], v[112:115]
	v_mfma_f32_16x16x32_bf16 v[100:103], v[180:183], v[206:209], v[100:103]
	v_mfma_f32_16x16x32_bf16 v[96:99], v[188:191], v[206:209], v[96:99]
	v_mfma_f32_16x16x32_bf16 v[84:87], v[180:183], v[214:217], v[84:87]
	v_mfma_f32_16x16x32_bf16 v[80:83], v[188:191], v[214:217], v[80:83]
	v_mfma_f32_16x16x32_bf16 v[68:71], v[180:183], v[226:229], v[68:71]
	v_mfma_f32_16x16x32_bf16 v[64:67], v[188:191], v[226:229], v[64:67]
	s_barrier
	s_add_i32 s62, s68, s46
	v_lshl_add_u64 v[138:139], s[26:27], 0, v[162:163]
	s_mov_b32 m0, s62
	ds_read_b128 v[192:195], v149 offset:16384
	ds_read_b128 v[198:201], v149 offset:17408
	ds_read_b128 v[202:205], v149 offset:18432
	ds_read_b128 v[206:209], v149 offset:19456
	ds_read_b128 v[210:213], v149 offset:20480
	ds_read_b128 v[214:217], v149 offset:21504
	ds_read_b128 v[218:221], v149 offset:22528
	ds_read_b128 v[226:229], v149 offset:23552
	global_load_lds_dwordx4 v[138:139], off
	s_add_i32 m0, s62, 0x2000
	s_add_u32 s78, s26, 0x40000
	v_lshl_add_u64 v[222:223], s[26:27], 0, v[166:167]
	s_addc_u32 s79, s27, 0
	s_add_i32 s62, s69, s46
	global_load_lds_dwordx4 v[222:223], off
	v_lshl_add_u64 v[230:231], s[78:79], 0, v[162:163]
	s_mov_b32 m0, s62
	v_lshl_add_u64 v[232:233], s[28:29], 0, v[164:165]
	global_load_lds_dwordx4 v[230:231], off
	v_lshl_add_u64 v[230:231], s[78:79], 0, v[166:167]
	s_add_i32 m0, s62, 0x2000
	s_nop 0
	global_load_lds_dwordx4 v[230:231], off
	v_lshl_add_u64 v[230:231], s[28:29], 0, v[160:161]
	s_mov_b32 m0, s23
	s_nop 0
	global_load_lds_dwordx4 v[230:231], off
	s_mov_b32 m0, s49
	s_nop 0
	global_load_lds_dwordx4 v[232:233], off
	s_waitcnt vmcnt(8)
	s_waitcnt lgkmcnt(0)
	s_barrier
	s_waitcnt lgkmcnt(0)
	v_mfma_f32_16x16x32_bf16 v[60:63], v[152:155], v[192:195], v[60:63]
	v_mfma_f32_16x16x32_bf16 v[56:59], v[168:171], v[192:195], v[56:59]
	v_mfma_f32_16x16x32_bf16 v[44:47], v[152:155], v[202:205], v[44:47]
	v_mfma_f32_16x16x32_bf16 v[40:43], v[168:171], v[202:205], v[40:43]
	v_mfma_f32_16x16x32_bf16 v[28:31], v[152:155], v[210:213], v[28:31]
	v_mfma_f32_16x16x32_bf16 v[24:27], v[168:171], v[210:213], v[24:27]
	v_mfma_f32_16x16x32_bf16 v[12:15], v[152:155], v[218:221], v[12:15]
	v_mfma_f32_16x16x32_bf16 v[8:11], v[168:171], v[218:221], v[8:11]
	v_mfma_f32_16x16x32_bf16 v[60:63], v[156:159], v[198:201], v[60:63]
	v_mfma_f32_16x16x32_bf16 v[56:59], v[172:175], v[198:201], v[56:59]
	v_mfma_f32_16x16x32_bf16 v[44:47], v[156:159], v[206:209], v[44:47]
	v_mfma_f32_16x16x32_bf16 v[40:43], v[172:175], v[206:209], v[40:43]
	v_mfma_f32_16x16x32_bf16 v[28:31], v[156:159], v[214:217], v[28:31]
	v_mfma_f32_16x16x32_bf16 v[24:27], v[172:175], v[214:217], v[24:27]
	v_mfma_f32_16x16x32_bf16 v[12:15], v[156:159], v[226:229], v[12:15]
	v_mfma_f32_16x16x32_bf16 v[8:11], v[172:175], v[226:229], v[8:11]
	v_mfma_f32_16x16x32_bf16 v[52:55], v[176:179], v[192:195], v[52:55]
	v_mfma_f32_16x16x32_bf16 v[48:51], v[184:187], v[192:195], v[48:51]
	v_mfma_f32_16x16x32_bf16 v[36:39], v[176:179], v[202:205], v[36:39]
	v_mfma_f32_16x16x32_bf16 v[32:35], v[184:187], v[202:205], v[32:35]
	v_mfma_f32_16x16x32_bf16 v[20:23], v[176:179], v[210:213], v[20:23]
	v_mfma_f32_16x16x32_bf16 v[16:19], v[184:187], v[210:213], v[16:19]
	v_mfma_f32_16x16x32_bf16 v[4:7], v[176:179], v[218:221], v[4:7]
	v_mfma_f32_16x16x32_bf16 v[0:3], v[184:187], v[218:221], v[0:3]
	v_mfma_f32_16x16x32_bf16 v[52:55], v[180:183], v[198:201], v[52:55]
	v_mfma_f32_16x16x32_bf16 v[48:51], v[188:191], v[198:201], v[48:51]
	v_mfma_f32_16x16x32_bf16 v[36:39], v[180:183], v[206:209], v[36:39]
	v_mfma_f32_16x16x32_bf16 v[32:35], v[188:191], v[206:209], v[32:35]
	v_mfma_f32_16x16x32_bf16 v[20:23], v[180:183], v[214:217], v[20:23]
	v_mfma_f32_16x16x32_bf16 v[16:19], v[188:191], v[214:217], v[16:19]
	v_mfma_f32_16x16x32_bf16 v[4:7], v[180:183], v[226:229], v[4:7]
	v_mfma_f32_16x16x32_bf16 v[0:3], v[188:191], v[226:229], v[0:3]
	s_barrier
	s_add_i32 s62, 0, 0x18000
	v_add_u32_e32 v140, s62, v142
	s_add_i32 s63, 0, 0x1c000
	ds_read_b128 v[152:155], v140
	ds_read_b128 v[156:159], v140 offset:1024
	ds_read_b128 v[168:171], v140 offset:2048
	ds_read_b128 v[172:175], v140 offset:3072
	v_add_u32_e32 v140, s63, v142
	ds_read_b128 v[176:179], v140
	ds_read_b128 v[180:183], v140 offset:1024
	ds_read_b128 v[184:187], v140 offset:2048
	ds_read_b128 v[188:191], v140 offset:3072
	s_add_u32 s28, s28, 0x40000
	s_addc_u32 s29, s29, 0
	s_mov_b32 m0, s50
	v_lshl_add_u64 v[234:235], s[28:29], 0, v[160:161]
	ds_read_b128 v[192:195], v149 offset:32768
	ds_read_b128 v[198:201], v149 offset:33792
	ds_read_b128 v[202:205], v149 offset:34816
	ds_read_b128 v[206:209], v149 offset:35840
	ds_read_b128 v[210:213], v149 offset:36864
	ds_read_b128 v[214:217], v149 offset:37888
	ds_read_b128 v[218:221], v149 offset:38912
	ds_read_b128 v[226:229], v149 offset:39936
	global_load_lds_dwordx4 v[234:235], off
	v_lshl_add_u64 v[234:235], s[28:29], 0, v[164:165]
	s_mov_b32 m0, s51
	s_nop 0
	global_load_lds_dwordx4 v[234:235], off
	s_waitcnt vmcnt(8)
	s_waitcnt lgkmcnt(0)
	s_barrier
	s_waitcnt lgkmcnt(0)
	v_mfma_f32_16x16x32_bf16 v[124:127], v[152:155], v[192:195], v[124:127]
	v_mfma_f32_16x16x32_bf16 v[120:123], v[168:171], v[192:195], v[120:123]
	v_mfma_f32_16x16x32_bf16 v[108:111], v[152:155], v[202:205], v[108:111]
	v_mfma_f32_16x16x32_bf16 v[104:107], v[168:171], v[202:205], v[104:107]
	v_mfma_f32_16x16x32_bf16 v[92:95], v[152:155], v[210:213], v[92:95]
	v_mfma_f32_16x16x32_bf16 v[88:91], v[168:171], v[210:213], v[88:91]
	v_mfma_f32_16x16x32_bf16 v[76:79], v[152:155], v[218:221], v[76:79]
	v_mfma_f32_16x16x32_bf16 v[72:75], v[168:171], v[218:221], v[72:75]
	v_mfma_f32_16x16x32_bf16 v[124:127], v[156:159], v[198:201], v[124:127]
	v_mfma_f32_16x16x32_bf16 v[120:123], v[172:175], v[198:201], v[120:123]
	v_mfma_f32_16x16x32_bf16 v[108:111], v[156:159], v[206:209], v[108:111]
	v_mfma_f32_16x16x32_bf16 v[104:107], v[172:175], v[206:209], v[104:107]
	v_mfma_f32_16x16x32_bf16 v[92:95], v[156:159], v[214:217], v[92:95]
	v_mfma_f32_16x16x32_bf16 v[88:91], v[172:175], v[214:217], v[88:91]
	v_mfma_f32_16x16x32_bf16 v[76:79], v[156:159], v[226:229], v[76:79]
	v_mfma_f32_16x16x32_bf16 v[72:75], v[172:175], v[226:229], v[72:75]
	v_mfma_f32_16x16x32_bf16 v[116:119], v[176:179], v[192:195], v[116:119]
	v_mfma_f32_16x16x32_bf16 v[112:115], v[184:187], v[192:195], v[112:115]
	v_mfma_f32_16x16x32_bf16 v[100:103], v[176:179], v[202:205], v[100:103]
	v_mfma_f32_16x16x32_bf16 v[96:99], v[184:187], v[202:205], v[96:99]
	v_mfma_f32_16x16x32_bf16 v[84:87], v[176:179], v[210:213], v[84:87]
	v_mfma_f32_16x16x32_bf16 v[80:83], v[184:187], v[210:213], v[80:83]
	v_mfma_f32_16x16x32_bf16 v[68:71], v[176:179], v[218:221], v[68:71]
	v_mfma_f32_16x16x32_bf16 v[64:67], v[184:187], v[218:221], v[64:67]
	v_mfma_f32_16x16x32_bf16 v[116:119], v[180:183], v[198:201], v[116:119]
	v_mfma_f32_16x16x32_bf16 v[112:115], v[188:191], v[198:201], v[112:115]
	v_mfma_f32_16x16x32_bf16 v[100:103], v[180:183], v[206:209], v[100:103]
	v_mfma_f32_16x16x32_bf16 v[96:99], v[188:191], v[206:209], v[96:99]
	v_mfma_f32_16x16x32_bf16 v[84:87], v[180:183], v[214:217], v[84:87]
	v_mfma_f32_16x16x32_bf16 v[80:83], v[188:191], v[214:217], v[80:83]
	v_mfma_f32_16x16x32_bf16 v[68:71], v[180:183], v[226:229], v[68:71]
	v_mfma_f32_16x16x32_bf16 v[64:67], v[188:191], v[226:229], v[64:67]
	s_barrier
	s_add_i32 s28, s62, s46
	v_lshl_add_u64 v[138:139], v[138:139], 0, s[4:5]
	s_mov_b32 m0, s28
	ds_read_b128 v[192:195], v149 offset:49152
	ds_read_b128 v[198:201], v149 offset:50176
	ds_read_b128 v[202:205], v149 offset:51200
	ds_read_b128 v[206:209], v149 offset:52224
	ds_read_b128 v[210:213], v149 offset:53248
	ds_read_b128 v[214:217], v149 offset:54272
	ds_read_b128 v[218:221], v149 offset:55296
	ds_read_b128 v[226:229], v149 offset:56320
	global_load_lds_dwordx4 v[138:139], off
	s_add_i32 m0, s28, 0x2000
	s_add_u32 s26, s26, 0x40080
	v_lshl_add_u64 v[138:139], v[222:223], 0, s[4:5]
	s_addc_u32 s27, s27, 0
	s_add_i32 s28, s63, s46
	global_load_lds_dwordx4 v[138:139], off
	v_lshl_add_u64 v[138:139], s[26:27], 0, v[162:163]
	s_mov_b32 m0, s28
	s_nop 0
	global_load_lds_dwordx4 v[138:139], off
	v_lshl_add_u64 v[138:139], s[26:27], 0, v[166:167]
	s_add_i32 m0, s28, 0x2000
	s_nop 0
	global_load_lds_dwordx4 v[138:139], off
	v_lshl_add_u64 v[138:139], v[230:231], 0, s[4:5]
	s_mov_b32 m0, s65
	s_nop 0
	global_load_lds_dwordx4 v[138:139], off
	v_lshl_add_u64 v[138:139], v[232:233], 0, s[4:5]
	s_mov_b32 m0, s66
	s_nop 0
	global_load_lds_dwordx4 v[138:139], off
	s_waitcnt vmcnt(8)
	s_waitcnt lgkmcnt(0)
	s_barrier
	s_waitcnt lgkmcnt(0)
	v_mfma_f32_16x16x32_bf16 v[60:63], v[152:155], v[192:195], v[60:63]
	v_mfma_f32_16x16x32_bf16 v[56:59], v[168:171], v[192:195], v[56:59]
	v_mfma_f32_16x16x32_bf16 v[44:47], v[152:155], v[202:205], v[44:47]
	v_mfma_f32_16x16x32_bf16 v[40:43], v[168:171], v[202:205], v[40:43]
	v_mfma_f32_16x16x32_bf16 v[28:31], v[152:155], v[210:213], v[28:31]
	v_mfma_f32_16x16x32_bf16 v[24:27], v[168:171], v[210:213], v[24:27]
	v_mfma_f32_16x16x32_bf16 v[12:15], v[152:155], v[218:221], v[12:15]
	v_mfma_f32_16x16x32_bf16 v[8:11], v[168:171], v[218:221], v[8:11]
	v_mfma_f32_16x16x32_bf16 v[60:63], v[156:159], v[198:201], v[60:63]
	v_mfma_f32_16x16x32_bf16 v[56:59], v[172:175], v[198:201], v[56:59]
	v_mfma_f32_16x16x32_bf16 v[44:47], v[156:159], v[206:209], v[44:47]
	v_mfma_f32_16x16x32_bf16 v[40:43], v[172:175], v[206:209], v[40:43]
	v_mfma_f32_16x16x32_bf16 v[28:31], v[156:159], v[214:217], v[28:31]
	v_mfma_f32_16x16x32_bf16 v[24:27], v[172:175], v[214:217], v[24:27]
	v_mfma_f32_16x16x32_bf16 v[12:15], v[156:159], v[226:229], v[12:15]
	v_mfma_f32_16x16x32_bf16 v[8:11], v[172:175], v[226:229], v[8:11]
	v_mfma_f32_16x16x32_bf16 v[52:55], v[176:179], v[192:195], v[52:55]
	v_mfma_f32_16x16x32_bf16 v[48:51], v[184:187], v[192:195], v[48:51]
	v_mfma_f32_16x16x32_bf16 v[36:39], v[176:179], v[202:205], v[36:39]
	v_mfma_f32_16x16x32_bf16 v[32:35], v[184:187], v[202:205], v[32:35]
	v_mfma_f32_16x16x32_bf16 v[20:23], v[176:179], v[210:213], v[20:23]
	v_mfma_f32_16x16x32_bf16 v[16:19], v[184:187], v[210:213], v[16:19]
	v_mfma_f32_16x16x32_bf16 v[4:7], v[176:179], v[218:221], v[4:7]
	v_mfma_f32_16x16x32_bf16 v[0:3], v[184:187], v[218:221], v[0:3]
	v_mfma_f32_16x16x32_bf16 v[52:55], v[180:183], v[198:201], v[52:55]
	v_mfma_f32_16x16x32_bf16 v[48:51], v[188:191], v[198:201], v[48:51]
	v_mfma_f32_16x16x32_bf16 v[36:39], v[180:183], v[206:209], v[36:39]
	v_mfma_f32_16x16x32_bf16 v[32:35], v[188:191], v[206:209], v[32:35]
	v_mfma_f32_16x16x32_bf16 v[20:23], v[180:183], v[214:217], v[20:23]
	v_mfma_f32_16x16x32_bf16 v[16:19], v[188:191], v[214:217], v[16:19]
	v_mfma_f32_16x16x32_bf16 v[4:7], v[180:183], v[226:229], v[4:7]
	v_mfma_f32_16x16x32_bf16 v[0:3], v[188:191], v[226:229], v[0:3]
	s_barrier
	s_add_i32 s76, s76, 2
	s_add_u32 s24, s24, 0x100
	s_addc_u32 s25, s25, 0
	s_add_u32 s74, s74, 0x100
	s_addc_u32 s75, s75, 0
	s_cmp_gt_u32 s76, 13
	s_cbranch_scc0 .LBB0_1357
	s_and_b64 vcc, exec, s[10:11]
	s_cbranch_vccz .LBB0_1360
	s_barrier

.LBB0_1438:
	ds_read_b128 v[128:131], v189
	ds_read_b128 v[132:135], v189 offset:1024
	ds_read_b128 v[136:139], v189 offset:2048
	ds_read_b128 v[140:143], v189 offset:3072
	ds_read_b128 v[144:147], v190
	ds_read_b128 v[148:151], v190 offset:1024
	ds_read_b128 v[168:171], v190 offset:2048
	ds_read_b128 v[172:175], v190 offset:3072
	s_add_u32 s24, s22, 0xfff50080
	s_addc_u32 s25, s23, -1
	s_cmp_eq_u32 s74, 40
	s_cselect_b32 s27, s5, s25
	s_cselect_b32 s26, s4, s24
	s_cselect_b32 s25, s19, s73
	s_cselect_b32 s24, s18, s72
	v_lshl_add_u64 v[184:185], s[22:23], 0, v[160:161]
	s_add_i32 m0, s45, 0xc000
	ds_read_b128 v[176:179], v191
	ds_read_b128 v[180:183], v191 offset:1024
	ds_read_b128 v[198:201], v191 offset:2048
	ds_read_b128 v[202:205], v191 offset:3072
	ds_read_b128 v[206:209], v191 offset:4096
	ds_read_b128 v[210:213], v191 offset:5120
	ds_read_b128 v[214:217], v191 offset:6144
	ds_read_b128 v[218:221], v191 offset:7168
	global_load_lds_dwordx4 v[184:185], off
	v_lshl_add_u64 v[184:185], s[22:23], 0, v[162:163]
	s_add_i32 m0, s45, 0xe000
	s_nop 0
	global_load_lds_dwordx4 v[184:185], off
	s_waitcnt vmcnt(8)
	s_waitcnt lgkmcnt(0)
	s_barrier
	s_waitcnt lgkmcnt(0)
	v_mfma_f32_16x16x32_bf16 v[124:127], v[128:131], v[176:179], v[124:127]
	v_mfma_f32_16x16x32_bf16 v[120:123], v[136:139], v[176:179], v[120:123]
	v_mfma_f32_16x16x32_bf16 v[108:111], v[128:131], v[198:201], v[108:111]
	v_mfma_f32_16x16x32_bf16 v[104:107], v[136:139], v[198:201], v[104:107]
	v_mfma_f32_16x16x32_bf16 v[92:95], v[128:131], v[206:209], v[92:95]
	v_mfma_f32_16x16x32_bf16 v[88:91], v[136:139], v[206:209], v[88:91]
	v_mfma_f32_16x16x32_bf16 v[76:79], v[128:131], v[214:217], v[76:79]
	v_mfma_f32_16x16x32_bf16 v[72:75], v[136:139], v[214:217], v[72:75]
	v_mfma_f32_16x16x32_bf16 v[124:127], v[132:135], v[180:183], v[124:127]
	v_mfma_f32_16x16x32_bf16 v[120:123], v[140:143], v[180:183], v[120:123]
	v_mfma_f32_16x16x32_bf16 v[108:111], v[132:135], v[202:205], v[108:111]
	v_mfma_f32_16x16x32_bf16 v[104:107], v[140:143], v[202:205], v[104:107]
	v_mfma_f32_16x16x32_bf16 v[92:95], v[132:135], v[210:213], v[92:95]
	v_mfma_f32_16x16x32_bf16 v[88:91], v[140:143], v[210:213], v[88:91]
	v_mfma_f32_16x16x32_bf16 v[76:79], v[132:135], v[218:221], v[76:79]
	v_mfma_f32_16x16x32_bf16 v[72:75], v[140:143], v[218:221], v[72:75]
	v_mfma_f32_16x16x32_bf16 v[116:119], v[144:147], v[176:179], v[116:119]
	v_mfma_f32_16x16x32_bf16 v[112:115], v[168:171], v[176:179], v[112:115]
	v_mfma_f32_16x16x32_bf16 v[100:103], v[144:147], v[198:201], v[100:103]
	v_mfma_f32_16x16x32_bf16 v[96:99], v[168:171], v[198:201], v[96:99]
	v_mfma_f32_16x16x32_bf16 v[84:87], v[144:147], v[206:209], v[84:87]
	v_mfma_f32_16x16x32_bf16 v[80:83], v[168:171], v[206:209], v[80:83]
	v_mfma_f32_16x16x32_bf16 v[68:71], v[144:147], v[214:217], v[68:71]
	v_mfma_f32_16x16x32_bf16 v[64:67], v[168:171], v[214:217], v[64:67]
	v_mfma_f32_16x16x32_bf16 v[116:119], v[148:151], v[180:183], v[116:119]
	v_mfma_f32_16x16x32_bf16 v[112:115], v[172:175], v[180:183], v[112:115]
	v_mfma_f32_16x16x32_bf16 v[100:103], v[148:151], v[202:205], v[100:103]
	v_mfma_f32_16x16x32_bf16 v[96:99], v[172:175], v[202:205], v[96:99]
	v_mfma_f32_16x16x32_bf16 v[84:87], v[148:151], v[210:213], v[84:87]
	v_mfma_f32_16x16x32_bf16 v[80:83], v[172:175], v[210:213], v[80:83]
	v_mfma_f32_16x16x32_bf16 v[68:71], v[148:151], v[218:221], v[68:71]
	v_mfma_f32_16x16x32_bf16 v[64:67], v[172:175], v[218:221], v[64:67]
	s_barrier
	s_add_i32 s62, s66, s44
	v_lshl_add_u64 v[184:185], s[24:25], 0, v[154:155]
	s_mov_b32 m0, s62
	ds_read_b128 v[176:179], v191 offset:16384
	ds_read_b128 v[180:183], v191 offset:17408
	ds_read_b128 v[198:201], v191 offset:18432
	ds_read_b128 v[202:205], v191 offset:19456
	ds_read_b128 v[206:209], v191 offset:20480
	ds_read_b128 v[210:213], v191 offset:21504
	ds_read_b128 v[214:217], v191 offset:22528
	ds_read_b128 v[218:221], v191 offset:23552
	global_load_lds_dwordx4 v[184:185], off
	s_add_i32 m0, s62, 0x2000
	s_add_u32 s76, s24, 0xb0000
	v_lshl_add_u64 v[194:195], s[24:25], 0, v[158:159]
	s_addc_u32 s77, s25, 0
	s_add_i32 s62, s67, s44
	global_load_lds_dwordx4 v[194:195], off
	v_lshl_add_u64 v[222:223], s[76:77], 0, v[154:155]
	s_mov_b32 m0, s62
	v_lshl_add_u64 v[226:227], s[26:27], 0, v[156:157]
	global_load_lds_dwordx4 v[222:223], off
	v_lshl_add_u64 v[222:223], s[76:77], 0, v[158:159]
	s_add_i32 m0, s62, 0x2000
	s_nop 0
	global_load_lds_dwordx4 v[222:223], off
	v_lshl_add_u64 v[222:223], s[26:27], 0, v[152:153]
	s_mov_b32 m0, s45
	s_nop 0
	global_load_lds_dwordx4 v[222:223], off
	s_mov_b32 m0, s46
	s_nop 0
	global_load_lds_dwordx4 v[226:227], off
	s_waitcnt vmcnt(8)
	s_waitcnt lgkmcnt(0)
	s_barrier
	s_waitcnt lgkmcnt(0)
	v_mfma_f32_16x16x32_bf16 v[60:63], v[128:131], v[176:179], v[60:63]
	v_mfma_f32_16x16x32_bf16 v[56:59], v[136:139], v[176:179], v[56:59]
	v_mfma_f32_16x16x32_bf16 v[44:47], v[128:131], v[198:201], v[44:47]
	v_mfma_f32_16x16x32_bf16 v[40:43], v[136:139], v[198:201], v[40:43]
	v_mfma_f32_16x16x32_bf16 v[28:31], v[128:131], v[206:209], v[28:31]
	v_mfma_f32_16x16x32_bf16 v[24:27], v[136:139], v[206:209], v[24:27]
	v_mfma_f32_16x16x32_bf16 v[12:15], v[128:131], v[214:217], v[12:15]
	v_mfma_f32_16x16x32_bf16 v[8:11], v[136:139], v[214:217], v[8:11]
	v_mfma_f32_16x16x32_bf16 v[60:63], v[132:135], v[180:183], v[60:63]
	v_mfma_f32_16x16x32_bf16 v[56:59], v[140:143], v[180:183], v[56:59]
	v_mfma_f32_16x16x32_bf16 v[44:47], v[132:135], v[202:205], v[44:47]
	v_mfma_f32_16x16x32_bf16 v[40:43], v[140:143], v[202:205], v[40:43]
	v_mfma_f32_16x16x32_bf16 v[28:31], v[132:135], v[210:213], v[28:31]
	v_mfma_f32_16x16x32_bf16 v[24:27], v[140:143], v[210:213], v[24:27]
	v_mfma_f32_16x16x32_bf16 v[12:15], v[132:135], v[218:221], v[12:15]
	v_mfma_f32_16x16x32_bf16 v[8:11], v[140:143], v[218:221], v[8:11]
	v_mfma_f32_16x16x32_bf16 v[52:55], v[144:147], v[176:179], v[52:55]
	v_mfma_f32_16x16x32_bf16 v[48:51], v[168:171], v[176:179], v[48:51]
	v_mfma_f32_16x16x32_bf16 v[36:39], v[144:147], v[198:201], v[36:39]
	v_mfma_f32_16x16x32_bf16 v[32:35], v[168:171], v[198:201], v[32:35]
	v_mfma_f32_16x16x32_bf16 v[20:23], v[144:147], v[206:209], v[20:23]
	v_mfma_f32_16x16x32_bf16 v[16:19], v[168:171], v[206:209], v[16:19]
	v_mfma_f32_16x16x32_bf16 v[4:7], v[144:147], v[214:217], v[4:7]
	v_mfma_f32_16x16x32_bf16 v[0:3], v[168:171], v[214:217], v[0:3]
	v_mfma_f32_16x16x32_bf16 v[52:55], v[148:151], v[180:183], v[52:55]
	v_mfma_f32_16x16x32_bf16 v[48:51], v[172:175], v[180:183], v[48:51]
	v_mfma_f32_16x16x32_bf16 v[36:39], v[148:151], v[202:205], v[36:39]
	v_mfma_f32_16x16x32_bf16 v[32:35], v[172:175], v[202:205], v[32:35]
	v_mfma_f32_16x16x32_bf16 v[20:23], v[148:151], v[210:213], v[20:23]
	v_mfma_f32_16x16x32_bf16 v[16:19], v[172:175], v[210:213], v[16:19]
	v_mfma_f32_16x16x32_bf16 v[4:7], v[148:151], v[218:221], v[4:7]
	v_mfma_f32_16x16x32_bf16 v[0:3], v[172:175], v[218:221], v[0:3]
	s_barrier
	s_add_i32 s62, 0, 0x18000
	s_add_i32 s63, 0, 0x1c000
	v_add_u32_e32 v140, s62, v187
	v_add_u32_e32 v172, s63, v187
	ds_read_b128 v[128:131], v140
	ds_read_b128 v[132:135], v140 offset:1024
	ds_read_b128 v[136:139], v140 offset:2048
	ds_read_b128 v[140:143], v140 offset:3072
	ds_read_b128 v[144:147], v172
	ds_read_b128 v[148:151], v172 offset:1024
	ds_read_b128 v[168:171], v172 offset:2048
	ds_read_b128 v[172:175], v172 offset:3072
	s_add_u32 s26, s26, 0xb0000
	s_addc_u32 s27, s27, 0
	s_mov_b32 m0, s47
	v_lshl_add_u64 v[228:229], s[26:27], 0, v[152:153]
	ds_read_b128 v[176:179], v191 offset:32768
	ds_read_b128 v[180:183], v191 offset:33792
	ds_read_b128 v[198:201], v191 offset:34816
	ds_read_b128 v[202:205], v191 offset:35840
	ds_read_b128 v[206:209], v191 offset:36864
	ds_read_b128 v[210:213], v191 offset:37888
	ds_read_b128 v[214:217], v191 offset:38912
	ds_read_b128 v[218:221], v191 offset:39936
	global_load_lds_dwordx4 v[228:229], off
	v_lshl_add_u64 v[228:229], s[26:27], 0, v[156:157]
	s_mov_b32 m0, s48
	s_nop 0
	global_load_lds_dwordx4 v[228:229], off
	s_waitcnt vmcnt(8)
	s_waitcnt lgkmcnt(0)
	s_barrier
	s_waitcnt lgkmcnt(0)
	v_mfma_f32_16x16x32_bf16 v[124:127], v[128:131], v[176:179], v[124:127]
	v_mfma_f32_16x16x32_bf16 v[120:123], v[136:139], v[176:179], v[120:123]
	v_mfma_f32_16x16x32_bf16 v[108:111], v[128:131], v[198:201], v[108:111]
	v_mfma_f32_16x16x32_bf16 v[104:107], v[136:139], v[198:201], v[104:107]
	v_mfma_f32_16x16x32_bf16 v[92:95], v[128:131], v[206:209], v[92:95]
	v_mfma_f32_16x16x32_bf16 v[88:91], v[136:139], v[206:209], v[88:91]
	v_mfma_f32_16x16x32_bf16 v[76:79], v[128:131], v[214:217], v[76:79]
	v_mfma_f32_16x16x32_bf16 v[72:75], v[136:139], v[214:217], v[72:75]
	v_mfma_f32_16x16x32_bf16 v[124:127], v[132:135], v[180:183], v[124:127]
	v_mfma_f32_16x16x32_bf16 v[120:123], v[140:143], v[180:183], v[120:123]
	v_mfma_f32_16x16x32_bf16 v[108:111], v[132:135], v[202:205], v[108:111]
	v_mfma_f32_16x16x32_bf16 v[104:107], v[140:143], v[202:205], v[104:107]
	v_mfma_f32_16x16x32_bf16 v[92:95], v[132:135], v[210:213], v[92:95]
	v_mfma_f32_16x16x32_bf16 v[88:91], v[140:143], v[210:213], v[88:91]
	v_mfma_f32_16x16x32_bf16 v[76:79], v[132:135], v[218:221], v[76:79]
	v_mfma_f32_16x16x32_bf16 v[72:75], v[140:143], v[218:221], v[72:75]
	v_mfma_f32_16x16x32_bf16 v[116:119], v[144:147], v[176:179], v[116:119]
	v_mfma_f32_16x16x32_bf16 v[112:115], v[168:171], v[176:179], v[112:115]
	v_mfma_f32_16x16x32_bf16 v[100:103], v[144:147], v[198:201], v[100:103]
	v_mfma_f32_16x16x32_bf16 v[96:99], v[168:171], v[198:201], v[96:99]
	v_mfma_f32_16x16x32_bf16 v[84:87], v[144:147], v[206:209], v[84:87]
	v_mfma_f32_16x16x32_bf16 v[80:83], v[168:171], v[206:209], v[80:83]
	v_mfma_f32_16x16x32_bf16 v[68:71], v[144:147], v[214:217], v[68:71]
	v_mfma_f32_16x16x32_bf16 v[64:67], v[168:171], v[214:217], v[64:67]
	v_mfma_f32_16x16x32_bf16 v[116:119], v[148:151], v[180:183], v[116:119]
	v_mfma_f32_16x16x32_bf16 v[112:115], v[172:175], v[180:183], v[112:115]
	v_mfma_f32_16x16x32_bf16 v[100:103], v[148:151], v[202:205], v[100:103]
	v_mfma_f32_16x16x32_bf16 v[96:99], v[172:175], v[202:205], v[96:99]
	v_mfma_f32_16x16x32_bf16 v[84:87], v[148:151], v[210:213], v[84:87]
	v_mfma_f32_16x16x32_bf16 v[80:83], v[172:175], v[210:213], v[80:83]
	v_mfma_f32_16x16x32_bf16 v[68:71], v[148:151], v[218:221], v[68:71]
	v_mfma_f32_16x16x32_bf16 v[64:67], v[172:175], v[218:221], v[64:67]
	s_barrier
	s_add_i32 s26, s62, s44
	v_lshl_add_u64 v[184:185], v[184:185], 0, s[14:15]
	s_mov_b32 m0, s26
	ds_read_b128 v[176:179], v191 offset:49152
	ds_read_b128 v[180:183], v191 offset:50176
	ds_read_b128 v[198:201], v191 offset:51200
	ds_read_b128 v[202:205], v191 offset:52224
	ds_read_b128 v[206:209], v191 offset:53248
	ds_read_b128 v[210:213], v191 offset:54272
	ds_read_b128 v[214:217], v191 offset:55296
	ds_read_b128 v[218:221], v191 offset:56320
	global_load_lds_dwordx4 v[184:185], off
	s_add_i32 m0, s26, 0x2000
	s_add_u32 s24, s24, 0xb0080
	v_lshl_add_u64 v[184:185], v[194:195], 0, s[14:15]
	s_addc_u32 s25, s25, 0
	s_add_i32 s26, s63, s44
	global_load_lds_dwordx4 v[184:185], off
	v_lshl_add_u64 v[184:185], s[24:25], 0, v[154:155]
	s_mov_b32 m0, s26
	s_nop 0
	global_load_lds_dwordx4 v[184:185], off
	v_lshl_add_u64 v[184:185], s[24:25], 0, v[158:159]
	s_add_i32 m0, s26, 0x2000
	s_nop 0
	global_load_lds_dwordx4 v[184:185], off
	v_lshl_add_u64 v[184:185], v[222:223], 0, s[14:15]
	s_mov_b32 m0, s50
	s_nop 0
	global_load_lds_dwordx4 v[184:185], off
	v_lshl_add_u64 v[184:185], v[226:227], 0, s[14:15]
	s_mov_b32 m0, s51
	s_nop 0
	global_load_lds_dwordx4 v[184:185], off
	s_waitcnt vmcnt(8)
	s_waitcnt lgkmcnt(0)
	s_barrier
	s_waitcnt lgkmcnt(0)
	v_mfma_f32_16x16x32_bf16 v[60:63], v[128:131], v[176:179], v[60:63]
	v_mfma_f32_16x16x32_bf16 v[56:59], v[136:139], v[176:179], v[56:59]
	v_mfma_f32_16x16x32_bf16 v[44:47], v[128:131], v[198:201], v[44:47]
	v_mfma_f32_16x16x32_bf16 v[40:43], v[136:139], v[198:201], v[40:43]
	v_mfma_f32_16x16x32_bf16 v[28:31], v[128:131], v[206:209], v[28:31]
	v_mfma_f32_16x16x32_bf16 v[24:27], v[136:139], v[206:209], v[24:27]
	v_mfma_f32_16x16x32_bf16 v[12:15], v[128:131], v[214:217], v[12:15]
	v_mfma_f32_16x16x32_bf16 v[8:11], v[136:139], v[214:217], v[8:11]
	v_mfma_f32_16x16x32_bf16 v[60:63], v[132:135], v[180:183], v[60:63]
	v_mfma_f32_16x16x32_bf16 v[56:59], v[140:143], v[180:183], v[56:59]
	v_mfma_f32_16x16x32_bf16 v[44:47], v[132:135], v[202:205], v[44:47]
	v_mfma_f32_16x16x32_bf16 v[40:43], v[140:143], v[202:205], v[40:43]
	v_mfma_f32_16x16x32_bf16 v[28:31], v[132:135], v[210:213], v[28:31]
	v_mfma_f32_16x16x32_bf16 v[24:27], v[140:143], v[210:213], v[24:27]
	v_mfma_f32_16x16x32_bf16 v[12:15], v[132:135], v[218:221], v[12:15]
	v_mfma_f32_16x16x32_bf16 v[8:11], v[140:143], v[218:221], v[8:11]
	v_mfma_f32_16x16x32_bf16 v[52:55], v[144:147], v[176:179], v[52:55]
	v_mfma_f32_16x16x32_bf16 v[48:51], v[168:171], v[176:179], v[48:51]
	v_mfma_f32_16x16x32_bf16 v[36:39], v[144:147], v[198:201], v[36:39]
	v_mfma_f32_16x16x32_bf16 v[32:35], v[168:171], v[198:201], v[32:35]
	v_mfma_f32_16x16x32_bf16 v[20:23], v[144:147], v[206:209], v[20:23]
	v_mfma_f32_16x16x32_bf16 v[16:19], v[168:171], v[206:209], v[16:19]
	v_mfma_f32_16x16x32_bf16 v[4:7], v[144:147], v[214:217], v[4:7]
	v_mfma_f32_16x16x32_bf16 v[0:3], v[168:171], v[214:217], v[0:3]
	v_mfma_f32_16x16x32_bf16 v[52:55], v[148:151], v[180:183], v[52:55]
	v_mfma_f32_16x16x32_bf16 v[48:51], v[172:175], v[180:183], v[48:51]
	v_mfma_f32_16x16x32_bf16 v[36:39], v[148:151], v[202:205], v[36:39]
	v_mfma_f32_16x16x32_bf16 v[32:35], v[172:175], v[202:205], v[32:35]
	v_mfma_f32_16x16x32_bf16 v[20:23], v[148:151], v[210:213], v[20:23]
	v_mfma_f32_16x16x32_bf16 v[16:19], v[172:175], v[210:213], v[16:19]
	v_mfma_f32_16x16x32_bf16 v[4:7], v[148:151], v[218:221], v[4:7]
	v_mfma_f32_16x16x32_bf16 v[0:3], v[172:175], v[218:221], v[0:3]
	s_barrier
	s_add_i32 s74, s74, 2
	s_add_u32 s22, s22, 0x100
	s_addc_u32 s23, s23, 0
	s_add_u32 s72, s72, 0x100
	s_addc_u32 s73, s73, 0
	s_cmp_gt_u32 s74, 41
	s_cbranch_scc0 .LBB0_1438
	s_and_b64 vcc, exec, s[16:17]
	s_cbranch_vccz .LBB0_1441
	s_barrier

.LBB0_1534:
	s_waitcnt vmcnt(0)
	ds_read_b128 v[36:39], v197
	ds_read_b128 v[40:43], v197 offset:1024
	ds_read_b128 v[44:47], v197 offset:2048
	ds_read_b128 v[48:51], v197 offset:3072
	ds_read_b128 v[80:83], v198
	ds_read_b128 v[84:87], v198 offset:1024
	ds_read_b128 v[88:91], v198 offset:2048
	ds_read_b128 v[92:95], v198 offset:3072
	s_add_u32 s28, s4, 0xfffc0080
	s_addc_u32 s29, s5, -1
	s_cmp_eq_u32 s75, 12
	s_cselect_b32 s45, s3, s29
	s_cselect_b32 s44, s19, s28
	s_cselect_b32 s29, s17, s74
	s_cselect_b32 s28, s27, s73
	v_lshl_add_u64 v[226:227], s[4:5], 0, v[172:173]
	s_add_i32 m0, s49, 0xc000
	ds_read_b128 v[180:183], v199
	ds_read_b128 v[184:187], v199 offset:1024
	ds_read_b128 v[188:191], v199 offset:2048
	ds_read_b128 v[204:207], v199 offset:3072
	ds_read_b128 v[208:211], v199 offset:4096
	ds_read_b128 v[212:215], v199 offset:5120
	ds_read_b128 v[216:219], v199 offset:6144
	ds_read_b128 v[220:223], v199 offset:7168
	global_load_lds_dwordx4 v[226:227], off
	v_lshl_add_u64 v[226:227], s[4:5], 0, v[174:175]
	s_add_i32 m0, s49, 0xe000
	s_nop 0
	global_load_lds_dwordx4 v[226:227], off
	s_waitcnt vmcnt(8)
	s_waitcnt lgkmcnt(0)
	s_barrier
	s_waitcnt lgkmcnt(0)
	v_mfma_f32_16x16x32_bf16 v[68:71], v[36:39], v[180:183], v[68:71]
	v_mfma_f32_16x16x32_bf16 v[64:67], v[44:47], v[180:183], v[64:67]
	v_mfma_f32_16x16x32_bf16 v[156:159], v[36:39], v[188:191], v[156:159]
	v_mfma_f32_16x16x32_bf16 v[152:155], v[44:47], v[188:191], v[152:155]
	v_mfma_f32_16x16x32_bf16 v[140:143], v[36:39], v[208:211], v[140:143]
	v_mfma_f32_16x16x32_bf16 v[136:139], v[44:47], v[208:211], v[136:139]
	v_mfma_f32_16x16x32_bf16 v[124:127], v[36:39], v[216:219], v[124:127]
	v_mfma_f32_16x16x32_bf16 v[120:123], v[44:47], v[216:219], v[120:123]
	v_mfma_f32_16x16x32_bf16 v[68:71], v[40:43], v[184:187], v[68:71]
	v_mfma_f32_16x16x32_bf16 v[64:67], v[48:51], v[184:187], v[64:67]
	v_mfma_f32_16x16x32_bf16 v[156:159], v[40:43], v[204:207], v[156:159]
	v_mfma_f32_16x16x32_bf16 v[152:155], v[48:51], v[204:207], v[152:155]
	v_mfma_f32_16x16x32_bf16 v[140:143], v[40:43], v[212:215], v[140:143]
	v_mfma_f32_16x16x32_bf16 v[136:139], v[48:51], v[212:215], v[136:139]
	v_mfma_f32_16x16x32_bf16 v[124:127], v[40:43], v[220:223], v[124:127]
	v_mfma_f32_16x16x32_bf16 v[120:123], v[48:51], v[220:223], v[120:123]
	v_mfma_f32_16x16x32_bf16 v[56:59], v[80:83], v[180:183], v[56:59]
	v_mfma_f32_16x16x32_bf16 v[52:55], v[88:91], v[180:183], v[52:55]
	v_mfma_f32_16x16x32_bf16 v[148:151], v[80:83], v[188:191], v[148:151]
	v_mfma_f32_16x16x32_bf16 v[144:147], v[88:91], v[188:191], v[144:147]
	v_mfma_f32_16x16x32_bf16 v[132:135], v[80:83], v[208:211], v[132:135]
	v_mfma_f32_16x16x32_bf16 v[128:131], v[88:91], v[208:211], v[128:131]
	v_mfma_f32_16x16x32_bf16 v[116:119], v[80:83], v[216:219], v[116:119]
	v_mfma_f32_16x16x32_bf16 v[112:115], v[88:91], v[216:219], v[112:115]
	v_mfma_f32_16x16x32_bf16 v[56:59], v[84:87], v[184:187], v[56:59]
	v_mfma_f32_16x16x32_bf16 v[52:55], v[92:95], v[184:187], v[52:55]
	v_mfma_f32_16x16x32_bf16 v[148:151], v[84:87], v[204:207], v[148:151]
	v_mfma_f32_16x16x32_bf16 v[144:147], v[92:95], v[204:207], v[144:147]
	v_mfma_f32_16x16x32_bf16 v[132:135], v[84:87], v[212:215], v[132:135]
	v_mfma_f32_16x16x32_bf16 v[128:131], v[92:95], v[212:215], v[128:131]
	v_mfma_f32_16x16x32_bf16 v[116:119], v[84:87], v[220:223], v[116:119]
	v_mfma_f32_16x16x32_bf16 v[112:115], v[92:95], v[220:223], v[112:115]
	s_barrier
	s_add_i32 s62, s71, s48
	v_lshl_add_u64 v[230:231], s[28:29], 0, v[162:163]
	s_mov_b32 m0, s62
	ds_read_b128 v[180:183], v199 offset:16384
	ds_read_b128 v[184:187], v199 offset:17408
	ds_read_b128 v[188:191], v199 offset:18432
	ds_read_b128 v[204:207], v199 offset:19456
	ds_read_b128 v[208:211], v199 offset:20480
	ds_read_b128 v[212:215], v199 offset:21504
	ds_read_b128 v[216:219], v199 offset:22528
	ds_read_b128 v[220:223], v199 offset:23552
	global_load_lds_dwordx4 v[230:231], off
	s_add_i32 m0, s62, 0x2000
	s_add_u32 s76, s28, 0x40000
	v_lshl_add_u64 v[232:233], s[28:29], 0, v[166:167]
	s_addc_u32 s77, s29, 0
	s_add_i32 s62, s72, s48
	global_load_lds_dwordx4 v[232:233], off
	v_lshl_add_u64 v[226:227], s[76:77], 0, v[162:163]
	s_mov_b32 m0, s62
	v_lshl_add_u64 v[234:235], s[44:45], 0, v[160:161]
	global_load_lds_dwordx4 v[226:227], off
	v_lshl_add_u64 v[226:227], s[76:77], 0, v[166:167]
	s_add_i32 m0, s62, 0x2000
	v_lshl_add_u64 v[236:237], s[44:45], 0, v[164:165]
	global_load_lds_dwordx4 v[226:227], off
	s_mov_b32 m0, s49
	s_nop 0
	global_load_lds_dwordx4 v[234:235], off
	s_mov_b32 m0, s50
	s_nop 0
	global_load_lds_dwordx4 v[236:237], off
	s_waitcnt vmcnt(8)
	s_waitcnt lgkmcnt(0)
	s_barrier
	s_waitcnt lgkmcnt(0)
	v_mfma_f32_16x16x32_bf16 v[108:111], v[36:39], v[180:183], v[108:111]
	v_mfma_f32_16x16x32_bf16 v[104:107], v[44:47], v[180:183], v[104:107]
	v_mfma_f32_16x16x32_bf16 v[76:79], v[36:39], v[188:191], v[76:79]
	v_mfma_f32_16x16x32_bf16 v[72:75], v[44:47], v[188:191], v[72:75]
	v_mfma_f32_16x16x32_bf16 v[28:31], v[36:39], v[208:211], v[28:31]
	v_mfma_f32_16x16x32_bf16 v[24:27], v[44:47], v[208:211], v[24:27]
	v_mfma_f32_16x16x32_bf16 v[12:15], v[36:39], v[216:219], v[12:15]
	v_mfma_f32_16x16x32_bf16 v[8:11], v[44:47], v[216:219], v[8:11]
	v_mfma_f32_16x16x32_bf16 v[108:111], v[40:43], v[184:187], v[108:111]
	v_mfma_f32_16x16x32_bf16 v[104:107], v[48:51], v[184:187], v[104:107]
	v_mfma_f32_16x16x32_bf16 v[76:79], v[40:43], v[204:207], v[76:79]
	v_mfma_f32_16x16x32_bf16 v[72:75], v[48:51], v[204:207], v[72:75]
	v_mfma_f32_16x16x32_bf16 v[28:31], v[40:43], v[212:215], v[28:31]
	v_mfma_f32_16x16x32_bf16 v[24:27], v[48:51], v[212:215], v[24:27]
	v_mfma_f32_16x16x32_bf16 v[12:15], v[40:43], v[220:223], v[12:15]
	v_mfma_f32_16x16x32_bf16 v[8:11], v[48:51], v[220:223], v[8:11]
	v_mfma_f32_16x16x32_bf16 v[32:35], v[88:91], v[188:191], v[32:35]
	v_mfma_f32_16x16x32_bf16 v[20:23], v[80:83], v[208:211], v[20:23]
	v_mfma_f32_16x16x32_bf16 v[16:19], v[88:91], v[208:211], v[16:19]
	v_mfma_f32_16x16x32_bf16 v[4:7], v[80:83], v[216:219], v[4:7]
	v_mfma_f32_16x16x32_bf16 v[0:3], v[88:91], v[216:219], v[0:3]
	v_mfma_f32_16x16x32_bf16 v[36:39], v[80:83], v[180:183], v[100:103]
	v_mfma_f32_16x16x32_bf16 v[40:43], v[88:91], v[180:183], v[96:99]
	v_mfma_f32_16x16x32_bf16 v[44:47], v[80:83], v[188:191], v[60:63]
	v_mfma_f32_16x16x32_bf16 v[32:35], v[92:95], v[204:207], v[32:35]
	v_mfma_f32_16x16x32_bf16 v[20:23], v[84:87], v[212:215], v[20:23]
	v_mfma_f32_16x16x32_bf16 v[16:19], v[92:95], v[212:215], v[16:19]
	v_mfma_f32_16x16x32_bf16 v[4:7], v[84:87], v[220:223], v[4:7]
	v_mfma_f32_16x16x32_bf16 v[0:3], v[92:95], v[220:223], v[0:3]
	v_mfma_f32_16x16x32_bf16 v[36:39], v[84:87], v[184:187], v[36:39]
	v_mfma_f32_16x16x32_bf16 v[40:43], v[92:95], v[184:187], v[40:43]
	v_mfma_f32_16x16x32_bf16 v[44:47], v[84:87], v[204:207], v[44:47]
	s_barrier
	s_add_i32 s62, 0, 0x18000
	s_add_i32 s63, 0, 0x1c000
	v_add_u32_e32 v84, s62, v194
	v_add_u32_e32 v96, s63, v194
	ds_read_b128 v[48:51], v84
	ds_read_b128 v[60:63], v84 offset:1024
	ds_read_b128 v[80:83], v84 offset:2048
	ds_read_b128 v[84:87], v84 offset:3072
	ds_read_b128 v[88:91], v96
	ds_read_b128 v[92:95], v96 offset:1024
	ds_read_b128 v[180:183], v96 offset:2048
	ds_read_b128 v[184:187], v96 offset:3072
	s_add_u32 s44, s44, 0x40000
	s_addc_u32 s45, s45, 0
	s_mov_b32 m0, s51
	v_lshl_add_u64 v[226:227], s[44:45], 0, v[160:161]
	ds_read_b128 v[96:99], v199 offset:32768
	ds_read_b128 v[100:103], v199 offset:33792
	ds_read_b128 v[188:191], v199 offset:34816
	ds_read_b128 v[204:207], v199 offset:35840
	ds_read_b128 v[208:211], v199 offset:36864
	ds_read_b128 v[212:215], v199 offset:37888
	ds_read_b128 v[216:219], v199 offset:38912
	ds_read_b128 v[220:223], v199 offset:39936
	global_load_lds_dwordx4 v[226:227], off
	v_lshl_add_u64 v[226:227], s[44:45], 0, v[164:165]
	s_mov_b32 m0, s64
	s_nop 0
	global_load_lds_dwordx4 v[226:227], off
	s_waitcnt vmcnt(8)
	s_waitcnt lgkmcnt(0)
	s_barrier
	s_waitcnt lgkmcnt(0)
	v_mfma_f32_16x16x32_bf16 v[68:71], v[48:51], v[96:99], v[68:71]
	v_mfma_f32_16x16x32_bf16 v[64:67], v[80:83], v[96:99], v[64:67]
	v_mfma_f32_16x16x32_bf16 v[156:159], v[48:51], v[188:191], v[156:159]
	v_mfma_f32_16x16x32_bf16 v[152:155], v[80:83], v[188:191], v[152:155]
	v_mfma_f32_16x16x32_bf16 v[140:143], v[48:51], v[208:211], v[140:143]
	v_mfma_f32_16x16x32_bf16 v[136:139], v[80:83], v[208:211], v[136:139]
	v_mfma_f32_16x16x32_bf16 v[124:127], v[48:51], v[216:219], v[124:127]
	v_mfma_f32_16x16x32_bf16 v[120:123], v[80:83], v[216:219], v[120:123]
	v_mfma_f32_16x16x32_bf16 v[68:71], v[60:63], v[100:103], v[68:71]
	v_mfma_f32_16x16x32_bf16 v[64:67], v[84:87], v[100:103], v[64:67]
	v_mfma_f32_16x16x32_bf16 v[156:159], v[60:63], v[204:207], v[156:159]
	v_mfma_f32_16x16x32_bf16 v[152:155], v[84:87], v[204:207], v[152:155]
	v_mfma_f32_16x16x32_bf16 v[140:143], v[60:63], v[212:215], v[140:143]
	v_mfma_f32_16x16x32_bf16 v[136:139], v[84:87], v[212:215], v[136:139]
	v_mfma_f32_16x16x32_bf16 v[124:127], v[60:63], v[220:223], v[124:127]
	v_mfma_f32_16x16x32_bf16 v[120:123], v[84:87], v[220:223], v[120:123]
	v_mfma_f32_16x16x32_bf16 v[56:59], v[88:91], v[96:99], v[56:59]
	v_mfma_f32_16x16x32_bf16 v[52:55], v[180:183], v[96:99], v[52:55]
	v_mfma_f32_16x16x32_bf16 v[96:99], v[88:91], v[188:191], v[148:151]
	v_mfma_f32_16x16x32_bf16 v[148:151], v[92:95], v[204:207], v[96:99]
	v_mfma_f32_16x16x32_bf16 v[96:99], v[180:183], v[188:191], v[144:147]
	v_mfma_f32_16x16x32_bf16 v[144:147], v[184:187], v[204:207], v[96:99]
	v_mfma_f32_16x16x32_bf16 v[96:99], v[88:91], v[208:211], v[132:135]
	v_mfma_f32_16x16x32_bf16 v[132:135], v[92:95], v[212:215], v[96:99]
	v_mfma_f32_16x16x32_bf16 v[96:99], v[180:183], v[208:211], v[128:131]
	v_mfma_f32_16x16x32_bf16 v[128:131], v[184:187], v[212:215], v[96:99]
	v_mfma_f32_16x16x32_bf16 v[96:99], v[88:91], v[216:219], v[116:119]
	v_mfma_f32_16x16x32_bf16 v[116:119], v[92:95], v[220:223], v[96:99]
	v_mfma_f32_16x16x32_bf16 v[96:99], v[180:183], v[216:219], v[112:115]
	v_mfma_f32_16x16x32_bf16 v[56:59], v[92:95], v[100:103], v[56:59]
	v_mfma_f32_16x16x32_bf16 v[52:55], v[184:187], v[100:103], v[52:55]
	v_mfma_f32_16x16x32_bf16 v[112:115], v[184:187], v[220:223], v[96:99]
	s_barrier
	s_add_i32 s44, s62, s48
	v_lshl_add_u64 v[100:101], v[230:231], 0, s[10:11]
	s_mov_b32 m0, s44
	ds_read_b128 v[96:99], v199 offset:49152
	ds_read_b128 v[188:191], v199 offset:50176
	ds_read_b128 v[204:207], v199 offset:51200
	ds_read_b128 v[208:211], v199 offset:52224
	ds_read_b128 v[212:215], v199 offset:53248
	ds_read_b128 v[216:219], v199 offset:54272
	ds_read_b128 v[220:223], v199 offset:55296
	ds_read_b128 v[226:229], v199 offset:56320
	global_load_lds_dwordx4 v[100:101], off
	s_add_i32 m0, s44, 0x2000
	s_add_u32 s28, s28, 0x40080
	v_lshl_add_u64 v[100:101], v[232:233], 0, s[10:11]
	s_addc_u32 s29, s29, 0
	s_add_i32 s44, s63, s48
	global_load_lds_dwordx4 v[100:101], off
	v_lshl_add_u64 v[100:101], s[28:29], 0, v[162:163]
	s_mov_b32 m0, s44
	s_nop 0
	global_load_lds_dwordx4 v[100:101], off
	v_lshl_add_u64 v[100:101], s[28:29], 0, v[166:167]
	s_add_i32 m0, s44, 0x2000
	s_nop 0
	global_load_lds_dwordx4 v[100:101], off
	v_lshl_add_u64 v[100:101], v[234:235], 0, s[10:11]
	s_mov_b32 m0, s67
	s_nop 0
	global_load_lds_dwordx4 v[100:101], off
	v_lshl_add_u64 v[100:101], v[236:237], 0, s[10:11]
	s_mov_b32 m0, s68
	s_nop 0
	global_load_lds_dwordx4 v[100:101], off
	s_waitcnt vmcnt(8)
	s_waitcnt lgkmcnt(0)
	s_barrier
	s_waitcnt lgkmcnt(0)
	v_mfma_f32_16x16x32_bf16 v[100:103], v[48:51], v[96:99], v[108:111]
	v_mfma_f32_16x16x32_bf16 v[108:111], v[60:63], v[188:191], v[100:103]
	v_mfma_f32_16x16x32_bf16 v[100:103], v[80:83], v[96:99], v[104:107]
	v_mfma_f32_16x16x32_bf16 v[76:79], v[48:51], v[204:207], v[76:79]
	v_mfma_f32_16x16x32_bf16 v[72:75], v[80:83], v[204:207], v[72:75]
	v_mfma_f32_16x16x32_bf16 v[28:31], v[48:51], v[212:215], v[28:31]
	v_mfma_f32_16x16x32_bf16 v[24:27], v[80:83], v[212:215], v[24:27]
	v_mfma_f32_16x16x32_bf16 v[12:15], v[48:51], v[220:223], v[12:15]
	v_mfma_f32_16x16x32_bf16 v[8:11], v[80:83], v[220:223], v[8:11]
	v_mfma_f32_16x16x32_bf16 v[104:107], v[84:87], v[188:191], v[100:103]
	v_mfma_f32_16x16x32_bf16 v[76:79], v[60:63], v[208:211], v[76:79]
	v_mfma_f32_16x16x32_bf16 v[72:75], v[84:87], v[208:211], v[72:75]
	v_mfma_f32_16x16x32_bf16 v[28:31], v[60:63], v[216:219], v[28:31]
	v_mfma_f32_16x16x32_bf16 v[24:27], v[84:87], v[216:219], v[24:27]
	v_mfma_f32_16x16x32_bf16 v[12:15], v[60:63], v[226:229], v[12:15]
	v_mfma_f32_16x16x32_bf16 v[8:11], v[84:87], v[226:229], v[8:11]
	v_mfma_f32_16x16x32_bf16 v[36:39], v[88:91], v[96:99], v[36:39]
	v_mfma_f32_16x16x32_bf16 v[100:103], v[92:95], v[188:191], v[36:39]
	v_mfma_f32_16x16x32_bf16 v[36:39], v[180:183], v[96:99], v[40:43]
	v_mfma_f32_16x16x32_bf16 v[96:99], v[184:187], v[188:191], v[36:39]
	v_mfma_f32_16x16x32_bf16 v[36:39], v[88:91], v[204:207], v[44:47]
	v_mfma_f32_16x16x32_bf16 v[32:35], v[180:183], v[204:207], v[32:35]
	v_mfma_f32_16x16x32_bf16 v[20:23], v[88:91], v[212:215], v[20:23]
	v_mfma_f32_16x16x32_bf16 v[16:19], v[180:183], v[212:215], v[16:19]
	v_mfma_f32_16x16x32_bf16 v[4:7], v[88:91], v[220:223], v[4:7]
	v_mfma_f32_16x16x32_bf16 v[0:3], v[180:183], v[220:223], v[0:3]
	v_mfma_f32_16x16x32_bf16 v[60:63], v[92:95], v[208:211], v[36:39]
	v_mfma_f32_16x16x32_bf16 v[32:35], v[184:187], v[208:211], v[32:35]
	v_mfma_f32_16x16x32_bf16 v[20:23], v[92:95], v[216:219], v[20:23]
	v_mfma_f32_16x16x32_bf16 v[16:19], v[184:187], v[216:219], v[16:19]
	v_mfma_f32_16x16x32_bf16 v[4:7], v[92:95], v[226:229], v[4:7]
	v_mfma_f32_16x16x32_bf16 v[0:3], v[184:187], v[226:229], v[0:3]
	s_barrier
	s_add_i32 s75, s75, 2
	s_add_u32 s4, s4, 0x100
	s_addc_u32 s5, s5, 0
	s_add_u32 s73, s73, 0x100
	s_addc_u32 s74, s74, 0
	s_cmp_gt_u32 s75, 13
	s_cbranch_scc0 .LBB0_1534
	s_and_b64 vcc, exec, s[12:13]
	s_cbranch_vccz .LBB0_1537
	s_barrier

.LBB0_1924:
	s_add_i32 s22, s26, 0x20000
	s_sub_i32 s22, s22, s56
	v_add_u32_e32 v2, s22, v188
	s_waitcnt vmcnt(7)
	ds_write_b128 v243, v[128:131]
	s_waitcnt vmcnt(6)
	ds_write_b128 v244, v[132:135] offset:4608
	s_waitcnt vmcnt(5)
	ds_write_b128 v243, v[136:139] offset:1152
	s_waitcnt vmcnt(4)
	ds_write_b128 v244, v[140:143] offset:5120
	s_waitcnt vmcnt(3)
	ds_write_b128 v243, v[144:147] offset:2304
	s_waitcnt vmcnt(2)
	ds_write_b128 v244, v[148:151] offset:5632
	s_waitcnt vmcnt(1)
	ds_write_b128 v243, v[152:155] offset:3456
	s_waitcnt vmcnt(0)
	ds_write_b128 v244, v[156:159] offset:6144
	v_add_u32_e32 v4, 0x4000, v2
	global_load_dwordx4 v[128:131], v2, s[40:41]
	global_load_dwordx4 v[132:135], v2, s[42:43]
	v_add_u32_e32 v5, 0x8000, v2
	global_load_dwordx4 v[136:139], v4, s[40:41]
	global_load_dwordx4 v[140:143], v4, s[42:43]
	v_add_u32_e32 v6, 0xc000, v2
	global_load_dwordx4 v[144:147], v5, s[40:41]
	global_load_dwordx4 v[148:151], v5, s[42:43]
	v_xor_b32_e32 v112, 0x80000000, v1
	global_load_dwordx4 v[152:155], v6, s[40:41]
	global_load_dwordx4 v[156:159], v6, s[42:43]
	s_waitcnt lgkmcnt(0)
	ds_read_b128 v[6:9], v242
	ds_read_b128 v[2:5], v242 offset:32
	ds_read_b128 v[10:13], v242 offset:8704
	v_mov_b32_e32 v113, v112
	v_mov_b32_e32 v114, v112
	v_mov_b32_e32 v115, v112
	v_mov_b32_e32 v116, v112
	v_mov_b32_e32 v117, v112
	v_mov_b32_e32 v118, v112
	v_mov_b32_e32 v119, v112
	v_mov_b32_e32 v120, v112
	v_mov_b32_e32 v121, v112
	v_mov_b32_e32 v122, v112
	v_mov_b32_e32 v123, v112
	v_mov_b32_e32 v124, v112
	v_mov_b32_e32 v125, v112
	v_mov_b32_e32 v126, v112
	v_mov_b32_e32 v127, v112
	ds_read_b128 v[96:99], v242 offset:8736
	s_andn2_b64 vcc, exec, s[20:21]
	s_waitcnt lgkmcnt(1)
	v_mfma_f32_32x32x16_bf16 v[112:127], v[6:9], v[10:13], v[112:127]
	s_waitcnt lgkmcnt(0)
	v_mfma_f32_32x32x16_bf16 v[112:127], v[2:5], v[96:99], v[112:127]
	ds_read_b128 v[10:13], v242 offset:64
	ds_read_b128 v[96:99], v242 offset:8768
	ds_read_b128 v[160:163], v242 offset:96
	ds_read_b128 v[100:103], v242 offset:8800
	s_waitcnt lgkmcnt(2)
	v_mfma_f32_32x32x16_bf16 v[112:127], v[10:13], v[96:99], v[112:127]
	v_xor_b32_e32 v96, 0x80000000, v15
	v_cndmask_b32_e64 v97, 0, 1, s[20:21]
	v_cmp_ne_u32_e64 s[22:23], 1, v97
	v_mov_b32_e32 v97, v96
	v_mov_b32_e32 v98, v96
	v_mov_b32_e32 v99, v96
	v_mov_b32_e32 v104, v96
	s_waitcnt lgkmcnt(0)
	v_mfma_f32_32x32x16_bf16 v[112:127], v[160:163], v[100:103], v[112:127]
	v_mov_b32_e32 v100, v96
	v_mov_b32_e32 v101, v96
	v_mov_b32_e32 v102, v96
	v_mov_b32_e32 v103, v96
	v_mov_b32_e32 v105, v96
	v_mov_b32_e32 v106, v96
	v_mov_b32_e32 v107, v96
	v_mov_b32_e32 v108, v96
	s_cbranch_vccnz .LBB0_1926
	ds_read_b128 v[246:249], v242 offset:13312
	ds_read_b128 v[250:253], v242 offset:13344
	v_mov_b32_e32 v109, v96
	v_mov_b32_e32 v110, v96
	v_mov_b32_e32 v111, v96
	s_waitcnt lgkmcnt(1)
	s_nop 0
	v_mfma_f32_32x32x16_bf16 v[96:111], v[6:9], v[246:249], v[96:111]
	s_waitcnt lgkmcnt(0)
	v_mfma_f32_32x32x16_bf16 v[96:111], v[2:5], v[250:253], v[96:111]
	ds_read_b128 v[2:5], v242 offset:13376
	ds_read_b128 v[6:9], v242 offset:13408
	s_waitcnt lgkmcnt(1)
	v_mfma_f32_32x32x16_bf16 v[96:111], v[10:13], v[2:5], v[96:111]
	s_waitcnt lgkmcnt(0)
	v_mfma_f32_32x32x16_bf16 v[96:111], v[160:163], v[6:9], v[96:111]
	s_branch .LBB0_1927

.LBB0_2040:
	ds_read_b128 v[128:131], v189
	ds_read_b128 v[132:135], v189 offset:1024
	ds_read_b128 v[136:139], v189 offset:2048
	ds_read_b128 v[140:143], v189 offset:3072
	ds_read_b128 v[144:147], v190
	ds_read_b128 v[148:151], v190 offset:1024
	ds_read_b128 v[168:171], v190 offset:2048
	ds_read_b128 v[172:175], v190 offset:3072
	s_add_u32 s26, s24, 0xfffc0080
	s_addc_u32 s27, s25, -1
	s_cmp_eq_u32 s70, 12
	s_cselect_b32 s29, s17, s27
	s_cselect_b32 s28, s23, s26
	s_cselect_b32 s27, s15, s69
	s_cselect_b32 s26, s67, s68
	v_lshl_add_u64 v[184:185], s[24:25], 0, v[160:161]
	s_add_i32 m0, s43, 0xc000
	ds_read_b128 v[176:179], v191
	ds_read_b128 v[180:183], v191 offset:1024
	ds_read_b128 v[198:201], v191 offset:2048
	ds_read_b128 v[202:205], v191 offset:3072
	ds_read_b128 v[206:209], v191 offset:4096
	ds_read_b128 v[210:213], v191 offset:5120
	ds_read_b128 v[214:217], v191 offset:6144
	ds_read_b128 v[218:221], v191 offset:7168
	global_load_lds_dwordx4 v[184:185], off
	v_lshl_add_u64 v[184:185], s[24:25], 0, v[162:163]
	s_add_i32 m0, s43, 0xe000
	s_nop 0
	global_load_lds_dwordx4 v[184:185], off
	s_waitcnt vmcnt(8)
	s_waitcnt lgkmcnt(0)
	s_barrier
	s_waitcnt lgkmcnt(0)
	v_mfma_f32_16x16x32_bf16 v[124:127], v[128:131], v[176:179], v[124:127]
	v_mfma_f32_16x16x32_bf16 v[120:123], v[136:139], v[176:179], v[120:123]
	v_mfma_f32_16x16x32_bf16 v[108:111], v[128:131], v[198:201], v[108:111]
	v_mfma_f32_16x16x32_bf16 v[104:107], v[136:139], v[198:201], v[104:107]
	v_mfma_f32_16x16x32_bf16 v[92:95], v[128:131], v[206:209], v[92:95]
	v_mfma_f32_16x16x32_bf16 v[88:91], v[136:139], v[206:209], v[88:91]
	v_mfma_f32_16x16x32_bf16 v[76:79], v[128:131], v[214:217], v[76:79]
	v_mfma_f32_16x16x32_bf16 v[72:75], v[136:139], v[214:217], v[72:75]
	v_mfma_f32_16x16x32_bf16 v[124:127], v[132:135], v[180:183], v[124:127]
	v_mfma_f32_16x16x32_bf16 v[120:123], v[140:143], v[180:183], v[120:123]
	v_mfma_f32_16x16x32_bf16 v[108:111], v[132:135], v[202:205], v[108:111]
	v_mfma_f32_16x16x32_bf16 v[104:107], v[140:143], v[202:205], v[104:107]
	v_mfma_f32_16x16x32_bf16 v[92:95], v[132:135], v[210:213], v[92:95]
	v_mfma_f32_16x16x32_bf16 v[88:91], v[140:143], v[210:213], v[88:91]
	v_mfma_f32_16x16x32_bf16 v[76:79], v[132:135], v[218:221], v[76:79]
	v_mfma_f32_16x16x32_bf16 v[72:75], v[140:143], v[218:221], v[72:75]
	v_mfma_f32_16x16x32_bf16 v[116:119], v[144:147], v[176:179], v[116:119]
	v_mfma_f32_16x16x32_bf16 v[112:115], v[168:171], v[176:179], v[112:115]
	v_mfma_f32_16x16x32_bf16 v[100:103], v[144:147], v[198:201], v[100:103]
	v_mfma_f32_16x16x32_bf16 v[96:99], v[168:171], v[198:201], v[96:99]
	v_mfma_f32_16x16x32_bf16 v[84:87], v[144:147], v[206:209], v[84:87]
	v_mfma_f32_16x16x32_bf16 v[80:83], v[168:171], v[206:209], v[80:83]
	v_mfma_f32_16x16x32_bf16 v[68:71], v[144:147], v[214:217], v[68:71]
	v_mfma_f32_16x16x32_bf16 v[64:67], v[168:171], v[214:217], v[64:67]
	v_mfma_f32_16x16x32_bf16 v[116:119], v[148:151], v[180:183], v[116:119]
	v_mfma_f32_16x16x32_bf16 v[112:115], v[172:175], v[180:183], v[112:115]
	v_mfma_f32_16x16x32_bf16 v[100:103], v[148:151], v[202:205], v[100:103]
	v_mfma_f32_16x16x32_bf16 v[96:99], v[172:175], v[202:205], v[96:99]
	v_mfma_f32_16x16x32_bf16 v[84:87], v[148:151], v[210:213], v[84:87]
	v_mfma_f32_16x16x32_bf16 v[80:83], v[172:175], v[210:213], v[80:83]
	v_mfma_f32_16x16x32_bf16 v[68:71], v[148:151], v[218:221], v[68:71]
	v_mfma_f32_16x16x32_bf16 v[64:67], v[172:175], v[218:221], v[64:67]
	s_barrier
	s_add_i32 s62, s64, s42
	v_lshl_add_u64 v[184:185], s[26:27], 0, v[154:155]
	s_mov_b32 m0, s62
	ds_read_b128 v[176:179], v191 offset:16384
	ds_read_b128 v[180:183], v191 offset:17408
	ds_read_b128 v[198:201], v191 offset:18432
	ds_read_b128 v[202:205], v191 offset:19456
	ds_read_b128 v[206:209], v191 offset:20480
	ds_read_b128 v[210:213], v191 offset:21504
	ds_read_b128 v[214:217], v191 offset:22528
	ds_read_b128 v[218:221], v191 offset:23552
	global_load_lds_dwordx4 v[184:185], off
	s_add_i32 m0, s62, 0x2000
	s_add_u32 s62, s26, 0x40000
	v_lshl_add_u64 v[194:195], s[26:27], 0, v[158:159]
	s_addc_u32 s63, s27, 0
	s_add_i32 s71, s65, s42
	global_load_lds_dwordx4 v[194:195], off
	v_lshl_add_u64 v[222:223], s[62:63], 0, v[154:155]
	s_mov_b32 m0, s71
	v_lshl_add_u64 v[226:227], s[28:29], 0, v[156:157]
	global_load_lds_dwordx4 v[222:223], off
	v_lshl_add_u64 v[222:223], s[62:63], 0, v[158:159]
	s_add_i32 m0, s71, 0x2000
	s_nop 0
	global_load_lds_dwordx4 v[222:223], off
	v_lshl_add_u64 v[222:223], s[28:29], 0, v[152:153]
	s_mov_b32 m0, s43
	s_nop 0
	global_load_lds_dwordx4 v[222:223], off
	s_mov_b32 m0, s44
	s_nop 0
	global_load_lds_dwordx4 v[226:227], off
	s_waitcnt vmcnt(8)
	s_waitcnt lgkmcnt(0)
	s_barrier
	s_waitcnt lgkmcnt(0)
	v_mfma_f32_16x16x32_bf16 v[60:63], v[128:131], v[176:179], v[60:63]
	v_mfma_f32_16x16x32_bf16 v[56:59], v[136:139], v[176:179], v[56:59]
	v_mfma_f32_16x16x32_bf16 v[44:47], v[128:131], v[198:201], v[44:47]
	v_mfma_f32_16x16x32_bf16 v[40:43], v[136:139], v[198:201], v[40:43]
	v_mfma_f32_16x16x32_bf16 v[28:31], v[128:131], v[206:209], v[28:31]
	v_mfma_f32_16x16x32_bf16 v[24:27], v[136:139], v[206:209], v[24:27]
	v_mfma_f32_16x16x32_bf16 v[12:15], v[128:131], v[214:217], v[12:15]
	v_mfma_f32_16x16x32_bf16 v[8:11], v[136:139], v[214:217], v[8:11]
	v_mfma_f32_16x16x32_bf16 v[60:63], v[132:135], v[180:183], v[60:63]
	v_mfma_f32_16x16x32_bf16 v[56:59], v[140:143], v[180:183], v[56:59]
	v_mfma_f32_16x16x32_bf16 v[44:47], v[132:135], v[202:205], v[44:47]
	v_mfma_f32_16x16x32_bf16 v[40:43], v[140:143], v[202:205], v[40:43]
	v_mfma_f32_16x16x32_bf16 v[28:31], v[132:135], v[210:213], v[28:31]
	v_mfma_f32_16x16x32_bf16 v[24:27], v[140:143], v[210:213], v[24:27]
	v_mfma_f32_16x16x32_bf16 v[12:15], v[132:135], v[218:221], v[12:15]
	v_mfma_f32_16x16x32_bf16 v[8:11], v[140:143], v[218:221], v[8:11]
	v_mfma_f32_16x16x32_bf16 v[52:55], v[144:147], v[176:179], v[52:55]
	v_mfma_f32_16x16x32_bf16 v[48:51], v[168:171], v[176:179], v[48:51]
	v_mfma_f32_16x16x32_bf16 v[36:39], v[144:147], v[198:201], v[36:39]
	v_mfma_f32_16x16x32_bf16 v[32:35], v[168:171], v[198:201], v[32:35]
	v_mfma_f32_16x16x32_bf16 v[20:23], v[144:147], v[206:209], v[20:23]
	v_mfma_f32_16x16x32_bf16 v[16:19], v[168:171], v[206:209], v[16:19]
	v_mfma_f32_16x16x32_bf16 v[4:7], v[144:147], v[214:217], v[4:7]
	v_mfma_f32_16x16x32_bf16 v[0:3], v[168:171], v[214:217], v[0:3]
	v_mfma_f32_16x16x32_bf16 v[52:55], v[148:151], v[180:183], v[52:55]
	v_mfma_f32_16x16x32_bf16 v[48:51], v[172:175], v[180:183], v[48:51]
	v_mfma_f32_16x16x32_bf16 v[36:39], v[148:151], v[202:205], v[36:39]
	v_mfma_f32_16x16x32_bf16 v[32:35], v[172:175], v[202:205], v[32:35]
	v_mfma_f32_16x16x32_bf16 v[20:23], v[148:151], v[210:213], v[20:23]
	v_mfma_f32_16x16x32_bf16 v[16:19], v[172:175], v[210:213], v[16:19]
	v_mfma_f32_16x16x32_bf16 v[4:7], v[148:151], v[218:221], v[4:7]
	v_mfma_f32_16x16x32_bf16 v[0:3], v[172:175], v[218:221], v[0:3]
	s_barrier
	s_add_i32 s62, 0, 0x18000
	s_add_i32 s63, 0, 0x1c000
	v_add_u32_e32 v140, s62, v187
	v_add_u32_e32 v172, s63, v187
	ds_read_b128 v[128:131], v140
	ds_read_b128 v[132:135], v140 offset:1024
	ds_read_b128 v[136:139], v140 offset:2048
	ds_read_b128 v[140:143], v140 offset:3072
	ds_read_b128 v[144:147], v172
	ds_read_b128 v[148:151], v172 offset:1024
	ds_read_b128 v[168:171], v172 offset:2048
	ds_read_b128 v[172:175], v172 offset:3072
	s_add_u32 s28, s28, 0x40000
	s_addc_u32 s29, s29, 0
	s_mov_b32 m0, s45
	v_lshl_add_u64 v[228:229], s[28:29], 0, v[152:153]
	ds_read_b128 v[176:179], v191 offset:32768
	ds_read_b128 v[180:183], v191 offset:33792
	ds_read_b128 v[198:201], v191 offset:34816
	ds_read_b128 v[202:205], v191 offset:35840
	ds_read_b128 v[206:209], v191 offset:36864
	ds_read_b128 v[210:213], v191 offset:37888
	ds_read_b128 v[214:217], v191 offset:38912
	ds_read_b128 v[218:221], v191 offset:39936
	global_load_lds_dwordx4 v[228:229], off
	v_lshl_add_u64 v[228:229], s[28:29], 0, v[156:157]
	s_mov_b32 m0, s46
	s_nop 0
	global_load_lds_dwordx4 v[228:229], off
	s_waitcnt vmcnt(8)
	s_waitcnt lgkmcnt(0)
	s_barrier
	s_waitcnt lgkmcnt(0)
	v_mfma_f32_16x16x32_bf16 v[124:127], v[128:131], v[176:179], v[124:127]
	v_mfma_f32_16x16x32_bf16 v[120:123], v[136:139], v[176:179], v[120:123]
	v_mfma_f32_16x16x32_bf16 v[108:111], v[128:131], v[198:201], v[108:111]
	v_mfma_f32_16x16x32_bf16 v[104:107], v[136:139], v[198:201], v[104:107]
	v_mfma_f32_16x16x32_bf16 v[92:95], v[128:131], v[206:209], v[92:95]
	v_mfma_f32_16x16x32_bf16 v[88:91], v[136:139], v[206:209], v[88:91]
	v_mfma_f32_16x16x32_bf16 v[76:79], v[128:131], v[214:217], v[76:79]
	v_mfma_f32_16x16x32_bf16 v[72:75], v[136:139], v[214:217], v[72:75]
	v_mfma_f32_16x16x32_bf16 v[124:127], v[132:135], v[180:183], v[124:127]
	v_mfma_f32_16x16x32_bf16 v[120:123], v[140:143], v[180:183], v[120:123]
	v_mfma_f32_16x16x32_bf16 v[108:111], v[132:135], v[202:205], v[108:111]
	v_mfma_f32_16x16x32_bf16 v[104:107], v[140:143], v[202:205], v[104:107]
	v_mfma_f32_16x16x32_bf16 v[92:95], v[132:135], v[210:213], v[92:95]
	v_mfma_f32_16x16x32_bf16 v[88:91], v[140:143], v[210:213], v[88:91]
	v_mfma_f32_16x16x32_bf16 v[76:79], v[132:135], v[218:221], v[76:79]
	v_mfma_f32_16x16x32_bf16 v[72:75], v[140:143], v[218:221], v[72:75]
	v_mfma_f32_16x16x32_bf16 v[116:119], v[144:147], v[176:179], v[116:119]
	v_mfma_f32_16x16x32_bf16 v[112:115], v[168:171], v[176:179], v[112:115]
	v_mfma_f32_16x16x32_bf16 v[100:103], v[144:147], v[198:201], v[100:103]
	v_mfma_f32_16x16x32_bf16 v[96:99], v[168:171], v[198:201], v[96:99]
	v_mfma_f32_16x16x32_bf16 v[84:87], v[144:147], v[206:209], v[84:87]
	v_mfma_f32_16x16x32_bf16 v[80:83], v[168:171], v[206:209], v[80:83]
	v_mfma_f32_16x16x32_bf16 v[68:71], v[144:147], v[214:217], v[68:71]
	v_mfma_f32_16x16x32_bf16 v[64:67], v[168:171], v[214:217], v[64:67]
	v_mfma_f32_16x16x32_bf16 v[116:119], v[148:151], v[180:183], v[116:119]
	v_mfma_f32_16x16x32_bf16 v[112:115], v[172:175], v[180:183], v[112:115]
	v_mfma_f32_16x16x32_bf16 v[100:103], v[148:151], v[202:205], v[100:103]
	v_mfma_f32_16x16x32_bf16 v[96:99], v[172:175], v[202:205], v[96:99]
	v_mfma_f32_16x16x32_bf16 v[84:87], v[148:151], v[210:213], v[84:87]
	v_mfma_f32_16x16x32_bf16 v[80:83], v[172:175], v[210:213], v[80:83]
	v_mfma_f32_16x16x32_bf16 v[68:71], v[148:151], v[218:221], v[68:71]
	v_mfma_f32_16x16x32_bf16 v[64:67], v[172:175], v[218:221], v[64:67]
	s_barrier
	s_add_i32 s28, s62, s42
	v_lshl_add_u64 v[184:185], v[184:185], 0, s[10:11]
	s_mov_b32 m0, s28
	ds_read_b128 v[176:179], v191 offset:49152
	ds_read_b128 v[180:183], v191 offset:50176
	ds_read_b128 v[198:201], v191 offset:51200
	ds_read_b128 v[202:205], v191 offset:52224
	ds_read_b128 v[206:209], v191 offset:53248
	ds_read_b128 v[210:213], v191 offset:54272
	ds_read_b128 v[214:217], v191 offset:55296
	ds_read_b128 v[218:221], v191 offset:56320
	global_load_lds_dwordx4 v[184:185], off
	s_add_i32 m0, s28, 0x2000
	s_add_u32 s26, s26, 0x40080
	v_lshl_add_u64 v[184:185], v[194:195], 0, s[10:11]
	s_addc_u32 s27, s27, 0
	s_add_i32 s28, s63, s42
	global_load_lds_dwordx4 v[184:185], off
	v_lshl_add_u64 v[184:185], s[26:27], 0, v[154:155]
	s_mov_b32 m0, s28
	s_nop 0
	global_load_lds_dwordx4 v[184:185], off
	v_lshl_add_u64 v[184:185], s[26:27], 0, v[158:159]
	s_add_i32 m0, s28, 0x2000
	s_nop 0
	global_load_lds_dwordx4 v[184:185], off
	v_lshl_add_u64 v[184:185], v[222:223], 0, s[10:11]
	s_mov_b32 m0, s48
	s_nop 0
	global_load_lds_dwordx4 v[184:185], off
	v_lshl_add_u64 v[184:185], v[226:227], 0, s[10:11]
	s_mov_b32 m0, s49
	s_nop 0
	global_load_lds_dwordx4 v[184:185], off
	s_waitcnt vmcnt(8)
	s_waitcnt lgkmcnt(0)
	s_barrier
	s_waitcnt lgkmcnt(0)
	v_mfma_f32_16x16x32_bf16 v[60:63], v[128:131], v[176:179], v[60:63]
	v_mfma_f32_16x16x32_bf16 v[56:59], v[136:139], v[176:179], v[56:59]
	v_mfma_f32_16x16x32_bf16 v[44:47], v[128:131], v[198:201], v[44:47]
	v_mfma_f32_16x16x32_bf16 v[40:43], v[136:139], v[198:201], v[40:43]
	v_mfma_f32_16x16x32_bf16 v[28:31], v[128:131], v[206:209], v[28:31]
	v_mfma_f32_16x16x32_bf16 v[24:27], v[136:139], v[206:209], v[24:27]
	v_mfma_f32_16x16x32_bf16 v[12:15], v[128:131], v[214:217], v[12:15]
	v_mfma_f32_16x16x32_bf16 v[8:11], v[136:139], v[214:217], v[8:11]
	v_mfma_f32_16x16x32_bf16 v[60:63], v[132:135], v[180:183], v[60:63]
	v_mfma_f32_16x16x32_bf16 v[56:59], v[140:143], v[180:183], v[56:59]
	v_mfma_f32_16x16x32_bf16 v[44:47], v[132:135], v[202:205], v[44:47]
	v_mfma_f32_16x16x32_bf16 v[40:43], v[140:143], v[202:205], v[40:43]
	v_mfma_f32_16x16x32_bf16 v[28:31], v[132:135], v[210:213], v[28:31]
	v_mfma_f32_16x16x32_bf16 v[24:27], v[140:143], v[210:213], v[24:27]
	v_mfma_f32_16x16x32_bf16 v[12:15], v[132:135], v[218:221], v[12:15]
	v_mfma_f32_16x16x32_bf16 v[8:11], v[140:143], v[218:221], v[8:11]
	v_mfma_f32_16x16x32_bf16 v[52:55], v[144:147], v[176:179], v[52:55]
	v_mfma_f32_16x16x32_bf16 v[48:51], v[168:171], v[176:179], v[48:51]
	v_mfma_f32_16x16x32_bf16 v[36:39], v[144:147], v[198:201], v[36:39]
	v_mfma_f32_16x16x32_bf16 v[32:35], v[168:171], v[198:201], v[32:35]
	v_mfma_f32_16x16x32_bf16 v[20:23], v[144:147], v[206:209], v[20:23]
	v_mfma_f32_16x16x32_bf16 v[16:19], v[168:171], v[206:209], v[16:19]
	v_mfma_f32_16x16x32_bf16 v[4:7], v[144:147], v[214:217], v[4:7]
	v_mfma_f32_16x16x32_bf16 v[0:3], v[168:171], v[214:217], v[0:3]
	v_mfma_f32_16x16x32_bf16 v[52:55], v[148:151], v[180:183], v[52:55]
	v_mfma_f32_16x16x32_bf16 v[48:51], v[172:175], v[180:183], v[48:51]
	v_mfma_f32_16x16x32_bf16 v[36:39], v[148:151], v[202:205], v[36:39]
	v_mfma_f32_16x16x32_bf16 v[32:35], v[172:175], v[202:205], v[32:35]
	v_mfma_f32_16x16x32_bf16 v[20:23], v[148:151], v[210:213], v[20:23]
	v_mfma_f32_16x16x32_bf16 v[16:19], v[172:175], v[210:213], v[16:19]
	v_mfma_f32_16x16x32_bf16 v[4:7], v[148:151], v[218:221], v[4:7]
	v_mfma_f32_16x16x32_bf16 v[0:3], v[172:175], v[218:221], v[0:3]
	s_barrier
	s_add_i32 s70, s70, 2
	s_add_u32 s24, s24, 0x100
	s_addc_u32 s25, s25, 0
	s_add_u32 s68, s68, 0x100
	s_addc_u32 s69, s69, 0
	s_cmp_gt_u32 s70, 13
	s_cbranch_scc0 .LBB0_2040
	s_and_b64 vcc, exec, s[12:13]
	s_cbranch_vccz .LBB0_2043
	s_barrier

.LBB0_2123:
	ds_read_b128 v[160:163], v155
	ds_read_b128 v[164:167], v155 offset:1024
	ds_read_b128 v[168:171], v155 offset:2048
	ds_read_b128 v[172:175], v155 offset:3072
	ds_read_b128 v[176:179], v156
	ds_read_b128 v[180:183], v156 offset:1024
	ds_read_b128 v[184:187], v156 offset:2048
	ds_read_b128 v[188:191], v156 offset:3072
	s_add_u32 s22, s20, 0xfffc0080
	s_addc_u32 s23, s21, -1
	s_cmp_eq_u32 s66, 12
	s_cselect_b32 s25, s13, s23
	s_cselect_b32 s24, s50, s22
	s_cselect_b32 s23, s11, s65
	s_cselect_b32 s22, s51, s64
	v_lshl_add_u64 v[146:147], s[20:21], 0, v[138:139]
	s_add_i32 m0, s19, 0xc000
	ds_read_b128 v[192:195], v157
	ds_read_b128 v[198:201], v157 offset:1024
	ds_read_b128 v[202:205], v157 offset:2048
	ds_read_b128 v[206:209], v157 offset:3072
	ds_read_b128 v[210:213], v157 offset:4096
	ds_read_b128 v[214:217], v157 offset:5120
	ds_read_b128 v[218:221], v157 offset:6144
	ds_read_b128 v[226:229], v157 offset:7168
	global_load_lds_dwordx4 v[146:147], off
	v_lshl_add_u64 v[146:147], s[20:21], 0, v[140:141]
	s_add_i32 m0, s19, 0xe000
	s_nop 0
	global_load_lds_dwordx4 v[146:147], off
	s_waitcnt vmcnt(8)
	s_waitcnt lgkmcnt(0)
	s_barrier
	s_waitcnt lgkmcnt(0)
	v_mfma_f32_16x16x32_bf16 v[124:127], v[160:163], v[192:195], v[124:127]
	v_mfma_f32_16x16x32_bf16 v[120:123], v[168:171], v[192:195], v[120:123]
	v_mfma_f32_16x16x32_bf16 v[108:111], v[160:163], v[202:205], v[108:111]
	v_mfma_f32_16x16x32_bf16 v[104:107], v[168:171], v[202:205], v[104:107]
	v_mfma_f32_16x16x32_bf16 v[92:95], v[160:163], v[210:213], v[92:95]
	v_mfma_f32_16x16x32_bf16 v[88:91], v[168:171], v[210:213], v[88:91]
	v_mfma_f32_16x16x32_bf16 v[76:79], v[160:163], v[218:221], v[76:79]
	v_mfma_f32_16x16x32_bf16 v[72:75], v[168:171], v[218:221], v[72:75]
	v_mfma_f32_16x16x32_bf16 v[124:127], v[164:167], v[198:201], v[124:127]
	v_mfma_f32_16x16x32_bf16 v[120:123], v[172:175], v[198:201], v[120:123]
	v_mfma_f32_16x16x32_bf16 v[108:111], v[164:167], v[206:209], v[108:111]
	v_mfma_f32_16x16x32_bf16 v[104:107], v[172:175], v[206:209], v[104:107]
	v_mfma_f32_16x16x32_bf16 v[92:95], v[164:167], v[214:217], v[92:95]
	v_mfma_f32_16x16x32_bf16 v[88:91], v[172:175], v[214:217], v[88:91]
	v_mfma_f32_16x16x32_bf16 v[76:79], v[164:167], v[226:229], v[76:79]
	v_mfma_f32_16x16x32_bf16 v[72:75], v[172:175], v[226:229], v[72:75]
	v_mfma_f32_16x16x32_bf16 v[116:119], v[176:179], v[192:195], v[116:119]
	v_mfma_f32_16x16x32_bf16 v[112:115], v[184:187], v[192:195], v[112:115]
	v_mfma_f32_16x16x32_bf16 v[100:103], v[176:179], v[202:205], v[100:103]
	v_mfma_f32_16x16x32_bf16 v[96:99], v[184:187], v[202:205], v[96:99]
	v_mfma_f32_16x16x32_bf16 v[84:87], v[176:179], v[210:213], v[84:87]
	v_mfma_f32_16x16x32_bf16 v[80:83], v[184:187], v[210:213], v[80:83]
	v_mfma_f32_16x16x32_bf16 v[68:71], v[176:179], v[218:221], v[68:71]
	v_mfma_f32_16x16x32_bf16 v[64:67], v[184:187], v[218:221], v[64:67]
	v_mfma_f32_16x16x32_bf16 v[116:119], v[180:183], v[198:201], v[116:119]
	v_mfma_f32_16x16x32_bf16 v[112:115], v[188:191], v[198:201], v[112:115]
	v_mfma_f32_16x16x32_bf16 v[100:103], v[180:183], v[206:209], v[100:103]
	v_mfma_f32_16x16x32_bf16 v[96:99], v[188:191], v[206:209], v[96:99]
	v_mfma_f32_16x16x32_bf16 v[84:87], v[180:183], v[214:217], v[84:87]
	v_mfma_f32_16x16x32_bf16 v[80:83], v[188:191], v[214:217], v[80:83]
	v_mfma_f32_16x16x32_bf16 v[68:71], v[180:183], v[226:229], v[68:71]
	v_mfma_f32_16x16x32_bf16 v[64:67], v[188:191], v[226:229], v[64:67]
	s_barrier
	s_add_i32 s62, s46, s28
	v_lshl_add_u64 v[146:147], s[22:23], 0, v[132:133]
	s_mov_b32 m0, s62
	ds_read_b128 v[192:195], v157 offset:16384
	ds_read_b128 v[198:201], v157 offset:17408
	ds_read_b128 v[202:205], v157 offset:18432
	ds_read_b128 v[206:209], v157 offset:19456
	ds_read_b128 v[210:213], v157 offset:20480
	ds_read_b128 v[214:217], v157 offset:21504
	ds_read_b128 v[218:221], v157 offset:22528
	ds_read_b128 v[226:229], v157 offset:23552
	global_load_lds_dwordx4 v[146:147], off
	s_add_i32 m0, s62, 0x2000
	s_add_u32 s62, s22, 0x40000
	v_lshl_add_u64 v[222:223], s[22:23], 0, v[128:129]
	s_addc_u32 s63, s23, 0
	s_add_i32 s67, s47, s28
	global_load_lds_dwordx4 v[222:223], off
	v_lshl_add_u64 v[230:231], s[62:63], 0, v[132:133]
	s_mov_b32 m0, s67
	v_lshl_add_u64 v[232:233], s[24:25], 0, v[130:131]
	global_load_lds_dwordx4 v[230:231], off
	v_lshl_add_u64 v[230:231], s[62:63], 0, v[128:129]
	s_add_i32 m0, s67, 0x2000
	s_nop 0
	global_load_lds_dwordx4 v[230:231], off
	v_lshl_add_u64 v[230:231], s[24:25], 0, v[134:135]
	s_mov_b32 m0, s19
	s_nop 0
	global_load_lds_dwordx4 v[230:231], off
	s_mov_b32 m0, s39
	s_nop 0
	global_load_lds_dwordx4 v[232:233], off
	s_waitcnt vmcnt(8)
	s_waitcnt lgkmcnt(0)
	s_barrier
	s_waitcnt lgkmcnt(0)
	v_mfma_f32_16x16x32_bf16 v[60:63], v[160:163], v[192:195], v[60:63]
	v_mfma_f32_16x16x32_bf16 v[56:59], v[168:171], v[192:195], v[56:59]
	v_mfma_f32_16x16x32_bf16 v[44:47], v[160:163], v[202:205], v[44:47]
	v_mfma_f32_16x16x32_bf16 v[40:43], v[168:171], v[202:205], v[40:43]
	v_mfma_f32_16x16x32_bf16 v[28:31], v[160:163], v[210:213], v[28:31]
	v_mfma_f32_16x16x32_bf16 v[24:27], v[168:171], v[210:213], v[24:27]
	v_mfma_f32_16x16x32_bf16 v[12:15], v[160:163], v[218:221], v[12:15]
	v_mfma_f32_16x16x32_bf16 v[8:11], v[168:171], v[218:221], v[8:11]
	v_mfma_f32_16x16x32_bf16 v[60:63], v[164:167], v[198:201], v[60:63]
	v_mfma_f32_16x16x32_bf16 v[56:59], v[172:175], v[198:201], v[56:59]
	v_mfma_f32_16x16x32_bf16 v[44:47], v[164:167], v[206:209], v[44:47]
	v_mfma_f32_16x16x32_bf16 v[40:43], v[172:175], v[206:209], v[40:43]
	v_mfma_f32_16x16x32_bf16 v[28:31], v[164:167], v[214:217], v[28:31]
	v_mfma_f32_16x16x32_bf16 v[24:27], v[172:175], v[214:217], v[24:27]
	v_mfma_f32_16x16x32_bf16 v[12:15], v[164:167], v[226:229], v[12:15]
	v_mfma_f32_16x16x32_bf16 v[8:11], v[172:175], v[226:229], v[8:11]
	v_mfma_f32_16x16x32_bf16 v[52:55], v[176:179], v[192:195], v[52:55]
	v_mfma_f32_16x16x32_bf16 v[48:51], v[184:187], v[192:195], v[48:51]
	v_mfma_f32_16x16x32_bf16 v[36:39], v[176:179], v[202:205], v[36:39]
	v_mfma_f32_16x16x32_bf16 v[32:35], v[184:187], v[202:205], v[32:35]
	v_mfma_f32_16x16x32_bf16 v[20:23], v[176:179], v[210:213], v[20:23]
	v_mfma_f32_16x16x32_bf16 v[16:19], v[184:187], v[210:213], v[16:19]
	v_mfma_f32_16x16x32_bf16 v[4:7], v[176:179], v[218:221], v[4:7]
	v_mfma_f32_16x16x32_bf16 v[0:3], v[184:187], v[218:221], v[0:3]
	v_mfma_f32_16x16x32_bf16 v[52:55], v[180:183], v[198:201], v[52:55]
	v_mfma_f32_16x16x32_bf16 v[48:51], v[188:191], v[198:201], v[48:51]
	v_mfma_f32_16x16x32_bf16 v[36:39], v[180:183], v[206:209], v[36:39]
	v_mfma_f32_16x16x32_bf16 v[32:35], v[188:191], v[206:209], v[32:35]
	v_mfma_f32_16x16x32_bf16 v[20:23], v[180:183], v[214:217], v[20:23]
	v_mfma_f32_16x16x32_bf16 v[16:19], v[188:191], v[214:217], v[16:19]
	v_mfma_f32_16x16x32_bf16 v[4:7], v[180:183], v[226:229], v[4:7]
	v_mfma_f32_16x16x32_bf16 v[0:3], v[188:191], v[226:229], v[0:3]
	s_barrier
	s_add_i32 s62, 0, 0x18000
	v_add_u32_e32 v148, s62, v150
	s_add_i32 s63, 0, 0x1c000
	ds_read_b128 v[160:163], v148
	ds_read_b128 v[164:167], v148 offset:1024
	ds_read_b128 v[168:171], v148 offset:2048
	ds_read_b128 v[172:175], v148 offset:3072
	v_add_u32_e32 v148, s63, v150
	ds_read_b128 v[176:179], v148
	ds_read_b128 v[180:183], v148 offset:1024
	ds_read_b128 v[184:187], v148 offset:2048
	ds_read_b128 v[188:191], v148 offset:3072
	s_add_u32 s24, s24, 0x40000
	s_addc_u32 s25, s25, 0
	s_mov_b32 m0, s40
	v_lshl_add_u64 v[234:235], s[24:25], 0, v[134:135]
	ds_read_b128 v[192:195], v157 offset:32768
	ds_read_b128 v[198:201], v157 offset:33792
	ds_read_b128 v[202:205], v157 offset:34816
	ds_read_b128 v[206:209], v157 offset:35840
	ds_read_b128 v[210:213], v157 offset:36864
	ds_read_b128 v[214:217], v157 offset:37888
	ds_read_b128 v[218:221], v157 offset:38912
	ds_read_b128 v[226:229], v157 offset:39936
	global_load_lds_dwordx4 v[234:235], off
	v_lshl_add_u64 v[234:235], s[24:25], 0, v[130:131]
	s_mov_b32 m0, s41
	s_nop 0
	global_load_lds_dwordx4 v[234:235], off
	s_waitcnt vmcnt(8)
	s_waitcnt lgkmcnt(0)
	s_barrier
	s_waitcnt lgkmcnt(0)
	v_mfma_f32_16x16x32_bf16 v[124:127], v[160:163], v[192:195], v[124:127]
	v_mfma_f32_16x16x32_bf16 v[120:123], v[168:171], v[192:195], v[120:123]
	v_mfma_f32_16x16x32_bf16 v[108:111], v[160:163], v[202:205], v[108:111]
	v_mfma_f32_16x16x32_bf16 v[104:107], v[168:171], v[202:205], v[104:107]
	v_mfma_f32_16x16x32_bf16 v[92:95], v[160:163], v[210:213], v[92:95]
	v_mfma_f32_16x16x32_bf16 v[88:91], v[168:171], v[210:213], v[88:91]
	v_mfma_f32_16x16x32_bf16 v[76:79], v[160:163], v[218:221], v[76:79]
	v_mfma_f32_16x16x32_bf16 v[72:75], v[168:171], v[218:221], v[72:75]
	v_mfma_f32_16x16x32_bf16 v[124:127], v[164:167], v[198:201], v[124:127]
	v_mfma_f32_16x16x32_bf16 v[120:123], v[172:175], v[198:201], v[120:123]
	v_mfma_f32_16x16x32_bf16 v[108:111], v[164:167], v[206:209], v[108:111]
	v_mfma_f32_16x16x32_bf16 v[104:107], v[172:175], v[206:209], v[104:107]
	v_mfma_f32_16x16x32_bf16 v[92:95], v[164:167], v[214:217], v[92:95]
	v_mfma_f32_16x16x32_bf16 v[88:91], v[172:175], v[214:217], v[88:91]
	v_mfma_f32_16x16x32_bf16 v[76:79], v[164:167], v[226:229], v[76:79]
	v_mfma_f32_16x16x32_bf16 v[72:75], v[172:175], v[226:229], v[72:75]
	v_mfma_f32_16x16x32_bf16 v[116:119], v[176:179], v[192:195], v[116:119]
	v_mfma_f32_16x16x32_bf16 v[112:115], v[184:187], v[192:195], v[112:115]
	v_mfma_f32_16x16x32_bf16 v[100:103], v[176:179], v[202:205], v[100:103]
	v_mfma_f32_16x16x32_bf16 v[96:99], v[184:187], v[202:205], v[96:99]
	v_mfma_f32_16x16x32_bf16 v[84:87], v[176:179], v[210:213], v[84:87]
	v_mfma_f32_16x16x32_bf16 v[80:83], v[184:187], v[210:213], v[80:83]
	v_mfma_f32_16x16x32_bf16 v[68:71], v[176:179], v[218:221], v[68:71]
	v_mfma_f32_16x16x32_bf16 v[64:67], v[184:187], v[218:221], v[64:67]
	v_mfma_f32_16x16x32_bf16 v[116:119], v[180:183], v[198:201], v[116:119]
	v_mfma_f32_16x16x32_bf16 v[112:115], v[188:191], v[198:201], v[112:115]
	v_mfma_f32_16x16x32_bf16 v[100:103], v[180:183], v[206:209], v[100:103]
	v_mfma_f32_16x16x32_bf16 v[96:99], v[188:191], v[206:209], v[96:99]
	v_mfma_f32_16x16x32_bf16 v[84:87], v[180:183], v[214:217], v[84:87]
	v_mfma_f32_16x16x32_bf16 v[80:83], v[188:191], v[214:217], v[80:83]
	v_mfma_f32_16x16x32_bf16 v[68:71], v[180:183], v[226:229], v[68:71]
	v_mfma_f32_16x16x32_bf16 v[64:67], v[188:191], v[226:229], v[64:67]
	s_barrier
	s_add_i32 s24, s62, s28
	v_lshl_add_u64 v[146:147], v[146:147], 0, s[6:7]
	s_mov_b32 m0, s24
	ds_read_b128 v[192:195], v157 offset:49152
	ds_read_b128 v[198:201], v157 offset:50176
	ds_read_b128 v[202:205], v157 offset:51200
	ds_read_b128 v[206:209], v157 offset:52224
	ds_read_b128 v[210:213], v157 offset:53248
	ds_read_b128 v[214:217], v157 offset:54272
	ds_read_b128 v[218:221], v157 offset:55296
	ds_read_b128 v[226:229], v157 offset:56320
	global_load_lds_dwordx4 v[146:147], off
	s_add_i32 m0, s24, 0x2000
	s_add_u32 s22, s22, 0x40080
	v_lshl_add_u64 v[146:147], v[222:223], 0, s[6:7]
	s_addc_u32 s23, s23, 0
	s_add_i32 s24, s63, s28
	global_load_lds_dwordx4 v[146:147], off
	v_lshl_add_u64 v[146:147], s[22:23], 0, v[132:133]
	s_mov_b32 m0, s24
	s_nop 0
	global_load_lds_dwordx4 v[146:147], off
	v_lshl_add_u64 v[146:147], s[22:23], 0, v[128:129]
	s_add_i32 m0, s24, 0x2000
	s_nop 0
	global_load_lds_dwordx4 v[146:147], off
	v_lshl_add_u64 v[146:147], v[230:231], 0, s[6:7]
	s_mov_b32 m0, s43
	s_nop 0
	global_load_lds_dwordx4 v[146:147], off
	v_lshl_add_u64 v[146:147], v[232:233], 0, s[6:7]
	s_mov_b32 m0, s44
	s_nop 0
	global_load_lds_dwordx4 v[146:147], off
	s_waitcnt vmcnt(8)
	s_waitcnt lgkmcnt(0)
	s_barrier
	s_waitcnt lgkmcnt(0)
	v_mfma_f32_16x16x32_bf16 v[60:63], v[160:163], v[192:195], v[60:63]
	v_mfma_f32_16x16x32_bf16 v[56:59], v[168:171], v[192:195], v[56:59]
	v_mfma_f32_16x16x32_bf16 v[44:47], v[160:163], v[202:205], v[44:47]
	v_mfma_f32_16x16x32_bf16 v[40:43], v[168:171], v[202:205], v[40:43]
	v_mfma_f32_16x16x32_bf16 v[28:31], v[160:163], v[210:213], v[28:31]
	v_mfma_f32_16x16x32_bf16 v[24:27], v[168:171], v[210:213], v[24:27]
	v_mfma_f32_16x16x32_bf16 v[12:15], v[160:163], v[218:221], v[12:15]
	v_mfma_f32_16x16x32_bf16 v[8:11], v[168:171], v[218:221], v[8:11]
	v_mfma_f32_16x16x32_bf16 v[60:63], v[164:167], v[198:201], v[60:63]
	v_mfma_f32_16x16x32_bf16 v[56:59], v[172:175], v[198:201], v[56:59]
	v_mfma_f32_16x16x32_bf16 v[44:47], v[164:167], v[206:209], v[44:47]
	v_mfma_f32_16x16x32_bf16 v[40:43], v[172:175], v[206:209], v[40:43]
	v_mfma_f32_16x16x32_bf16 v[28:31], v[164:167], v[214:217], v[28:31]
	v_mfma_f32_16x16x32_bf16 v[24:27], v[172:175], v[214:217], v[24:27]
	v_mfma_f32_16x16x32_bf16 v[12:15], v[164:167], v[226:229], v[12:15]
	v_mfma_f32_16x16x32_bf16 v[8:11], v[172:175], v[226:229], v[8:11]
	v_mfma_f32_16x16x32_bf16 v[52:55], v[176:179], v[192:195], v[52:55]
	v_mfma_f32_16x16x32_bf16 v[48:51], v[184:187], v[192:195], v[48:51]
	v_mfma_f32_16x16x32_bf16 v[36:39], v[176:179], v[202:205], v[36:39]
	v_mfma_f32_16x16x32_bf16 v[32:35], v[184:187], v[202:205], v[32:35]
	v_mfma_f32_16x16x32_bf16 v[20:23], v[176:179], v[210:213], v[20:23]
	v_mfma_f32_16x16x32_bf16 v[16:19], v[184:187], v[210:213], v[16:19]
	v_mfma_f32_16x16x32_bf16 v[4:7], v[176:179], v[218:221], v[4:7]
	v_mfma_f32_16x16x32_bf16 v[0:3], v[184:187], v[218:221], v[0:3]
	v_mfma_f32_16x16x32_bf16 v[52:55], v[180:183], v[198:201], v[52:55]
	v_mfma_f32_16x16x32_bf16 v[48:51], v[188:191], v[198:201], v[48:51]
	v_mfma_f32_16x16x32_bf16 v[36:39], v[180:183], v[206:209], v[36:39]
	v_mfma_f32_16x16x32_bf16 v[32:35], v[188:191], v[206:209], v[32:35]
	v_mfma_f32_16x16x32_bf16 v[20:23], v[180:183], v[214:217], v[20:23]
	v_mfma_f32_16x16x32_bf16 v[16:19], v[188:191], v[214:217], v[16:19]
	v_mfma_f32_16x16x32_bf16 v[4:7], v[180:183], v[226:229], v[4:7]
	v_mfma_f32_16x16x32_bf16 v[0:3], v[188:191], v[226:229], v[0:3]
	s_barrier
	s_add_i32 s66, s66, 2
	s_add_u32 s20, s20, 0x100
	s_addc_u32 s21, s21, 0
	s_add_u32 s64, s64, 0x100
	s_addc_u32 s65, s65, 0
	s_cmp_gt_u32 s66, 13
	s_cbranch_scc0 .LBB0_2123
	s_and_b64 vcc, exec, s[8:9]
	s_cbranch_vccz .LBB0_2126
	s_barrier

.LBB0_2204:
	ds_read_b128 v[128:131], v189
	ds_read_b128 v[132:135], v189 offset:1024
	ds_read_b128 v[136:139], v189 offset:2048
	ds_read_b128 v[140:143], v189 offset:3072
	ds_read_b128 v[144:147], v190
	ds_read_b128 v[148:151], v190 offset:1024
	ds_read_b128 v[168:171], v190 offset:2048
	ds_read_b128 v[172:175], v190 offset:3072
	s_add_u32 s20, s18, 0xfff50080
	s_addc_u32 s21, s19, -1
	s_cmp_eq_u32 s64, 40
	s_cselect_b32 s23, s5, s21
	s_cselect_b32 s22, s4, s20
	s_cselect_b32 s21, s17, s51
	s_cselect_b32 s20, s16, s50
	v_lshl_add_u64 v[184:185], s[18:19], 0, v[160:161]
	s_add_i32 m0, s27, 0xc000
	ds_read_b128 v[176:179], v191
	ds_read_b128 v[180:183], v191 offset:1024
	ds_read_b128 v[198:201], v191 offset:2048
	ds_read_b128 v[202:205], v191 offset:3072
	ds_read_b128 v[206:209], v191 offset:4096
	ds_read_b128 v[210:213], v191 offset:5120
	ds_read_b128 v[214:217], v191 offset:6144
	ds_read_b128 v[218:221], v191 offset:7168
	global_load_lds_dwordx4 v[184:185], off
	v_lshl_add_u64 v[184:185], s[18:19], 0, v[162:163]
	s_add_i32 m0, s27, 0xe000
	s_nop 0
	global_load_lds_dwordx4 v[184:185], off
	s_waitcnt vmcnt(8)
	s_waitcnt lgkmcnt(0)
	s_barrier
	s_waitcnt lgkmcnt(0)
	v_mfma_f32_16x16x32_bf16 v[124:127], v[128:131], v[176:179], v[124:127]
	v_mfma_f32_16x16x32_bf16 v[120:123], v[136:139], v[176:179], v[120:123]
	v_mfma_f32_16x16x32_bf16 v[108:111], v[128:131], v[198:201], v[108:111]
	v_mfma_f32_16x16x32_bf16 v[104:107], v[136:139], v[198:201], v[104:107]
	v_mfma_f32_16x16x32_bf16 v[92:95], v[128:131], v[206:209], v[92:95]
	v_mfma_f32_16x16x32_bf16 v[88:91], v[136:139], v[206:209], v[88:91]
	v_mfma_f32_16x16x32_bf16 v[76:79], v[128:131], v[214:217], v[76:79]
	v_mfma_f32_16x16x32_bf16 v[72:75], v[136:139], v[214:217], v[72:75]
	v_mfma_f32_16x16x32_bf16 v[124:127], v[132:135], v[180:183], v[124:127]
	v_mfma_f32_16x16x32_bf16 v[120:123], v[140:143], v[180:183], v[120:123]
	v_mfma_f32_16x16x32_bf16 v[108:111], v[132:135], v[202:205], v[108:111]
	v_mfma_f32_16x16x32_bf16 v[104:107], v[140:143], v[202:205], v[104:107]
	v_mfma_f32_16x16x32_bf16 v[92:95], v[132:135], v[210:213], v[92:95]
	v_mfma_f32_16x16x32_bf16 v[88:91], v[140:143], v[210:213], v[88:91]
	v_mfma_f32_16x16x32_bf16 v[76:79], v[132:135], v[218:221], v[76:79]
	v_mfma_f32_16x16x32_bf16 v[72:75], v[140:143], v[218:221], v[72:75]
	v_mfma_f32_16x16x32_bf16 v[116:119], v[144:147], v[176:179], v[116:119]
	v_mfma_f32_16x16x32_bf16 v[112:115], v[168:171], v[176:179], v[112:115]
	v_mfma_f32_16x16x32_bf16 v[100:103], v[144:147], v[198:201], v[100:103]
	v_mfma_f32_16x16x32_bf16 v[96:99], v[168:171], v[198:201], v[96:99]
	v_mfma_f32_16x16x32_bf16 v[84:87], v[144:147], v[206:209], v[84:87]
	v_mfma_f32_16x16x32_bf16 v[80:83], v[168:171], v[206:209], v[80:83]
	v_mfma_f32_16x16x32_bf16 v[68:71], v[144:147], v[214:217], v[68:71]
	v_mfma_f32_16x16x32_bf16 v[64:67], v[168:171], v[214:217], v[64:67]
	v_mfma_f32_16x16x32_bf16 v[116:119], v[148:151], v[180:183], v[116:119]
	v_mfma_f32_16x16x32_bf16 v[112:115], v[172:175], v[180:183], v[112:115]
	v_mfma_f32_16x16x32_bf16 v[100:103], v[148:151], v[202:205], v[100:103]
	v_mfma_f32_16x16x32_bf16 v[96:99], v[172:175], v[202:205], v[96:99]
	v_mfma_f32_16x16x32_bf16 v[84:87], v[148:151], v[210:213], v[84:87]
	v_mfma_f32_16x16x32_bf16 v[80:83], v[172:175], v[210:213], v[80:83]
	v_mfma_f32_16x16x32_bf16 v[68:71], v[148:151], v[218:221], v[68:71]
	v_mfma_f32_16x16x32_bf16 v[64:67], v[172:175], v[218:221], v[64:67]
	s_barrier
	s_add_i32 s62, s44, s26
	v_lshl_add_u64 v[184:185], s[20:21], 0, v[154:155]
	s_mov_b32 m0, s62
	ds_read_b128 v[176:179], v191 offset:16384
	ds_read_b128 v[180:183], v191 offset:17408
	ds_read_b128 v[198:201], v191 offset:18432
	ds_read_b128 v[202:205], v191 offset:19456
	ds_read_b128 v[206:209], v191 offset:20480
	ds_read_b128 v[210:213], v191 offset:21504
	ds_read_b128 v[214:217], v191 offset:22528
	ds_read_b128 v[218:221], v191 offset:23552
	global_load_lds_dwordx4 v[184:185], off
	s_add_i32 m0, s62, 0x2000
	s_add_u32 s62, s20, 0xb0000
	v_lshl_add_u64 v[194:195], s[20:21], 0, v[158:159]
	s_addc_u32 s63, s21, 0
	s_add_i32 s65, s45, s26
	global_load_lds_dwordx4 v[194:195], off
	v_lshl_add_u64 v[222:223], s[62:63], 0, v[154:155]
	s_mov_b32 m0, s65
	v_lshl_add_u64 v[226:227], s[22:23], 0, v[156:157]
	global_load_lds_dwordx4 v[222:223], off
	v_lshl_add_u64 v[222:223], s[62:63], 0, v[158:159]
	s_add_i32 m0, s65, 0x2000
	s_nop 0
	global_load_lds_dwordx4 v[222:223], off
	v_lshl_add_u64 v[222:223], s[22:23], 0, v[152:153]
	s_mov_b32 m0, s27
	s_nop 0
	global_load_lds_dwordx4 v[222:223], off
	s_mov_b32 m0, s28
	s_nop 0
	global_load_lds_dwordx4 v[226:227], off
	s_waitcnt vmcnt(8)
	s_waitcnt lgkmcnt(0)
	s_barrier
	s_waitcnt lgkmcnt(0)
	v_mfma_f32_16x16x32_bf16 v[60:63], v[128:131], v[176:179], v[60:63]
	v_mfma_f32_16x16x32_bf16 v[56:59], v[136:139], v[176:179], v[56:59]
	v_mfma_f32_16x16x32_bf16 v[44:47], v[128:131], v[198:201], v[44:47]
	v_mfma_f32_16x16x32_bf16 v[40:43], v[136:139], v[198:201], v[40:43]
	v_mfma_f32_16x16x32_bf16 v[28:31], v[128:131], v[206:209], v[28:31]
	v_mfma_f32_16x16x32_bf16 v[24:27], v[136:139], v[206:209], v[24:27]
	v_mfma_f32_16x16x32_bf16 v[12:15], v[128:131], v[214:217], v[12:15]
	v_mfma_f32_16x16x32_bf16 v[8:11], v[136:139], v[214:217], v[8:11]
	v_mfma_f32_16x16x32_bf16 v[60:63], v[132:135], v[180:183], v[60:63]
	v_mfma_f32_16x16x32_bf16 v[56:59], v[140:143], v[180:183], v[56:59]
	v_mfma_f32_16x16x32_bf16 v[44:47], v[132:135], v[202:205], v[44:47]
	v_mfma_f32_16x16x32_bf16 v[40:43], v[140:143], v[202:205], v[40:43]
	v_mfma_f32_16x16x32_bf16 v[28:31], v[132:135], v[210:213], v[28:31]
	v_mfma_f32_16x16x32_bf16 v[24:27], v[140:143], v[210:213], v[24:27]
	v_mfma_f32_16x16x32_bf16 v[12:15], v[132:135], v[218:221], v[12:15]
	v_mfma_f32_16x16x32_bf16 v[8:11], v[140:143], v[218:221], v[8:11]
	v_mfma_f32_16x16x32_bf16 v[52:55], v[144:147], v[176:179], v[52:55]
	v_mfma_f32_16x16x32_bf16 v[48:51], v[168:171], v[176:179], v[48:51]
	v_mfma_f32_16x16x32_bf16 v[36:39], v[144:147], v[198:201], v[36:39]
	v_mfma_f32_16x16x32_bf16 v[32:35], v[168:171], v[198:201], v[32:35]
	v_mfma_f32_16x16x32_bf16 v[20:23], v[144:147], v[206:209], v[20:23]
	v_mfma_f32_16x16x32_bf16 v[16:19], v[168:171], v[206:209], v[16:19]
	v_mfma_f32_16x16x32_bf16 v[4:7], v[144:147], v[214:217], v[4:7]
	v_mfma_f32_16x16x32_bf16 v[0:3], v[168:171], v[214:217], v[0:3]
	v_mfma_f32_16x16x32_bf16 v[52:55], v[148:151], v[180:183], v[52:55]
	v_mfma_f32_16x16x32_bf16 v[48:51], v[172:175], v[180:183], v[48:51]
	v_mfma_f32_16x16x32_bf16 v[36:39], v[148:151], v[202:205], v[36:39]
	v_mfma_f32_16x16x32_bf16 v[32:35], v[172:175], v[202:205], v[32:35]
	v_mfma_f32_16x16x32_bf16 v[20:23], v[148:151], v[210:213], v[20:23]
	v_mfma_f32_16x16x32_bf16 v[16:19], v[172:175], v[210:213], v[16:19]
	v_mfma_f32_16x16x32_bf16 v[4:7], v[148:151], v[218:221], v[4:7]
	v_mfma_f32_16x16x32_bf16 v[0:3], v[172:175], v[218:221], v[0:3]
	s_barrier
	s_add_i32 s62, 0, 0x18000
	s_add_i32 s63, 0, 0x1c000
	v_add_u32_e32 v140, s62, v187
	v_add_u32_e32 v172, s63, v187
	ds_read_b128 v[128:131], v140
	ds_read_b128 v[132:135], v140 offset:1024
	ds_read_b128 v[136:139], v140 offset:2048
	ds_read_b128 v[140:143], v140 offset:3072
	ds_read_b128 v[144:147], v172
	ds_read_b128 v[148:151], v172 offset:1024
	ds_read_b128 v[168:171], v172 offset:2048
	ds_read_b128 v[172:175], v172 offset:3072
	s_add_u32 s22, s22, 0xb0000
	s_addc_u32 s23, s23, 0
	s_mov_b32 m0, s29
	v_lshl_add_u64 v[228:229], s[22:23], 0, v[152:153]
	ds_read_b128 v[176:179], v191 offset:32768
	ds_read_b128 v[180:183], v191 offset:33792
	ds_read_b128 v[198:201], v191 offset:34816
	ds_read_b128 v[202:205], v191 offset:35840
	ds_read_b128 v[206:209], v191 offset:36864
	ds_read_b128 v[210:213], v191 offset:37888
	ds_read_b128 v[214:217], v191 offset:38912
	ds_read_b128 v[218:221], v191 offset:39936
	global_load_lds_dwordx4 v[228:229], off
	v_lshl_add_u64 v[228:229], s[22:23], 0, v[156:157]
	s_mov_b32 m0, s38
	s_nop 0
	global_load_lds_dwordx4 v[228:229], off
	s_waitcnt vmcnt(8)
	s_waitcnt lgkmcnt(0)
	s_barrier
	s_waitcnt lgkmcnt(0)
	v_mfma_f32_16x16x32_bf16 v[124:127], v[128:131], v[176:179], v[124:127]
	v_mfma_f32_16x16x32_bf16 v[120:123], v[136:139], v[176:179], v[120:123]
	v_mfma_f32_16x16x32_bf16 v[108:111], v[128:131], v[198:201], v[108:111]
	v_mfma_f32_16x16x32_bf16 v[104:107], v[136:139], v[198:201], v[104:107]
	v_mfma_f32_16x16x32_bf16 v[92:95], v[128:131], v[206:209], v[92:95]
	v_mfma_f32_16x16x32_bf16 v[88:91], v[136:139], v[206:209], v[88:91]
	v_mfma_f32_16x16x32_bf16 v[76:79], v[128:131], v[214:217], v[76:79]
	v_mfma_f32_16x16x32_bf16 v[72:75], v[136:139], v[214:217], v[72:75]
	v_mfma_f32_16x16x32_bf16 v[124:127], v[132:135], v[180:183], v[124:127]
	v_mfma_f32_16x16x32_bf16 v[120:123], v[140:143], v[180:183], v[120:123]
	v_mfma_f32_16x16x32_bf16 v[108:111], v[132:135], v[202:205], v[108:111]
	v_mfma_f32_16x16x32_bf16 v[104:107], v[140:143], v[202:205], v[104:107]
	v_mfma_f32_16x16x32_bf16 v[92:95], v[132:135], v[210:213], v[92:95]
	v_mfma_f32_16x16x32_bf16 v[88:91], v[140:143], v[210:213], v[88:91]
	v_mfma_f32_16x16x32_bf16 v[76:79], v[132:135], v[218:221], v[76:79]
	v_mfma_f32_16x16x32_bf16 v[72:75], v[140:143], v[218:221], v[72:75]
	v_mfma_f32_16x16x32_bf16 v[116:119], v[144:147], v[176:179], v[116:119]
	v_mfma_f32_16x16x32_bf16 v[112:115], v[168:171], v[176:179], v[112:115]
	v_mfma_f32_16x16x32_bf16 v[100:103], v[144:147], v[198:201], v[100:103]
	v_mfma_f32_16x16x32_bf16 v[96:99], v[168:171], v[198:201], v[96:99]
	v_mfma_f32_16x16x32_bf16 v[84:87], v[144:147], v[206:209], v[84:87]
	v_mfma_f32_16x16x32_bf16 v[80:83], v[168:171], v[206:209], v[80:83]
	v_mfma_f32_16x16x32_bf16 v[68:71], v[144:147], v[214:217], v[68:71]
	v_mfma_f32_16x16x32_bf16 v[64:67], v[168:171], v[214:217], v[64:67]
	v_mfma_f32_16x16x32_bf16 v[116:119], v[148:151], v[180:183], v[116:119]
	v_mfma_f32_16x16x32_bf16 v[112:115], v[172:175], v[180:183], v[112:115]
	v_mfma_f32_16x16x32_bf16 v[100:103], v[148:151], v[202:205], v[100:103]
	v_mfma_f32_16x16x32_bf16 v[96:99], v[172:175], v[202:205], v[96:99]
	v_mfma_f32_16x16x32_bf16 v[84:87], v[148:151], v[210:213], v[84:87]
	v_mfma_f32_16x16x32_bf16 v[80:83], v[172:175], v[210:213], v[80:83]
	v_mfma_f32_16x16x32_bf16 v[68:71], v[148:151], v[218:221], v[68:71]
	v_mfma_f32_16x16x32_bf16 v[64:67], v[172:175], v[218:221], v[64:67]
	s_barrier
	s_add_i32 s22, s62, s26
	v_lshl_add_u64 v[184:185], v[184:185], 0, s[12:13]
	s_mov_b32 m0, s22
	ds_read_b128 v[176:179], v191 offset:49152
	ds_read_b128 v[180:183], v191 offset:50176
	ds_read_b128 v[198:201], v191 offset:51200
	ds_read_b128 v[202:205], v191 offset:52224
	ds_read_b128 v[206:209], v191 offset:53248
	ds_read_b128 v[210:213], v191 offset:54272
	ds_read_b128 v[214:217], v191 offset:55296
	ds_read_b128 v[218:221], v191 offset:56320
	global_load_lds_dwordx4 v[184:185], off
	s_add_i32 m0, s22, 0x2000
	s_add_u32 s20, s20, 0xb0080
	v_lshl_add_u64 v[184:185], v[194:195], 0, s[12:13]
	s_addc_u32 s21, s21, 0
	s_add_i32 s22, s63, s26
	global_load_lds_dwordx4 v[184:185], off
	v_lshl_add_u64 v[184:185], s[20:21], 0, v[154:155]
	s_mov_b32 m0, s22
	s_nop 0
	global_load_lds_dwordx4 v[184:185], off
	v_lshl_add_u64 v[184:185], s[20:21], 0, v[158:159]
	s_add_i32 m0, s22, 0x2000
	s_nop 0
	global_load_lds_dwordx4 v[184:185], off
	v_lshl_add_u64 v[184:185], v[222:223], 0, s[12:13]
	s_mov_b32 m0, s40
	s_nop 0
	global_load_lds_dwordx4 v[184:185], off
	v_lshl_add_u64 v[184:185], v[226:227], 0, s[12:13]
	s_mov_b32 m0, s41
	s_nop 0
	global_load_lds_dwordx4 v[184:185], off
	s_waitcnt vmcnt(8)
	s_waitcnt lgkmcnt(0)
	s_barrier
	s_waitcnt lgkmcnt(0)
	v_mfma_f32_16x16x32_bf16 v[60:63], v[128:131], v[176:179], v[60:63]
	v_mfma_f32_16x16x32_bf16 v[56:59], v[136:139], v[176:179], v[56:59]
	v_mfma_f32_16x16x32_bf16 v[44:47], v[128:131], v[198:201], v[44:47]
	v_mfma_f32_16x16x32_bf16 v[40:43], v[136:139], v[198:201], v[40:43]
	v_mfma_f32_16x16x32_bf16 v[28:31], v[128:131], v[206:209], v[28:31]
	v_mfma_f32_16x16x32_bf16 v[24:27], v[136:139], v[206:209], v[24:27]
	v_mfma_f32_16x16x32_bf16 v[12:15], v[128:131], v[214:217], v[12:15]
	v_mfma_f32_16x16x32_bf16 v[8:11], v[136:139], v[214:217], v[8:11]
	v_mfma_f32_16x16x32_bf16 v[60:63], v[132:135], v[180:183], v[60:63]
	v_mfma_f32_16x16x32_bf16 v[56:59], v[140:143], v[180:183], v[56:59]
	v_mfma_f32_16x16x32_bf16 v[44:47], v[132:135], v[202:205], v[44:47]
	v_mfma_f32_16x16x32_bf16 v[40:43], v[140:143], v[202:205], v[40:43]
	v_mfma_f32_16x16x32_bf16 v[28:31], v[132:135], v[210:213], v[28:31]
	v_mfma_f32_16x16x32_bf16 v[24:27], v[140:143], v[210:213], v[24:27]
	v_mfma_f32_16x16x32_bf16 v[12:15], v[132:135], v[218:221], v[12:15]
	v_mfma_f32_16x16x32_bf16 v[8:11], v[140:143], v[218:221], v[8:11]
	v_mfma_f32_16x16x32_bf16 v[52:55], v[144:147], v[176:179], v[52:55]
	v_mfma_f32_16x16x32_bf16 v[48:51], v[168:171], v[176:179], v[48:51]
	v_mfma_f32_16x16x32_bf16 v[36:39], v[144:147], v[198:201], v[36:39]
	v_mfma_f32_16x16x32_bf16 v[32:35], v[168:171], v[198:201], v[32:35]
	v_mfma_f32_16x16x32_bf16 v[20:23], v[144:147], v[206:209], v[20:23]
	v_mfma_f32_16x16x32_bf16 v[16:19], v[168:171], v[206:209], v[16:19]
	v_mfma_f32_16x16x32_bf16 v[4:7], v[144:147], v[214:217], v[4:7]
	v_mfma_f32_16x16x32_bf16 v[0:3], v[168:171], v[214:217], v[0:3]
	v_mfma_f32_16x16x32_bf16 v[52:55], v[148:151], v[180:183], v[52:55]
	v_mfma_f32_16x16x32_bf16 v[48:51], v[172:175], v[180:183], v[48:51]
	v_mfma_f32_16x16x32_bf16 v[36:39], v[148:151], v[202:205], v[36:39]
	v_mfma_f32_16x16x32_bf16 v[32:35], v[172:175], v[202:205], v[32:35]
	v_mfma_f32_16x16x32_bf16 v[20:23], v[148:151], v[210:213], v[20:23]
	v_mfma_f32_16x16x32_bf16 v[16:19], v[172:175], v[210:213], v[16:19]
	v_mfma_f32_16x16x32_bf16 v[4:7], v[148:151], v[218:221], v[4:7]
	v_mfma_f32_16x16x32_bf16 v[0:3], v[172:175], v[218:221], v[0:3]
	s_barrier
	s_add_i32 s64, s64, 2
	s_add_u32 s18, s18, 0x100
	s_addc_u32 s19, s19, 0
	s_add_u32 s50, s50, 0x100
	s_addc_u32 s51, s51, 0
	s_cmp_gt_u32 s64, 41
	s_cbranch_scc0 .LBB0_2204
	s_and_b64 vcc, exec, s[14:15]
	s_cbranch_vccz .LBB0_2207
	s_barrier
